# load-segment instruction trim on top of balanced loads: dead temp adds removed, one m0 write hoisted per loop body to drop its s_nop
# baseline (speedup 1.0000x reference)
; #define PG8_STAGE(bufoff, gbase, voff) do { _Pragma("unroll") for (int _i = 0; _i < 2; ++_i) \
;         __builtin_amdgcn_global_load_lds((const unsigned*)((const char*)(gbase) + (voff)[_i]), (LAS unsigned*)(lds + (bufoff) + ldsw + _i * 8192), 16, 0, ((voff) == voffA ? AUXA : 0)); } while (0)
; #define PG8_LDA(dst, b, h) do { _Pragma("unroll") for (int m = 0; m < 4; ++m) _Pragma("unroll") for (int k = 0; k < 2; ++k) dst[m][k] = *(const LAS bf16x8*)(lds + PG8_SA(b, h) + aoff + m * 2048 + k * 1024); } while (0)
; #define PG8_LDB(dst, b, h) do { _Pragma("unroll") for (int n = 0; n < 2; ++n) _Pragma("unroll") for (int k = 0; k < 2; ++k) dst[n][k] = *(const LAS bf16x8*)(lds + PG8_SB(b, h) + boff + n * 2048 + k * 1024); } while (0)
; #define PG8_WAIT_V(n) asm volatile("s_waitcnt vmcnt(" #n ")" ::: "memory")
; #define PG8_SCHED __builtin_amdgcn_sched_barrier(0)
;     ...
;             const bool last = (t == nt - 2);
;             const char* a1 = cA + (size_t)(t + 1) * kstep;
;             const char* a2 = last ? nA : cA + (size_t)(t + 2) * kstep; const char* b2 = last ? nB : cB + (size_t)(t + 2) * kstep;
;             const char* a3 = a2 + kstep; const char* b3 = b2 + kstep;
;             PG8_LDB(B0, 0, 0); PG8_LDB(B1, 0, 1); PG8_SCHED; PG8_LDA(At, 0, 0); PG8_STAGE(PG8_SA(1, 1), a1 + hsA, voffA);
;             if (Epi::NPRE != 0 && last) { E.pre(sv, cur, wr, fr); PG8_WAIT_V(16); } else { PG8_WAIT_V(8); }
.LBB0_149:
	s_add_u32 s98, s28, 0xfff80000
	s_mov_b32 m0, s50
	s_addc_u32 s99, s29, -1
	global_load_lds_dwordx4 v200, s[98:99]
	s_mov_b32 m0, s51
	s_nop 0
	global_load_lds_dwordx4 v196, s[98:99]
	ds_read_b128 v[144:147], v224
	ds_read_b128 v[148:151], v224 offset:1024
	ds_read_b128 v[152:155], v224 offset:2048
	ds_read_b128 v[156:159], v224 offset:3072
	ds_read_b128 v[128:131], v225
	ds_read_b128 v[132:135], v225 offset:1024
	ds_read_b128 v[136:139], v225 offset:2048
	ds_read_b128 v[140:143], v225 offset:3072
	s_cmp_eq_u32 s52, s61
	s_cselect_b64 s[30:31], -1, 0
	s_cmp_lg_u32 s52, s61
	s_cselect_b64 s[36:37], -1, 0
	s_add_i32 m0, s40, 0xc000
	ds_read_b128 v[184:187], v226
	ds_read_b128 v[188:191], v226 offset:1024
	ds_read_b128 v[176:179], v226 offset:2048
	ds_read_b128 v[180:183], v226 offset:3072
	ds_read_b128 v[168:171], v226 offset:4096
	ds_read_b128 v[172:175], v226 offset:5120
	ds_read_b128 v[160:163], v226 offset:6144
	ds_read_b128 v[164:167], v226 offset:7168
	global_load_lds_dwordx4 v202, s[28:29]
	s_add_i32 m0, s40, 0xe000
	s_mov_b64 s[34:35], -1
	global_load_lds_dwordx4 v204, s[28:29]
	s_and_b64 vcc, exec, s[36:37]
	s_cbranch_vccz .LBB0_151
	s_waitcnt vmcnt(8)
	s_mov_b64 s[34:35], 0

; #define PG8_STAGE(bufoff, gbase, voff) do { _Pragma("unroll") for (int _i = 0; _i < 2; ++_i) \
;         __builtin_amdgcn_global_load_lds((const unsigned*)((const char*)(gbase) + (voff)[_i]), (LAS unsigned*)(lds + (bufoff) + ldsw + _i * 8192), 16, 0, ((voff) == voffA ? AUXA : 0)); } while (0)
; #define PG8_LDA(dst, b, h) do { _Pragma("unroll") for (int m = 0; m < 4; ++m) _Pragma("unroll") for (int k = 0; k < 2; ++k) dst[m][k] = *(const LAS bf16x8*)(lds + PG8_SA(b, h) + aoff + m * 2048 + k * 1024); } while (0)
; #define PG8_LDB(dst, b, h) do { _Pragma("unroll") for (int n = 0; n < 2; ++n) _Pragma("unroll") for (int k = 0; k < 2; ++k) dst[n][k] = *(const LAS bf16x8*)(lds + PG8_SB(b, h) + boff + n * 2048 + k * 1024); } while (0)
; #define PG8_MMA(ai, bj, At, Bt) do { __builtin_amdgcn_s_setprio(1); _Pragma("unroll") for (int m = 0; m < 4; ++m) _Pragma("unroll") for (int n = 0; n < 2; ++n) _Pragma("unroll") for (int k = 0; k < 2; ++k) \
;         acc[ai][bj][m][n] = __builtin_amdgcn_mfma_f32_16x16x32_bf16(Bt[n][k], At[m][k], acc[ai][bj][m][n], 0, 0, 0); __builtin_amdgcn_s_setprio(0); } while (0)
; #define PG8_WAIT_V(n) asm volatile("s_waitcnt vmcnt(" #n ")" ::: "memory")
; #define PG8_WAIT_L(n) asm volatile("s_waitcnt lgkmcnt(" #n ")" ::: "memory")
; #define PG8_BAR __builtin_amdgcn_s_barrier()
; #define PG8_SCHED __builtin_amdgcn_sched_barrier(0)
;     ...
;             const char* a2 = last ? nA : cA + (size_t)(t + 2) * kstep; const char* b2 = last ? nB : cB + (size_t)(t + 2) * kstep;
;             const char* a3 = a2 + kstep; const char* b3 = b2 + kstep;
;             PG8_LDB(B0, 0, 0); PG8_LDB(B1, 0, 1); PG8_SCHED; PG8_LDA(At, 0, 0); PG8_STAGE(PG8_SA(1, 1), a1 + hsA, voffA);
;             if (Epi::NPRE != 0 && last) { E.pre(sv, cur, wr, fr); PG8_WAIT_V(16); } else { PG8_WAIT_V(8); }
;             PG8_WAIT_L(0); PG8_BAR; PG8_MMA(0, 0, At, B0); PG8_MMA(0, 1, At, B1); PG8_BAR; PG8_SCHED;
;             PG8_LDA(At, 0, 1); PG8_STAGE(PG8_SB(0, 0), b2, voffB); PG8_STAGE(PG8_SB(0, 1), b2 + hsB, voffB); PG8_STAGE(PG8_SA(0, 0), a2, voffA);
;             if (Epi::NPRE != 0 && last) { PG8_WAIT_V(16); } else { PG8_WAIT_V(8); }
.LBB0_153:
	s_add_u32 s34, s28, 0xfff80080
	s_addc_u32 s35, s29, -1
	s_waitcnt lgkmcnt(0)
	s_and_b64 s[30:31], s[30:31], exec
	s_cselect_b32 s35, s21, s35
	s_cselect_b32 s34, s23, s34
	s_cselect_b32 s31, s57, s60
	s_cselect_b32 s30, s58, s59
	s_setprio 1
	s_barrier
	v_mfma_f32_16x16x32_bf16 v[124:127], v[144:147], v[184:187], v[124:127]
	v_mfma_f32_16x16x32_bf16 v[116:119], v[152:155], v[184:187], v[116:119]
	v_mfma_f32_16x16x32_bf16 v[108:111], v[144:147], v[176:179], v[108:111]
	v_mfma_f32_16x16x32_bf16 v[100:103], v[152:155], v[176:179], v[100:103]
	v_mfma_f32_16x16x32_bf16 v[92:95], v[144:147], v[168:171], v[92:95]
	v_mfma_f32_16x16x32_bf16 v[84:87], v[152:155], v[168:171], v[84:87]
	v_mfma_f32_16x16x32_bf16 v[76:79], v[144:147], v[160:163], v[76:79]
	v_mfma_f32_16x16x32_bf16 v[68:71], v[152:155], v[160:163], v[68:71]
	v_mfma_f32_16x16x32_bf16 v[124:127], v[148:151], v[188:191], v[124:127]
	v_mfma_f32_16x16x32_bf16 v[116:119], v[156:159], v[188:191], v[116:119]
	v_mfma_f32_16x16x32_bf16 v[108:111], v[148:151], v[180:183], v[108:111]
	v_mfma_f32_16x16x32_bf16 v[100:103], v[156:159], v[180:183], v[100:103]
	v_mfma_f32_16x16x32_bf16 v[92:95], v[148:151], v[172:175], v[92:95]
	v_mfma_f32_16x16x32_bf16 v[84:87], v[156:159], v[172:175], v[84:87]
	v_mfma_f32_16x16x32_bf16 v[76:79], v[148:151], v[164:167], v[76:79]
	v_mfma_f32_16x16x32_bf16 v[68:71], v[156:159], v[164:167], v[68:71]
	v_mfma_f32_16x16x32_bf16 v[120:123], v[128:131], v[184:187], v[120:123]
	v_mfma_f32_16x16x32_bf16 v[112:115], v[136:139], v[184:187], v[112:115]
	v_mfma_f32_16x16x32_bf16 v[104:107], v[128:131], v[176:179], v[104:107]
	v_mfma_f32_16x16x32_bf16 v[96:99], v[136:139], v[176:179], v[96:99]
	v_mfma_f32_16x16x32_bf16 v[88:91], v[128:131], v[168:171], v[88:91]
	v_mfma_f32_16x16x32_bf16 v[80:83], v[136:139], v[168:171], v[80:83]
	v_mfma_f32_16x16x32_bf16 v[72:75], v[128:131], v[160:163], v[72:75]
	v_mfma_f32_16x16x32_bf16 v[64:67], v[136:139], v[160:163], v[64:67]
	v_mfma_f32_16x16x32_bf16 v[120:123], v[132:135], v[188:191], v[120:123]
	v_mfma_f32_16x16x32_bf16 v[112:115], v[140:143], v[188:191], v[112:115]
	v_mfma_f32_16x16x32_bf16 v[104:107], v[132:135], v[180:183], v[104:107]
	v_mfma_f32_16x16x32_bf16 v[96:99], v[140:143], v[180:183], v[96:99]
	v_mfma_f32_16x16x32_bf16 v[88:91], v[132:135], v[172:175], v[88:91]
	v_mfma_f32_16x16x32_bf16 v[80:83], v[140:143], v[172:175], v[80:83]
	v_mfma_f32_16x16x32_bf16 v[72:75], v[132:135], v[164:167], v[72:75]
	v_mfma_f32_16x16x32_bf16 v[64:67], v[140:143], v[164:167], v[64:67]
	s_barrier
	s_setprio 0
	s_add_u32 s98, s30, s16
	s_addc_u32 s99, s31, s17
	s_mov_b32 m0, s41
	s_add_u32 s38, s30, 0x80000
	ds_read_b128 v[184:187], v226 offset:16384
	ds_read_b128 v[188:191], v226 offset:17408
	ds_read_b128 v[176:179], v226 offset:18432
	ds_read_b128 v[180:183], v226 offset:19456
	ds_read_b128 v[168:171], v226 offset:20480
	ds_read_b128 v[172:175], v226 offset:21504
	ds_read_b128 v[160:163], v226 offset:22528
	ds_read_b128 v[164:167], v226 offset:23552
	global_load_lds_dwordx4 v198, s[30:31]
	s_mov_b32 m0, s42
	s_addc_u32 s39, s31, 0
	global_load_lds_dwordx4 v194, s[30:31]
	s_mov_b32 m0, s43
	s_nop 0
	global_load_lds_dwordx4 v198, s[38:39]
	s_mov_b32 m0, s44
	s_nop 0
	global_load_lds_dwordx4 v194, s[38:39]
	s_mov_b64 s[38:39], -1
	s_and_b64 vcc, exec, s[36:37]
	s_cbranch_vccz .LBB0_155
	s_waitcnt vmcnt(6)
	s_mov_b64 s[38:39], 0

; #define PG8_STAGE(bufoff, gbase, voff) do { _Pragma("unroll") for (int _i = 0; _i < 2; ++_i) \
;         __builtin_amdgcn_global_load_lds((const unsigned*)((const char*)(gbase) + (voff)[_i]), (LAS unsigned*)(lds + (bufoff) + ldsw + _i * 8192), 16, 0, ((voff) == voffA ? AUXA : 0)); } while (0)
; #define PG8_LDA(dst, b, h) do { _Pragma("unroll") for (int m = 0; m < 4; ++m) _Pragma("unroll") for (int k = 0; k < 2; ++k) dst[m][k] = *(const LAS bf16x8*)(lds + PG8_SA(b, h) + aoff + m * 2048 + k * 1024); } while (0)
; #define PG8_LDB(dst, b, h) do { _Pragma("unroll") for (int n = 0; n < 2; ++n) _Pragma("unroll") for (int k = 0; k < 2; ++k) dst[n][k] = *(const LAS bf16x8*)(lds + PG8_SB(b, h) + boff + n * 2048 + k * 1024); } while (0)
; #define PG8_MMA(ai, bj, At, Bt) do { __builtin_amdgcn_s_setprio(1); _Pragma("unroll") for (int m = 0; m < 4; ++m) _Pragma("unroll") for (int n = 0; n < 2; ++n) _Pragma("unroll") for (int k = 0; k < 2; ++k) \
;         acc[ai][bj][m][n] = __builtin_amdgcn_mfma_f32_16x16x32_bf16(Bt[n][k], At[m][k], acc[ai][bj][m][n], 0, 0, 0); __builtin_amdgcn_s_setprio(0); } while (0)
; #define PG8_WAIT_V(n) asm volatile("s_waitcnt vmcnt(" #n ")" ::: "memory")
; #define PG8_WAIT_L(n) asm volatile("s_waitcnt lgkmcnt(" #n ")" ::: "memory")
; #define PG8_BAR __builtin_amdgcn_s_barrier()
; #define PG8_SCHED __builtin_amdgcn_sched_barrier(0)
;     ...
;         for (int t = 0; t < nt; t += 2) {
;             const bool last = (t == nt - 2);
;             const char* a1 = cA + (size_t)(t + 1) * kstep;
;             const char* a2 = last ? nA : cA + (size_t)(t + 2) * kstep; const char* b2 = last ? nB : cB + (size_t)(t + 2) * kstep;
;             const char* a3 = a2 + kstep; const char* b3 = b2 + kstep;
;             PG8_LDB(B0, 0, 0); PG8_LDB(B1, 0, 1); PG8_SCHED; PG8_LDA(At, 0, 0); PG8_STAGE(PG8_SA(1, 1), a1 + hsA, voffA);
;             if (Epi::NPRE != 0 && last) { E.pre(sv, cur, wr, fr); PG8_WAIT_V(16); } else { PG8_WAIT_V(8); }
;             PG8_WAIT_L(0); PG8_BAR; PG8_MMA(0, 0, At, B0); PG8_MMA(0, 1, At, B1); PG8_BAR; PG8_SCHED;
;             PG8_LDA(At, 0, 1); PG8_STAGE(PG8_SB(0, 0), b2, voffB); PG8_STAGE(PG8_SB(0, 1), b2 + hsB, voffB); PG8_STAGE(PG8_SA(0, 0), a2, voffA);
;             if (Epi::NPRE != 0 && last) { PG8_WAIT_V(16); } else { PG8_WAIT_V(8); }
;             PG8_WAIT_L(0); PG8_BAR; PG8_MMA(1, 0, At, B0); PG8_MMA(1, 1, At, B1); PG8_BAR; PG8_SCHED;
.LBB0_246:
	s_add_u32 s98, s24, 0xffea0000
	s_mov_b32 m0, s39
	s_addc_u32 s99, s25, -1
	global_load_lds_dwordx4 v128, s[98:99]
	s_mov_b32 m0, s40
	s_nop 0
	global_load_lds_dwordx4 v132, s[98:99]
	ds_read_b128 v[144:147], v208
	ds_read_b128 v[148:151], v208 offset:1024
	ds_read_b128 v[152:155], v208 offset:2048
	ds_read_b128 v[156:159], v208 offset:3072
	ds_read_b128 v[160:163], v209
	ds_read_b128 v[164:167], v209 offset:1024
	ds_read_b128 v[168:171], v209 offset:2048
	ds_read_b128 v[172:175], v209 offset:3072
	s_add_i32 s52, s26, 2
	s_add_u32 s27, s24, 0xffea0080
	s_addc_u32 s28, s25, -1
	s_cmp_eq_u32 s41, s26
	s_cselect_b32 s26, s22, s50
	s_cselect_b32 s29, s11, s28
	s_cselect_b32 s28, s10, s27
	s_cselect_b32 s27, s23, s51
	s_add_i32 m0, s30, 0xc000
	ds_read_b128 v[176:179], v210
	ds_read_b128 v[180:183], v210 offset:1024
	ds_read_b128 v[184:187], v210 offset:2048
	ds_read_b128 v[188:191], v210 offset:3072
	ds_read_b128 v[194:197], v210 offset:4096
	ds_read_b128 v[198:201], v210 offset:5120
	ds_read_b128 v[202:205], v210 offset:6144
	ds_read_b128 v[212:215], v210 offset:7168
	global_load_lds_dwordx4 v136, s[24:25]
	s_add_i32 m0, s30, 0xe000
	s_nop 0
	global_load_lds_dwordx4 v138, s[24:25]
	s_waitcnt vmcnt(8)
	s_waitcnt lgkmcnt(0)
	s_setprio 1
	s_barrier
	v_mfma_f32_16x16x32_bf16 v[124:127], v[144:147], v[176:179], v[124:127]
	v_mfma_f32_16x16x32_bf16 v[120:123], v[152:155], v[176:179], v[120:123]
	v_mfma_f32_16x16x32_bf16 v[116:119], v[144:147], v[184:187], v[116:119]
	v_mfma_f32_16x16x32_bf16 v[112:115], v[152:155], v[184:187], v[112:115]
	v_mfma_f32_16x16x32_bf16 v[104:107], v[144:147], v[194:197], v[104:107]
	v_mfma_f32_16x16x32_bf16 v[96:99], v[152:155], v[194:197], v[96:99]
	v_mfma_f32_16x16x32_bf16 v[88:91], v[144:147], v[202:205], v[88:91]
	v_mfma_f32_16x16x32_bf16 v[80:83], v[152:155], v[202:205], v[80:83]
	v_mfma_f32_16x16x32_bf16 v[124:127], v[148:151], v[180:183], v[124:127]
	v_mfma_f32_16x16x32_bf16 v[120:123], v[156:159], v[180:183], v[120:123]
	v_mfma_f32_16x16x32_bf16 v[116:119], v[148:151], v[188:191], v[116:119]
	v_mfma_f32_16x16x32_bf16 v[112:115], v[156:159], v[188:191], v[112:115]
	v_mfma_f32_16x16x32_bf16 v[104:107], v[148:151], v[198:201], v[104:107]
	v_mfma_f32_16x16x32_bf16 v[96:99], v[156:159], v[198:201], v[96:99]
	v_mfma_f32_16x16x32_bf16 v[88:91], v[148:151], v[212:215], v[88:91]
	v_mfma_f32_16x16x32_bf16 v[80:83], v[156:159], v[212:215], v[80:83]
	v_mfma_f32_16x16x32_bf16 v[108:111], v[160:163], v[176:179], v[108:111]
	v_mfma_f32_16x16x32_bf16 v[100:103], v[168:171], v[176:179], v[100:103]
	v_mfma_f32_16x16x32_bf16 v[92:95], v[160:163], v[184:187], v[92:95]
	v_mfma_f32_16x16x32_bf16 v[84:87], v[168:171], v[184:187], v[84:87]
	v_mfma_f32_16x16x32_bf16 v[76:79], v[160:163], v[194:197], v[76:79]
	v_mfma_f32_16x16x32_bf16 v[72:75], v[168:171], v[194:197], v[72:75]
	v_mfma_f32_16x16x32_bf16 v[68:71], v[160:163], v[202:205], v[68:71]
	v_mfma_f32_16x16x32_bf16 v[64:67], v[168:171], v[202:205], v[64:67]
	v_mfma_f32_16x16x32_bf16 v[108:111], v[164:167], v[180:183], v[108:111]
	v_mfma_f32_16x16x32_bf16 v[100:103], v[172:175], v[180:183], v[100:103]
	v_mfma_f32_16x16x32_bf16 v[92:95], v[164:167], v[188:191], v[92:95]
	v_mfma_f32_16x16x32_bf16 v[84:87], v[172:175], v[188:191], v[84:87]
	v_mfma_f32_16x16x32_bf16 v[76:79], v[164:167], v[198:201], v[76:79]
	v_mfma_f32_16x16x32_bf16 v[72:75], v[172:175], v[198:201], v[72:75]
	v_mfma_f32_16x16x32_bf16 v[68:71], v[164:167], v[212:215], v[68:71]
	v_mfma_f32_16x16x32_bf16 v[64:67], v[172:175], v[212:215], v[64:67]
	s_barrier
	s_setprio 0
	s_add_u32 s98, s26, s16
	s_addc_u32 s99, s27, s17
	s_add_i32 s53, s44, s5
	s_mov_b32 m0, s53
	ds_read_b128 v[176:179], v210 offset:16384
	ds_read_b128 v[180:183], v210 offset:17408
	ds_read_b128 v[184:187], v210 offset:18432
	ds_read_b128 v[188:191], v210 offset:19456
	ds_read_b128 v[194:197], v210 offset:20480
	ds_read_b128 v[198:201], v210 offset:21504
	ds_read_b128 v[202:205], v210 offset:22528
	ds_read_b128 v[212:215], v210 offset:23552
	global_load_lds_dwordx4 v130, s[26:27]
	s_add_i32 m0, s53, 0x2000
	s_add_u32 s54, s26, 0x160000
	s_addc_u32 s55, s27, 0
	s_add_i32 s53, s45, s5
	global_load_lds_dwordx4 v134, s[26:27]
	s_mov_b32 m0, s53
	s_nop 0
	global_load_lds_dwordx4 v130, s[54:55]
	s_add_i32 m0, s53, 0x2000
	s_nop 0
	global_load_lds_dwordx4 v134, s[54:55]
	s_waitcnt vmcnt(6)
	s_waitcnt lgkmcnt(0)
	s_setprio 1
	s_barrier
	v_mfma_f32_16x16x32_bf16 v[60:63], v[144:147], v[176:179], v[60:63]
	v_mfma_f32_16x16x32_bf16 v[56:59], v[152:155], v[176:179], v[56:59]
	v_mfma_f32_16x16x32_bf16 v[52:55], v[144:147], v[184:187], v[52:55]
	v_mfma_f32_16x16x32_bf16 v[48:51], v[152:155], v[184:187], v[48:51]
	v_mfma_f32_16x16x32_bf16 v[40:43], v[144:147], v[194:197], v[40:43]
	v_mfma_f32_16x16x32_bf16 v[32:35], v[152:155], v[194:197], v[32:35]
	v_mfma_f32_16x16x32_bf16 v[24:27], v[144:147], v[202:205], v[24:27]
	v_mfma_f32_16x16x32_bf16 v[16:19], v[152:155], v[202:205], v[16:19]
	v_mfma_f32_16x16x32_bf16 v[60:63], v[148:151], v[180:183], v[60:63]
	v_mfma_f32_16x16x32_bf16 v[56:59], v[156:159], v[180:183], v[56:59]
	v_mfma_f32_16x16x32_bf16 v[52:55], v[148:151], v[188:191], v[52:55]
	v_mfma_f32_16x16x32_bf16 v[48:51], v[156:159], v[188:191], v[48:51]
	v_mfma_f32_16x16x32_bf16 v[40:43], v[148:151], v[198:201], v[40:43]
	v_mfma_f32_16x16x32_bf16 v[32:35], v[156:159], v[198:201], v[32:35]
	v_mfma_f32_16x16x32_bf16 v[24:27], v[148:151], v[212:215], v[24:27]
	v_mfma_f32_16x16x32_bf16 v[16:19], v[156:159], v[212:215], v[16:19]
	v_mfma_f32_16x16x32_bf16 v[44:47], v[160:163], v[176:179], v[44:47]
	v_mfma_f32_16x16x32_bf16 v[36:39], v[168:171], v[176:179], v[36:39]
	v_mfma_f32_16x16x32_bf16 v[28:31], v[160:163], v[184:187], v[28:31]
	v_mfma_f32_16x16x32_bf16 v[20:23], v[168:171], v[184:187], v[20:23]
	v_mfma_f32_16x16x32_bf16 v[12:15], v[160:163], v[194:197], v[12:15]
	v_mfma_f32_16x16x32_bf16 v[8:11], v[168:171], v[194:197], v[8:11]
	v_mfma_f32_16x16x32_bf16 v[4:7], v[160:163], v[202:205], v[4:7]
	v_mfma_f32_16x16x32_bf16 v[0:3], v[168:171], v[202:205], v[0:3]
	v_mfma_f32_16x16x32_bf16 v[44:47], v[164:167], v[180:183], v[44:47]
	v_mfma_f32_16x16x32_bf16 v[36:39], v[172:175], v[180:183], v[36:39]
	v_mfma_f32_16x16x32_bf16 v[28:31], v[164:167], v[188:191], v[28:31]
	v_mfma_f32_16x16x32_bf16 v[20:23], v[172:175], v[188:191], v[20:23]
	v_mfma_f32_16x16x32_bf16 v[12:15], v[164:167], v[198:201], v[12:15]
	v_mfma_f32_16x16x32_bf16 v[8:11], v[172:175], v[198:201], v[8:11]
	v_mfma_f32_16x16x32_bf16 v[4:7], v[164:167], v[212:215], v[4:7]
	v_mfma_f32_16x16x32_bf16 v[0:3], v[172:175], v[212:215], v[0:3]
	s_barrier
; #define PG8_STAGE(bufoff, gbase, voff) do { _Pragma("unroll") for (int _i = 0; _i < 2; ++_i) \
;         __builtin_amdgcn_global_load_lds((const unsigned*)((const char*)(gbase) + (voff)[_i]), (LAS unsigned*)(lds + (bufoff) + ldsw + _i * 8192), 16, 0, ((voff) == voffA ? AUXA : 0)); } while (0)
; #define PG8_LDA(dst, b, h) do { _Pragma("unroll") for (int m = 0; m < 4; ++m) _Pragma("unroll") for (int k = 0; k < 2; ++k) dst[m][k] = *(const LAS bf16x8*)(lds + PG8_SA(b, h) + aoff + m * 2048 + k * 1024); } while (0)
; #define PG8_LDB(dst, b, h) do { _Pragma("unroll") for (int n = 0; n < 2; ++n) _Pragma("unroll") for (int k = 0; k < 2; ++k) dst[n][k] = *(const LAS bf16x8*)(lds + PG8_SB(b, h) + boff + n * 2048 + k * 1024); } while (0)
; #define PG8_MMA(ai, bj, At, Bt) do { __builtin_amdgcn_s_setprio(1); _Pragma("unroll") for (int m = 0; m < 4; ++m) _Pragma("unroll") for (int n = 0; n < 2; ++n) _Pragma("unroll") for (int k = 0; k < 2; ++k) \
;         acc[ai][bj][m][n] = __builtin_amdgcn_mfma_f32_16x16x32_bf16(Bt[n][k], At[m][k], acc[ai][bj][m][n], 0, 0, 0); __builtin_amdgcn_s_setprio(0); } while (0)
; #define PG8_WAIT_V(n) asm volatile("s_waitcnt vmcnt(" #n ")" ::: "memory")
; #define PG8_WAIT_L(n) asm volatile("s_waitcnt lgkmcnt(" #n ")" ::: "memory")
; #define PG8_BAR __builtin_amdgcn_s_barrier()
; #define PG8_SCHED __builtin_amdgcn_sched_barrier(0)
;     ...
;             PG8_LDB(B0, 1, 0); PG8_LDB(B1, 1, 1); PG8_SCHED; PG8_LDA(At, 1, 0); PG8_STAGE(PG8_SA(0, 1), a2 + hsA, voffA);
;             PG8_WAIT_V(8); PG8_WAIT_L(0); PG8_BAR; PG8_MMA(0, 0, At, B0); PG8_MMA(0, 1, At, B1); PG8_BAR; PG8_SCHED;
;             PG8_LDA(At, 1, 1); PG8_STAGE(PG8_SB(1, 0), b3, voffB); PG8_STAGE(PG8_SB(1, 1), b3 + hsB, voffB); PG8_STAGE(PG8_SA(1, 0), a3, voffA);
	s_mov_b32 m0, s30
	s_nop 0
	global_load_lds_dwordx4 v128, s[28:29]
	s_mov_b32 m0, s31
	s_nop 0
	global_load_lds_dwordx4 v132, s[28:29]
	s_setprio 0
	s_add_i32 s53, 0, 0x18000
	s_add_i32 s54, 0, 0x1c000
	v_add_u32_e32 v156, s53, v206
	v_add_u32_e32 v172, s54, v206
	ds_read_b128 v[144:147], v156
	ds_read_b128 v[148:151], v156 offset:1024
	ds_read_b128 v[152:155], v156 offset:2048
	ds_read_b128 v[156:159], v156 offset:3072
	ds_read_b128 v[160:163], v172
	ds_read_b128 v[164:167], v172 offset:1024
	ds_read_b128 v[168:171], v172 offset:2048
	ds_read_b128 v[172:175], v172 offset:3072
	s_add_u32 s28, s28, 0x160000
	s_addc_u32 s29, s29, 0
	s_mov_b32 m0, s34
	ds_read_b128 v[176:179], v210 offset:32768
	ds_read_b128 v[180:183], v210 offset:33792
	ds_read_b128 v[184:187], v210 offset:34816
	ds_read_b128 v[188:191], v210 offset:35840
	ds_read_b128 v[194:197], v210 offset:36864
	ds_read_b128 v[198:201], v210 offset:37888
	ds_read_b128 v[202:205], v210 offset:38912
	ds_read_b128 v[212:215], v210 offset:39936
	global_load_lds_dwordx4 v128, s[28:29]
	s_mov_b32 m0, s35
	s_nop 0
	global_load_lds_dwordx4 v132, s[28:29]
	s_waitcnt vmcnt(8)
	s_waitcnt lgkmcnt(0)
	s_setprio 1
	s_barrier
	v_mfma_f32_16x16x32_bf16 v[124:127], v[144:147], v[176:179], v[124:127]
	v_mfma_f32_16x16x32_bf16 v[120:123], v[152:155], v[176:179], v[120:123]
	v_mfma_f32_16x16x32_bf16 v[116:119], v[144:147], v[184:187], v[116:119]
	v_mfma_f32_16x16x32_bf16 v[112:115], v[152:155], v[184:187], v[112:115]
	v_mfma_f32_16x16x32_bf16 v[104:107], v[144:147], v[194:197], v[104:107]
	v_mfma_f32_16x16x32_bf16 v[96:99], v[152:155], v[194:197], v[96:99]
	v_mfma_f32_16x16x32_bf16 v[88:91], v[144:147], v[202:205], v[88:91]
	v_mfma_f32_16x16x32_bf16 v[80:83], v[152:155], v[202:205], v[80:83]
	v_mfma_f32_16x16x32_bf16 v[124:127], v[148:151], v[180:183], v[124:127]
	v_mfma_f32_16x16x32_bf16 v[120:123], v[156:159], v[180:183], v[120:123]
	v_mfma_f32_16x16x32_bf16 v[116:119], v[148:151], v[188:191], v[116:119]
	v_mfma_f32_16x16x32_bf16 v[112:115], v[156:159], v[188:191], v[112:115]
	v_mfma_f32_16x16x32_bf16 v[104:107], v[148:151], v[198:201], v[104:107]
	v_mfma_f32_16x16x32_bf16 v[96:99], v[156:159], v[198:201], v[96:99]
	v_mfma_f32_16x16x32_bf16 v[88:91], v[148:151], v[212:215], v[88:91]
	v_mfma_f32_16x16x32_bf16 v[80:83], v[156:159], v[212:215], v[80:83]
	v_mfma_f32_16x16x32_bf16 v[108:111], v[160:163], v[176:179], v[108:111]
	v_mfma_f32_16x16x32_bf16 v[100:103], v[168:171], v[176:179], v[100:103]
	v_mfma_f32_16x16x32_bf16 v[92:95], v[160:163], v[184:187], v[92:95]
	v_mfma_f32_16x16x32_bf16 v[84:87], v[168:171], v[184:187], v[84:87]
	v_mfma_f32_16x16x32_bf16 v[76:79], v[160:163], v[194:197], v[76:79]
	v_mfma_f32_16x16x32_bf16 v[72:75], v[168:171], v[194:197], v[72:75]
	v_mfma_f32_16x16x32_bf16 v[68:71], v[160:163], v[202:205], v[68:71]
	v_mfma_f32_16x16x32_bf16 v[64:67], v[168:171], v[202:205], v[64:67]
	v_mfma_f32_16x16x32_bf16 v[108:111], v[164:167], v[180:183], v[108:111]
	v_mfma_f32_16x16x32_bf16 v[100:103], v[172:175], v[180:183], v[100:103]
	v_mfma_f32_16x16x32_bf16 v[92:95], v[164:167], v[188:191], v[92:95]
	v_mfma_f32_16x16x32_bf16 v[84:87], v[172:175], v[188:191], v[84:87]
	v_mfma_f32_16x16x32_bf16 v[76:79], v[164:167], v[198:201], v[76:79]
	v_mfma_f32_16x16x32_bf16 v[72:75], v[172:175], v[198:201], v[72:75]
	v_mfma_f32_16x16x32_bf16 v[68:71], v[164:167], v[212:215], v[68:71]
	v_mfma_f32_16x16x32_bf16 v[64:67], v[172:175], v[212:215], v[64:67]
	s_barrier
	s_setprio 0
	s_add_i32 s28, s53, s5
	s_mov_b32 m0, s28
	ds_read_b128 v[176:179], v210 offset:49152
	ds_read_b128 v[180:183], v210 offset:50176
	ds_read_b128 v[184:187], v210 offset:51200
	ds_read_b128 v[188:191], v210 offset:52224
	ds_read_b128 v[194:197], v210 offset:53248
	ds_read_b128 v[198:201], v210 offset:54272
	ds_read_b128 v[202:205], v210 offset:55296
	ds_read_b128 v[212:215], v210 offset:56320
	global_load_lds_dwordx4 v130, s[98:99]
	s_add_i32 m0, s28, 0x2000
	s_add_u32 s26, s26, 0x160080
	s_addc_u32 s27, s27, 0
	s_add_i32 s28, s54, s5
	global_load_lds_dwordx4 v134, s[98:99]
	s_mov_b32 m0, s28
	s_nop 0
	global_load_lds_dwordx4 v130, s[26:27]
	s_add_i32 m0, s28, 0x2000
	s_nop 0
	global_load_lds_dwordx4 v134, s[26:27]
	s_waitcnt vmcnt(6)
	s_waitcnt lgkmcnt(0)
	s_setprio 1
	s_barrier
; #define PG8_STAGE(bufoff, gbase, voff) do { _Pragma("unroll") for (int _i = 0; _i < 2; ++_i) \
;         __builtin_amdgcn_global_load_lds((const unsigned*)((const char*)(gbase) + (voff)[_i]), (LAS unsigned*)(lds + (bufoff) + ldsw + _i * 8192), 16, 0, ((voff) == voffA ? AUXA : 0)); } while (0)
; #define PG8_LDA(dst, b, h) do { _Pragma("unroll") for (int m = 0; m < 4; ++m) _Pragma("unroll") for (int k = 0; k < 2; ++k) dst[m][k] = *(const LAS bf16x8*)(lds + PG8_SA(b, h) + aoff + m * 2048 + k * 1024); } while (0)
; #define PG8_MMA(ai, bj, At, Bt) do { __builtin_amdgcn_s_setprio(1); _Pragma("unroll") for (int m = 0; m < 4; ++m) _Pragma("unroll") for (int n = 0; n < 2; ++n) _Pragma("unroll") for (int k = 0; k < 2; ++k) \
;         acc[ai][bj][m][n] = __builtin_amdgcn_mfma_f32_16x16x32_bf16(Bt[n][k], At[m][k], acc[ai][bj][m][n], 0, 0, 0); __builtin_amdgcn_s_setprio(0); } while (0)
; #define PG8_WAIT_V(n) asm volatile("s_waitcnt vmcnt(" #n ")" ::: "memory")
; #define PG8_WAIT_L(n) asm volatile("s_waitcnt lgkmcnt(" #n ")" ::: "memory")
; #define PG8_BAR __builtin_amdgcn_s_barrier()
; #define PG8_SCHED __builtin_amdgcn_sched_barrier(0)
;     ...
;             PG8_LDA(At, 1, 1); PG8_STAGE(PG8_SB(1, 0), b3, voffB); PG8_STAGE(PG8_SB(1, 1), b3 + hsB, voffB); PG8_STAGE(PG8_SA(1, 0), a3, voffA);
;             PG8_WAIT_V(8); PG8_WAIT_L(0); PG8_BAR; PG8_MMA(1, 0, At, B0); PG8_MMA(1, 1, At, B1); PG8_BAR; PG8_SCHED;
;         }
;     __device__ __forceinline__ void operator()(const Acc& acc, const Unit& u, int wr, int wc, int fr, int fq, const float (&sv8)[8]) const {
;     ...
;                     const int col = colb + bj * 128;
;                     const f32x4 y0 = xr[m][bj][0] + acc[ai][bj][m][0] * scale, y1 = xr[m][bj][1] + acc[ai][bj][m][1] * scale;
	v_mfma_f32_16x16x32_bf16 v[60:63], v[144:147], v[176:179], v[60:63]
	v_mfma_f32_16x16x32_bf16 v[56:59], v[152:155], v[176:179], v[56:59]
	v_mfma_f32_16x16x32_bf16 v[52:55], v[144:147], v[184:187], v[52:55]
	v_mfma_f32_16x16x32_bf16 v[48:51], v[152:155], v[184:187], v[48:51]
	v_mfma_f32_16x16x32_bf16 v[40:43], v[144:147], v[194:197], v[40:43]
	v_mfma_f32_16x16x32_bf16 v[32:35], v[152:155], v[194:197], v[32:35]
	v_mfma_f32_16x16x32_bf16 v[24:27], v[144:147], v[202:205], v[24:27]
	v_mfma_f32_16x16x32_bf16 v[16:19], v[152:155], v[202:205], v[16:19]
	v_mfma_f32_16x16x32_bf16 v[60:63], v[148:151], v[180:183], v[60:63]
	v_mfma_f32_16x16x32_bf16 v[56:59], v[156:159], v[180:183], v[56:59]
	v_mfma_f32_16x16x32_bf16 v[52:55], v[148:151], v[188:191], v[52:55]
	v_mfma_f32_16x16x32_bf16 v[48:51], v[156:159], v[188:191], v[48:51]
	v_mfma_f32_16x16x32_bf16 v[40:43], v[148:151], v[198:201], v[40:43]
	v_mfma_f32_16x16x32_bf16 v[32:35], v[156:159], v[198:201], v[32:35]
	v_mfma_f32_16x16x32_bf16 v[24:27], v[148:151], v[212:215], v[24:27]
	v_mfma_f32_16x16x32_bf16 v[16:19], v[156:159], v[212:215], v[16:19]
	v_mfma_f32_16x16x32_bf16 v[44:47], v[160:163], v[176:179], v[44:47]
	v_mfma_f32_16x16x32_bf16 v[36:39], v[168:171], v[176:179], v[36:39]
	v_mfma_f32_16x16x32_bf16 v[28:31], v[160:163], v[184:187], v[28:31]
	v_mfma_f32_16x16x32_bf16 v[20:23], v[168:171], v[184:187], v[20:23]
	v_mfma_f32_16x16x32_bf16 v[12:15], v[160:163], v[194:197], v[12:15]
	v_mfma_f32_16x16x32_bf16 v[8:11], v[168:171], v[194:197], v[8:11]
	v_mfma_f32_16x16x32_bf16 v[4:7], v[160:163], v[202:205], v[4:7]
	v_mfma_f32_16x16x32_bf16 v[0:3], v[168:171], v[202:205], v[0:3]
	v_mfma_f32_16x16x32_bf16 v[44:47], v[164:167], v[180:183], v[44:47]
	v_mfma_f32_16x16x32_bf16 v[36:39], v[172:175], v[180:183], v[36:39]
	v_mfma_f32_16x16x32_bf16 v[28:31], v[164:167], v[188:191], v[28:31]
	v_mfma_f32_16x16x32_bf16 v[20:23], v[172:175], v[188:191], v[20:23]
	v_mfma_f32_16x16x32_bf16 v[12:15], v[164:167], v[198:201], v[12:15]
	v_mfma_f32_16x16x32_bf16 v[8:11], v[172:175], v[198:201], v[8:11]
	v_mfma_f32_16x16x32_bf16 v[4:7], v[164:167], v[212:215], v[4:7]
	v_mfma_f32_16x16x32_bf16 v[0:3], v[172:175], v[212:215], v[0:3]
	s_barrier
	s_setprio 0
	s_add_u32 s24, s24, 0x100
	s_addc_u32 s25, s25, 0
	s_add_u32 s50, s50, 0x100
	s_addc_u32 s51, s51, 0
	s_cmp_ge_i32 s52, s38
	s_mov_b32 s26, s52
	s_cbranch_scc0 .LBB0_246
	v_pk_mul_f32 v[178:179], v[126:127], 0.5 op_sel_hi:[1,0]
	v_pk_mul_f32 v[184:185], v[124:125], 0.5 op_sel_hi:[1,0]
	v_pk_mul_f32 v[182:183], v[122:123], 0.5 op_sel_hi:[1,0]
	v_pk_mul_f32 v[180:181], v[120:121], 0.5 op_sel_hi:[1,0]
	v_pk_mul_f32 v[194:195], v[110:111], 0.5 op_sel_hi:[1,0]
	v_pk_mul_f32 v[190:191], v[108:109], 0.5 op_sel_hi:[1,0]
	v_pk_mul_f32 v[188:189], v[102:103], 0.5 op_sel_hi:[1,0]
	v_pk_mul_f32 v[186:187], v[100:101], 0.5 op_sel_hi:[1,0]
	v_pk_mul_f32 v[168:169], v[118:119], 0.5 op_sel_hi:[1,0]
	v_pk_mul_f32 v[166:167], v[116:117], 0.5 op_sel_hi:[1,0]
	v_pk_mul_f32 v[164:165], v[114:115], 0.5 op_sel_hi:[1,0]
	v_pk_mul_f32 v[162:163], v[112:113], 0.5 op_sel_hi:[1,0]
	v_pk_mul_f32 v[176:177], v[94:95], 0.5 op_sel_hi:[1,0]
	v_pk_mul_f32 v[174:175], v[92:93], 0.5 op_sel_hi:[1,0]
	v_pk_mul_f32 v[172:173], v[86:87], 0.5 op_sel_hi:[1,0]
	v_pk_mul_f32 v[170:171], v[84:85], 0.5 op_sel_hi:[1,0]
	v_pk_mul_f32 v[152:153], v[106:107], 0.5 op_sel_hi:[1,0]
	v_pk_mul_f32 v[150:151], v[104:105], 0.5 op_sel_hi:[1,0]
	v_pk_mul_f32 v[148:149], v[98:99], 0.5 op_sel_hi:[1,0]
	v_pk_mul_f32 v[146:147], v[96:97], 0.5 op_sel_hi:[1,0]
	v_pk_mul_f32 v[160:161], v[78:79], 0.5 op_sel_hi:[1,0]
	v_pk_mul_f32 v[158:159], v[76:77], 0.5 op_sel_hi:[1,0]
	v_pk_mul_f32 v[156:157], v[74:75], 0.5 op_sel_hi:[1,0]
	v_pk_mul_f32 v[154:155], v[72:73], 0.5 op_sel_hi:[1,0]
	v_pk_mul_f32 v[120:121], v[90:91], 0.5 op_sel_hi:[1,0]
	v_pk_mul_f32 v[118:119], v[88:89], 0.5 op_sel_hi:[1,0]
	v_pk_mul_f32 v[116:117], v[82:83], 0.5 op_sel_hi:[1,0]
	v_pk_mul_f32 v[114:115], v[80:81], 0.5 op_sel_hi:[1,0]
	v_pk_mul_f32 v[144:145], v[70:71], 0.5 op_sel_hi:[1,0]
	v_pk_mul_f32 v[126:127], v[68:69], 0.5 op_sel_hi:[1,0]
	v_pk_mul_f32 v[124:125], v[66:67], 0.5 op_sel_hi:[1,0]
	v_pk_mul_f32 v[122:123], v[64:65], 0.5 op_sel_hi:[1,0]
	v_pk_mul_f32 v[102:103], v[62:63], 0.5 op_sel_hi:[1,0]
	v_pk_mul_f32 v[100:101], v[60:61], 0.5 op_sel_hi:[1,0]
	v_pk_mul_f32 v[98:99], v[58:59], 0.5 op_sel_hi:[1,0]
	v_pk_mul_f32 v[96:97], v[56:57], 0.5 op_sel_hi:[1,0]
	v_pk_mul_f32 v[110:111], v[46:47], 0.5 op_sel_hi:[1,0]
	v_pk_mul_f32 v[108:109], v[44:45], 0.5 op_sel_hi:[1,0]
	v_pk_mul_f32 v[106:107], v[38:39], 0.5 op_sel_hi:[1,0]
	v_pk_mul_f32 v[104:105], v[36:37], 0.5 op_sel_hi:[1,0]
	v_pk_mul_f32 v[86:87], v[54:55], 0.5 op_sel_hi:[1,0]
	v_pk_mul_f32 v[84:85], v[52:53], 0.5 op_sel_hi:[1,0]
	v_pk_mul_f32 v[82:83], v[50:51], 0.5 op_sel_hi:[1,0]
	v_pk_mul_f32 v[80:81], v[48:49], 0.5 op_sel_hi:[1,0]
	v_pk_mul_f32 v[94:95], v[30:31], 0.5 op_sel_hi:[1,0]
	v_pk_mul_f32 v[92:93], v[28:29], 0.5 op_sel_hi:[1,0]
	v_pk_mul_f32 v[90:91], v[22:23], 0.5 op_sel_hi:[1,0]
	v_pk_mul_f32 v[88:89], v[20:21], 0.5 op_sel_hi:[1,0]
	v_pk_mul_f32 v[70:71], v[42:43], 0.5 op_sel_hi:[1,0]
	v_pk_mul_f32 v[68:69], v[40:41], 0.5 op_sel_hi:[1,0]
	v_pk_mul_f32 v[66:67], v[34:35], 0.5 op_sel_hi:[1,0]
	v_pk_mul_f32 v[64:65], v[32:33], 0.5 op_sel_hi:[1,0]
	v_pk_mul_f32 v[78:79], v[14:15], 0.5 op_sel_hi:[1,0]
	v_pk_mul_f32 v[76:77], v[12:13], 0.5 op_sel_hi:[1,0]
	v_pk_mul_f32 v[74:75], v[10:11], 0.5 op_sel_hi:[1,0]
	v_pk_mul_f32 v[72:73], v[8:9], 0.5 op_sel_hi:[1,0]
	v_pk_mul_f32 v[54:55], v[26:27], 0.5 op_sel_hi:[1,0]
	v_pk_mul_f32 v[52:53], v[24:25], 0.5 op_sel_hi:[1,0]
	v_pk_mul_f32 v[50:51], v[18:19], 0.5 op_sel_hi:[1,0]
	v_pk_mul_f32 v[48:49], v[16:17], 0.5 op_sel_hi:[1,0]
	v_pk_mul_f32 v[62:63], v[6:7], 0.5 op_sel_hi:[1,0]
	v_pk_mul_f32 v[60:61], v[4:5], 0.5 op_sel_hi:[1,0]
	v_pk_mul_f32 v[58:59], v[2:3], 0.5 op_sel_hi:[1,0]
	v_pk_mul_f32 v[56:57], v[0:1], 0.5 op_sel_hi:[1,0]

; #define PG8_STAGE(bufoff, gbase, voff) do { _Pragma("unroll") for (int _i = 0; _i < 2; ++_i) \
;         __builtin_amdgcn_global_load_lds((const unsigned*)((const char*)(gbase) + (voff)[_i]), (LAS unsigned*)(lds + (bufoff) + ldsw + _i * 8192), 16, 0, ((voff) == voffA ? AUXA : 0)); } while (0)
; #define PG8_LDA(dst, b, h) do { _Pragma("unroll") for (int m = 0; m < 4; ++m) _Pragma("unroll") for (int k = 0; k < 2; ++k) dst[m][k] = *(const LAS bf16x8*)(lds + PG8_SA(b, h) + aoff + m * 2048 + k * 1024); } while (0)
; #define PG8_LDB(dst, b, h) do { _Pragma("unroll") for (int n = 0; n < 2; ++n) _Pragma("unroll") for (int k = 0; k < 2; ++k) dst[n][k] = *(const LAS bf16x8*)(lds + PG8_SB(b, h) + boff + n * 2048 + k * 1024); } while (0)
; #define PG8_WAIT_V(n) asm volatile("s_waitcnt vmcnt(" #n ")" ::: "memory")
; #define PG8_SCHED __builtin_amdgcn_sched_barrier(0)
;     ...
;             const bool last = (t == nt - 2);
;             const char* a1 = cA + (size_t)(t + 1) * kstep;
;             const char* a2 = last ? nA : cA + (size_t)(t + 2) * kstep; const char* b2 = last ? nB : cB + (size_t)(t + 2) * kstep;
;             const char* a3 = a2 + kstep; const char* b3 = b2 + kstep;
;             PG8_LDB(B0, 0, 0); PG8_LDB(B1, 0, 1); PG8_SCHED; PG8_LDA(At, 0, 0); PG8_STAGE(PG8_SA(1, 1), a1 + hsA, voffA);
;             if (Epi::NPRE != 0 && last) { E.pre(sv, cur, wr, fr); PG8_WAIT_V(16); } else { PG8_WAIT_V(8); }
.LBB0_371:
	s_add_u32 s98, s28, 0xfff80000
	s_mov_b32 m0, s50
	s_addc_u32 s99, s29, -1
	global_load_lds_dwordx4 v194, s[98:99]
	s_mov_b32 m0, s51
	s_nop 0
	global_load_lds_dwordx4 v198, s[98:99]
	ds_read_b128 v[144:147], v237
	ds_read_b128 v[148:151], v237 offset:1024
	ds_read_b128 v[152:155], v237 offset:2048
	ds_read_b128 v[156:159], v237 offset:3072
	ds_read_b128 v[128:131], v238
	ds_read_b128 v[132:135], v238 offset:1024
	ds_read_b128 v[136:139], v238 offset:2048
	ds_read_b128 v[140:143], v238 offset:3072
	s_cmp_eq_u32 s53, s71
	s_cselect_b64 s[30:31], -1, 0
	s_cmp_lg_u32 s53, s71
	s_cselect_b64 s[36:37], -1, 0
	s_add_i32 m0, s13, 0xc000
	ds_read_b128 v[184:187], v239
	ds_read_b128 v[188:191], v239 offset:1024
	ds_read_b128 v[176:179], v239 offset:2048
	ds_read_b128 v[180:183], v239 offset:3072
	ds_read_b128 v[168:171], v239 offset:4096
	ds_read_b128 v[172:175], v239 offset:5120
	ds_read_b128 v[160:163], v239 offset:6144
	ds_read_b128 v[164:167], v239 offset:7168
	global_load_lds_dwordx4 v216, s[28:29]
	s_add_i32 m0, s13, 0xe000
	s_mov_b64 s[34:35], -1
	global_load_lds_dwordx4 v218, s[28:29]
	s_and_b64 vcc, exec, s[36:37]
	s_cbranch_vccz .LBB0_373
	s_waitcnt vmcnt(8)
	s_mov_b64 s[34:35], 0

; #define PG8_STAGE(bufoff, gbase, voff) do { _Pragma("unroll") for (int _i = 0; _i < 2; ++_i) \
;         __builtin_amdgcn_global_load_lds((const unsigned*)((const char*)(gbase) + (voff)[_i]), (LAS unsigned*)(lds + (bufoff) + ldsw + _i * 8192), 16, 0, ((voff) == voffA ? AUXA : 0)); } while (0)
; #define PG8_LDA(dst, b, h) do { _Pragma("unroll") for (int m = 0; m < 4; ++m) _Pragma("unroll") for (int k = 0; k < 2; ++k) dst[m][k] = *(const LAS bf16x8*)(lds + PG8_SA(b, h) + aoff + m * 2048 + k * 1024); } while (0)
; #define PG8_LDB(dst, b, h) do { _Pragma("unroll") for (int n = 0; n < 2; ++n) _Pragma("unroll") for (int k = 0; k < 2; ++k) dst[n][k] = *(const LAS bf16x8*)(lds + PG8_SB(b, h) + boff + n * 2048 + k * 1024); } while (0)
; #define PG8_MMA(ai, bj, At, Bt) do { __builtin_amdgcn_s_setprio(1); _Pragma("unroll") for (int m = 0; m < 4; ++m) _Pragma("unroll") for (int n = 0; n < 2; ++n) _Pragma("unroll") for (int k = 0; k < 2; ++k) \
;         acc[ai][bj][m][n] = __builtin_amdgcn_mfma_f32_16x16x32_bf16(Bt[n][k], At[m][k], acc[ai][bj][m][n], 0, 0, 0); __builtin_amdgcn_s_setprio(0); } while (0)
; #define PG8_WAIT_V(n) asm volatile("s_waitcnt vmcnt(" #n ")" ::: "memory")
; #define PG8_WAIT_L(n) asm volatile("s_waitcnt lgkmcnt(" #n ")" ::: "memory")
; #define PG8_BAR __builtin_amdgcn_s_barrier()
; #define PG8_SCHED __builtin_amdgcn_sched_barrier(0)
;     ...
;             const char* a2 = last ? nA : cA + (size_t)(t + 2) * kstep; const char* b2 = last ? nB : cB + (size_t)(t + 2) * kstep;
;             const char* a3 = a2 + kstep; const char* b3 = b2 + kstep;
;             PG8_LDB(B0, 0, 0); PG8_LDB(B1, 0, 1); PG8_SCHED; PG8_LDA(At, 0, 0); PG8_STAGE(PG8_SA(1, 1), a1 + hsA, voffA);
;             if (Epi::NPRE != 0 && last) { E.pre(sv, cur, wr, fr); PG8_WAIT_V(16); } else { PG8_WAIT_V(8); }
;             PG8_WAIT_L(0); PG8_BAR; PG8_MMA(0, 0, At, B0); PG8_MMA(0, 1, At, B1); PG8_BAR; PG8_SCHED;
;             PG8_LDA(At, 0, 1); PG8_STAGE(PG8_SB(0, 0), b2, voffB); PG8_STAGE(PG8_SB(0, 1), b2 + hsB, voffB); PG8_STAGE(PG8_SA(0, 0), a2, voffA);
;             if (Epi::NPRE != 0 && last) { PG8_WAIT_V(16); } else { PG8_WAIT_V(8); }
.LBB0_375:
	s_add_u32 s34, s28, 0xfff80080
	s_addc_u32 s35, s29, -1
	s_waitcnt lgkmcnt(0)
	s_and_b64 s[30:31], s[30:31], exec
	s_cselect_b32 s35, s7, s35
	s_cselect_b32 s34, s21, s34
	s_cselect_b32 s31, s23, s70
	s_cselect_b32 s30, s68, s69
	s_setprio 1
	s_barrier
	v_mfma_f32_16x16x32_bf16 v[124:127], v[144:147], v[184:187], v[124:127]
	v_mfma_f32_16x16x32_bf16 v[120:123], v[152:155], v[184:187], v[120:123]
	v_mfma_f32_16x16x32_bf16 v[108:111], v[144:147], v[176:179], v[108:111]
	v_mfma_f32_16x16x32_bf16 v[104:107], v[152:155], v[176:179], v[104:107]
	v_mfma_f32_16x16x32_bf16 v[92:95], v[144:147], v[168:171], v[92:95]
	v_mfma_f32_16x16x32_bf16 v[88:91], v[152:155], v[168:171], v[88:91]
	v_mfma_f32_16x16x32_bf16 v[76:79], v[144:147], v[160:163], v[76:79]
	v_mfma_f32_16x16x32_bf16 v[72:75], v[152:155], v[160:163], v[72:75]
	v_mfma_f32_16x16x32_bf16 v[124:127], v[148:151], v[188:191], v[124:127]
	v_mfma_f32_16x16x32_bf16 v[120:123], v[156:159], v[188:191], v[120:123]
	v_mfma_f32_16x16x32_bf16 v[108:111], v[148:151], v[180:183], v[108:111]
	v_mfma_f32_16x16x32_bf16 v[104:107], v[156:159], v[180:183], v[104:107]
	v_mfma_f32_16x16x32_bf16 v[92:95], v[148:151], v[172:175], v[92:95]
	v_mfma_f32_16x16x32_bf16 v[88:91], v[156:159], v[172:175], v[88:91]
	v_mfma_f32_16x16x32_bf16 v[76:79], v[148:151], v[164:167], v[76:79]
	v_mfma_f32_16x16x32_bf16 v[72:75], v[156:159], v[164:167], v[72:75]
	v_mfma_f32_16x16x32_bf16 v[116:119], v[128:131], v[184:187], v[116:119]
	v_mfma_f32_16x16x32_bf16 v[112:115], v[136:139], v[184:187], v[112:115]
	v_mfma_f32_16x16x32_bf16 v[100:103], v[128:131], v[176:179], v[100:103]
	v_mfma_f32_16x16x32_bf16 v[96:99], v[136:139], v[176:179], v[96:99]
	v_mfma_f32_16x16x32_bf16 v[84:87], v[128:131], v[168:171], v[84:87]
	v_mfma_f32_16x16x32_bf16 v[80:83], v[136:139], v[168:171], v[80:83]
	v_mfma_f32_16x16x32_bf16 v[68:71], v[128:131], v[160:163], v[68:71]
	v_mfma_f32_16x16x32_bf16 v[64:67], v[136:139], v[160:163], v[64:67]
	v_mfma_f32_16x16x32_bf16 v[116:119], v[132:135], v[188:191], v[116:119]
	v_mfma_f32_16x16x32_bf16 v[112:115], v[140:143], v[188:191], v[112:115]
	v_mfma_f32_16x16x32_bf16 v[100:103], v[132:135], v[180:183], v[100:103]
	v_mfma_f32_16x16x32_bf16 v[96:99], v[140:143], v[180:183], v[96:99]
	v_mfma_f32_16x16x32_bf16 v[84:87], v[132:135], v[172:175], v[84:87]
	v_mfma_f32_16x16x32_bf16 v[80:83], v[140:143], v[172:175], v[80:83]
	v_mfma_f32_16x16x32_bf16 v[68:71], v[132:135], v[164:167], v[68:71]
	v_mfma_f32_16x16x32_bf16 v[64:67], v[140:143], v[164:167], v[64:67]
	s_barrier
	s_setprio 0
	s_add_u32 s98, s30, s10
	s_addc_u32 s99, s31, s11
	s_mov_b32 m0, s40
	s_add_u32 s38, s30, 0x80000
	ds_read_b128 v[184:187], v239 offset:16384
	ds_read_b128 v[188:191], v239 offset:17408
	ds_read_b128 v[176:179], v239 offset:18432
	ds_read_b128 v[180:183], v239 offset:19456
	ds_read_b128 v[168:171], v239 offset:20480
	ds_read_b128 v[172:175], v239 offset:21504
	ds_read_b128 v[160:163], v239 offset:22528
	ds_read_b128 v[164:167], v239 offset:23552
	global_load_lds_dwordx4 v196, s[30:31]
	s_mov_b32 m0, s41
	s_addc_u32 s39, s31, 0
	global_load_lds_dwordx4 v200, s[30:31]
	s_mov_b32 m0, s42
	s_nop 0
	global_load_lds_dwordx4 v196, s[38:39]
	s_mov_b32 m0, s43
	s_nop 0
	global_load_lds_dwordx4 v200, s[38:39]
	s_mov_b64 s[38:39], -1
	s_and_b64 vcc, exec, s[36:37]
	s_cbranch_vccz .LBB0_377
	s_waitcnt vmcnt(6)
	s_mov_b64 s[38:39], 0

; #define PG8_STAGE(bufoff, gbase, voff) do { _Pragma("unroll") for (int _i = 0; _i < 2; ++_i) \
;         __builtin_amdgcn_global_load_lds((const unsigned*)((const char*)(gbase) + (voff)[_i]), (LAS unsigned*)(lds + (bufoff) + ldsw + _i * 8192), 16, 0, ((voff) == voffA ? AUXA : 0)); } while (0)
; #define PG8_LDA(dst, b, h) do { _Pragma("unroll") for (int m = 0; m < 4; ++m) _Pragma("unroll") for (int k = 0; k < 2; ++k) dst[m][k] = *(const LAS bf16x8*)(lds + PG8_SA(b, h) + aoff + m * 2048 + k * 1024); } while (0)
; #define PG8_LDB(dst, b, h) do { _Pragma("unroll") for (int n = 0; n < 2; ++n) _Pragma("unroll") for (int k = 0; k < 2; ++k) dst[n][k] = *(const LAS bf16x8*)(lds + PG8_SB(b, h) + boff + n * 2048 + k * 1024); } while (0)
; #define PG8_MMA(ai, bj, At, Bt) do { __builtin_amdgcn_s_setprio(1); _Pragma("unroll") for (int m = 0; m < 4; ++m) _Pragma("unroll") for (int n = 0; n < 2; ++n) _Pragma("unroll") for (int k = 0; k < 2; ++k) \
;         acc[ai][bj][m][n] = __builtin_amdgcn_mfma_f32_16x16x32_bf16(Bt[n][k], At[m][k], acc[ai][bj][m][n], 0, 0, 0); __builtin_amdgcn_s_setprio(0); } while (0)
; #define PG8_WAIT_V(n) asm volatile("s_waitcnt vmcnt(" #n ")" ::: "memory")
; #define PG8_WAIT_L(n) asm volatile("s_waitcnt lgkmcnt(" #n ")" ::: "memory")
; #define PG8_BAR __builtin_amdgcn_s_barrier()
; #define PG8_SCHED __builtin_amdgcn_sched_barrier(0)
;     ...
;         for (int t = 0; t < nt; t += 2) {
;             const bool last = (t == nt - 2);
;             const char* a1 = cA + (size_t)(t + 1) * kstep;
;             const char* a2 = last ? nA : cA + (size_t)(t + 2) * kstep; const char* b2 = last ? nB : cB + (size_t)(t + 2) * kstep;
;             const char* a3 = a2 + kstep; const char* b3 = b2 + kstep;
;             PG8_LDB(B0, 0, 0); PG8_LDB(B1, 0, 1); PG8_SCHED; PG8_LDA(At, 0, 0); PG8_STAGE(PG8_SA(1, 1), a1 + hsA, voffA);
;             if (Epi::NPRE != 0 && last) { E.pre(sv, cur, wr, fr); PG8_WAIT_V(16); } else { PG8_WAIT_V(8); }
;             PG8_WAIT_L(0); PG8_BAR; PG8_MMA(0, 0, At, B0); PG8_MMA(0, 1, At, B1); PG8_BAR; PG8_SCHED;
;             PG8_LDA(At, 0, 1); PG8_STAGE(PG8_SB(0, 0), b2, voffB); PG8_STAGE(PG8_SB(0, 1), b2 + hsB, voffB); PG8_STAGE(PG8_SA(0, 0), a2, voffA);
;             if (Epi::NPRE != 0 && last) { PG8_WAIT_V(16); } else { PG8_WAIT_V(8); }
;             PG8_WAIT_L(0); PG8_BAR; PG8_MMA(1, 0, At, B0); PG8_MMA(1, 1, At, B1); PG8_BAR; PG8_SCHED;
.LBB0_648:
	s_add_u32 s98, s22, 0xfffe0000
	s_mov_b32 m0, s36
	s_addc_u32 s99, s23, -1
	global_load_lds_dwordx4 v134, s[98:99]
	s_mov_b32 m0, s37
	s_nop 0
	global_load_lds_dwordx4 v130, s[98:99]
	ds_read_b128 v[148:151], v143
	ds_read_b128 v[152:155], v143 offset:1024
	ds_read_b128 v[156:159], v143 offset:2048
	ds_read_b128 v[160:163], v143 offset:3072
	ds_read_b128 v[164:167], v144
	ds_read_b128 v[168:171], v144 offset:1024
	ds_read_b128 v[172:175], v144 offset:2048
	ds_read_b128 v[176:179], v144 offset:3072
	s_add_i32 s56, s24, 2
	s_add_u32 s25, s22, 0xfffe0080
	s_addc_u32 s26, s23, -1
	s_cmp_eq_u32 s38, s24
	s_cselect_b32 s24, s53, s54
	s_cselect_b32 s27, s50, s26
	s_cselect_b32 s26, s51, s25
	s_cselect_b32 s25, s52, s55
	s_mov_b32 m0, s39
	ds_read_b128 v[180:183], v145
	ds_read_b128 v[184:187], v145 offset:1024
	ds_read_b128 v[188:191], v145 offset:2048
	ds_read_b128 v[194:197], v145 offset:3072
	ds_read_b128 v[198:201], v145 offset:4096
	ds_read_b128 v[202:205], v145 offset:5120
	ds_read_b128 v[206:209], v145 offset:6144
	ds_read_b128 v[210:213], v145 offset:7168
	global_load_lds_dwordx4 v138, s[22:23]
	s_mov_b32 m0, s40
	s_nop 0
	global_load_lds_dwordx4 v140, s[22:23]
	s_waitcnt vmcnt(8)
	s_waitcnt lgkmcnt(0)
	s_setprio 1
	s_barrier
	v_mfma_f32_16x16x32_bf16 v[124:127], v[148:151], v[180:183], v[124:127]
	v_mfma_f32_16x16x32_bf16 v[120:123], v[156:159], v[180:183], v[120:123]
	v_mfma_f32_16x16x32_bf16 v[108:111], v[148:151], v[188:191], v[108:111]
	v_mfma_f32_16x16x32_bf16 v[104:107], v[156:159], v[188:191], v[104:107]
	v_mfma_f32_16x16x32_bf16 v[92:95], v[148:151], v[198:201], v[92:95]
	v_mfma_f32_16x16x32_bf16 v[88:91], v[156:159], v[198:201], v[88:91]
	v_mfma_f32_16x16x32_bf16 v[76:79], v[148:151], v[206:209], v[76:79]
	v_mfma_f32_16x16x32_bf16 v[72:75], v[156:159], v[206:209], v[72:75]
	v_mfma_f32_16x16x32_bf16 v[124:127], v[152:155], v[184:187], v[124:127]
	v_mfma_f32_16x16x32_bf16 v[120:123], v[160:163], v[184:187], v[120:123]
	v_mfma_f32_16x16x32_bf16 v[108:111], v[152:155], v[194:197], v[108:111]
	v_mfma_f32_16x16x32_bf16 v[104:107], v[160:163], v[194:197], v[104:107]
	v_mfma_f32_16x16x32_bf16 v[92:95], v[152:155], v[202:205], v[92:95]
	v_mfma_f32_16x16x32_bf16 v[88:91], v[160:163], v[202:205], v[88:91]
	v_mfma_f32_16x16x32_bf16 v[76:79], v[152:155], v[210:213], v[76:79]
	v_mfma_f32_16x16x32_bf16 v[72:75], v[160:163], v[210:213], v[72:75]
	v_mfma_f32_16x16x32_bf16 v[116:119], v[164:167], v[180:183], v[116:119]
	v_mfma_f32_16x16x32_bf16 v[112:115], v[172:175], v[180:183], v[112:115]
	v_mfma_f32_16x16x32_bf16 v[100:103], v[164:167], v[188:191], v[100:103]
	v_mfma_f32_16x16x32_bf16 v[96:99], v[172:175], v[188:191], v[96:99]
	v_mfma_f32_16x16x32_bf16 v[84:87], v[164:167], v[198:201], v[84:87]
	v_mfma_f32_16x16x32_bf16 v[80:83], v[172:175], v[198:201], v[80:83]
	v_mfma_f32_16x16x32_bf16 v[68:71], v[164:167], v[206:209], v[68:71]
	v_mfma_f32_16x16x32_bf16 v[64:67], v[172:175], v[206:209], v[64:67]
	v_mfma_f32_16x16x32_bf16 v[116:119], v[168:171], v[184:187], v[116:119]
	v_mfma_f32_16x16x32_bf16 v[112:115], v[176:179], v[184:187], v[112:115]
	v_mfma_f32_16x16x32_bf16 v[100:103], v[168:171], v[194:197], v[100:103]
	v_mfma_f32_16x16x32_bf16 v[96:99], v[176:179], v[194:197], v[96:99]
	v_mfma_f32_16x16x32_bf16 v[84:87], v[168:171], v[202:205], v[84:87]
	v_mfma_f32_16x16x32_bf16 v[80:83], v[176:179], v[202:205], v[80:83]
	v_mfma_f32_16x16x32_bf16 v[68:71], v[168:171], v[210:213], v[68:71]
	v_mfma_f32_16x16x32_bf16 v[64:67], v[176:179], v[210:213], v[64:67]
	s_barrier
	s_setprio 0
	s_add_u32 s98, s24, s12
	s_addc_u32 s99, s25, s13
	s_mov_b32 m0, s41
	s_add_u32 s66, s24, 0x10000
	ds_read_b128 v[180:183], v145 offset:16384
	ds_read_b128 v[184:187], v145 offset:17408
	ds_read_b128 v[188:191], v145 offset:18432
	ds_read_b128 v[194:197], v145 offset:19456
	ds_read_b128 v[198:201], v145 offset:20480
	ds_read_b128 v[202:205], v145 offset:21504
	ds_read_b128 v[206:209], v145 offset:22528
	ds_read_b128 v[210:213], v145 offset:23552
	global_load_lds_dwordx4 v132, s[24:25]
	s_mov_b32 m0, s42
	s_addc_u32 s67, s25, 0
	global_load_lds_dwordx4 v128, s[24:25]
	s_mov_b32 m0, s43
	s_nop 0
	global_load_lds_dwordx4 v132, s[66:67]
	s_mov_b32 m0, s44
	s_nop 0
	global_load_lds_dwordx4 v128, s[66:67]
	s_waitcnt vmcnt(6)
	s_waitcnt lgkmcnt(0)
	s_setprio 1
	s_barrier
	v_mfma_f32_16x16x32_bf16 v[60:63], v[148:151], v[180:183], v[60:63]
	v_mfma_f32_16x16x32_bf16 v[56:59], v[156:159], v[180:183], v[56:59]
	v_mfma_f32_16x16x32_bf16 v[44:47], v[148:151], v[188:191], v[44:47]
	v_mfma_f32_16x16x32_bf16 v[40:43], v[156:159], v[188:191], v[40:43]
	v_mfma_f32_16x16x32_bf16 v[28:31], v[148:151], v[198:201], v[28:31]
	v_mfma_f32_16x16x32_bf16 v[24:27], v[156:159], v[198:201], v[24:27]
	v_mfma_f32_16x16x32_bf16 v[12:15], v[148:151], v[206:209], v[12:15]
	v_mfma_f32_16x16x32_bf16 v[8:11], v[156:159], v[206:209], v[8:11]
	v_mfma_f32_16x16x32_bf16 v[60:63], v[152:155], v[184:187], v[60:63]
	v_mfma_f32_16x16x32_bf16 v[56:59], v[160:163], v[184:187], v[56:59]
	v_mfma_f32_16x16x32_bf16 v[44:47], v[152:155], v[194:197], v[44:47]
	v_mfma_f32_16x16x32_bf16 v[40:43], v[160:163], v[194:197], v[40:43]
	v_mfma_f32_16x16x32_bf16 v[28:31], v[152:155], v[202:205], v[28:31]
	v_mfma_f32_16x16x32_bf16 v[24:27], v[160:163], v[202:205], v[24:27]
	v_mfma_f32_16x16x32_bf16 v[12:15], v[152:155], v[210:213], v[12:15]
	v_mfma_f32_16x16x32_bf16 v[8:11], v[160:163], v[210:213], v[8:11]
	v_mfma_f32_16x16x32_bf16 v[52:55], v[164:167], v[180:183], v[52:55]
	v_mfma_f32_16x16x32_bf16 v[48:51], v[172:175], v[180:183], v[48:51]
	v_mfma_f32_16x16x32_bf16 v[36:39], v[164:167], v[188:191], v[36:39]
	v_mfma_f32_16x16x32_bf16 v[32:35], v[172:175], v[188:191], v[32:35]
	v_mfma_f32_16x16x32_bf16 v[20:23], v[164:167], v[198:201], v[20:23]
	v_mfma_f32_16x16x32_bf16 v[16:19], v[172:175], v[198:201], v[16:19]
	v_mfma_f32_16x16x32_bf16 v[4:7], v[164:167], v[206:209], v[4:7]
	v_mfma_f32_16x16x32_bf16 v[0:3], v[172:175], v[206:209], v[0:3]
	v_mfma_f32_16x16x32_bf16 v[52:55], v[168:171], v[184:187], v[52:55]
	v_mfma_f32_16x16x32_bf16 v[48:51], v[176:179], v[184:187], v[48:51]
	v_mfma_f32_16x16x32_bf16 v[36:39], v[168:171], v[194:197], v[36:39]
	v_mfma_f32_16x16x32_bf16 v[32:35], v[176:179], v[194:197], v[32:35]
	v_mfma_f32_16x16x32_bf16 v[20:23], v[168:171], v[202:205], v[20:23]
	v_mfma_f32_16x16x32_bf16 v[16:19], v[176:179], v[202:205], v[16:19]
	v_mfma_f32_16x16x32_bf16 v[4:7], v[168:171], v[210:213], v[4:7]
	v_mfma_f32_16x16x32_bf16 v[0:3], v[176:179], v[210:213], v[0:3]
	s_barrier
; #define PG8_STAGE(bufoff, gbase, voff) do { _Pragma("unroll") for (int _i = 0; _i < 2; ++_i) \
;         __builtin_amdgcn_global_load_lds((const unsigned*)((const char*)(gbase) + (voff)[_i]), (LAS unsigned*)(lds + (bufoff) + ldsw + _i * 8192), 16, 0, ((voff) == voffA ? AUXA : 0)); } while (0)
; #define PG8_LDA(dst, b, h) do { _Pragma("unroll") for (int m = 0; m < 4; ++m) _Pragma("unroll") for (int k = 0; k < 2; ++k) dst[m][k] = *(const LAS bf16x8*)(lds + PG8_SA(b, h) + aoff + m * 2048 + k * 1024); } while (0)
; #define PG8_LDB(dst, b, h) do { _Pragma("unroll") for (int n = 0; n < 2; ++n) _Pragma("unroll") for (int k = 0; k < 2; ++k) dst[n][k] = *(const LAS bf16x8*)(lds + PG8_SB(b, h) + boff + n * 2048 + k * 1024); } while (0)
; #define PG8_MMA(ai, bj, At, Bt) do { __builtin_amdgcn_s_setprio(1); _Pragma("unroll") for (int m = 0; m < 4; ++m) _Pragma("unroll") for (int n = 0; n < 2; ++n) _Pragma("unroll") for (int k = 0; k < 2; ++k) \
;         acc[ai][bj][m][n] = __builtin_amdgcn_mfma_f32_16x16x32_bf16(Bt[n][k], At[m][k], acc[ai][bj][m][n], 0, 0, 0); __builtin_amdgcn_s_setprio(0); } while (0)
; #define PG8_WAIT_V(n) asm volatile("s_waitcnt vmcnt(" #n ")" ::: "memory")
; #define PG8_WAIT_L(n) asm volatile("s_waitcnt lgkmcnt(" #n ")" ::: "memory")
; #define PG8_BAR __builtin_amdgcn_s_barrier()
; #define PG8_SCHED __builtin_amdgcn_sched_barrier(0)
;     ...
;             PG8_LDB(B0, 1, 0); PG8_LDB(B1, 1, 1); PG8_SCHED; PG8_LDA(At, 1, 0); PG8_STAGE(PG8_SA(0, 1), a2 + hsA, voffA);
;             PG8_WAIT_V(8); PG8_WAIT_L(0); PG8_BAR; PG8_MMA(0, 0, At, B0); PG8_MMA(0, 1, At, B1); PG8_BAR; PG8_SCHED;
;             PG8_LDA(At, 1, 1); PG8_STAGE(PG8_SB(1, 0), b3, voffB); PG8_STAGE(PG8_SB(1, 1), b3 + hsB, voffB); PG8_STAGE(PG8_SA(1, 0), a3, voffA);
;             PG8_WAIT_V(8); PG8_WAIT_L(0); PG8_BAR; PG8_MMA(1, 0, At, B0); PG8_MMA(1, 1, At, B1); PG8_BAR; PG8_SCHED;
;         }
	s_mov_b32 m0, s3
	s_nop 0
	global_load_lds_dwordx4 v134, s[26:27]
	s_mov_b32 m0, s29
	s_nop 0
	global_load_lds_dwordx4 v130, s[26:27]
	s_setprio 0
	ds_read_b128 v[148:151], v146
	ds_read_b128 v[152:155], v146 offset:1024
	ds_read_b128 v[156:159], v146 offset:2048
	ds_read_b128 v[160:163], v146 offset:3072
	ds_read_b128 v[164:167], v147
	ds_read_b128 v[168:171], v147 offset:1024
	ds_read_b128 v[172:175], v147 offset:2048
	ds_read_b128 v[176:179], v147 offset:3072
	s_add_u32 s26, s26, 0x20000
	s_addc_u32 s27, s27, 0
	s_mov_b32 m0, s30
	ds_read_b128 v[180:183], v145 offset:32768
	ds_read_b128 v[184:187], v145 offset:33792
	ds_read_b128 v[188:191], v145 offset:34816
	ds_read_b128 v[194:197], v145 offset:35840
	ds_read_b128 v[198:201], v145 offset:36864
	ds_read_b128 v[202:205], v145 offset:37888
	ds_read_b128 v[206:209], v145 offset:38912
	ds_read_b128 v[210:213], v145 offset:39936
	global_load_lds_dwordx4 v134, s[26:27]
	s_mov_b32 m0, s31
	s_nop 0
	global_load_lds_dwordx4 v130, s[26:27]
	s_waitcnt vmcnt(8)
	s_waitcnt lgkmcnt(0)
	s_setprio 1
	s_barrier
	v_mfma_f32_16x16x32_bf16 v[124:127], v[148:151], v[180:183], v[124:127]
	v_mfma_f32_16x16x32_bf16 v[120:123], v[156:159], v[180:183], v[120:123]
	v_mfma_f32_16x16x32_bf16 v[108:111], v[148:151], v[188:191], v[108:111]
	v_mfma_f32_16x16x32_bf16 v[104:107], v[156:159], v[188:191], v[104:107]
	v_mfma_f32_16x16x32_bf16 v[92:95], v[148:151], v[198:201], v[92:95]
	v_mfma_f32_16x16x32_bf16 v[88:91], v[156:159], v[198:201], v[88:91]
	v_mfma_f32_16x16x32_bf16 v[76:79], v[148:151], v[206:209], v[76:79]
	v_mfma_f32_16x16x32_bf16 v[72:75], v[156:159], v[206:209], v[72:75]
	v_mfma_f32_16x16x32_bf16 v[124:127], v[152:155], v[184:187], v[124:127]
	v_mfma_f32_16x16x32_bf16 v[120:123], v[160:163], v[184:187], v[120:123]
	v_mfma_f32_16x16x32_bf16 v[108:111], v[152:155], v[194:197], v[108:111]
	v_mfma_f32_16x16x32_bf16 v[104:107], v[160:163], v[194:197], v[104:107]
	v_mfma_f32_16x16x32_bf16 v[92:95], v[152:155], v[202:205], v[92:95]
	v_mfma_f32_16x16x32_bf16 v[88:91], v[160:163], v[202:205], v[88:91]
	v_mfma_f32_16x16x32_bf16 v[76:79], v[152:155], v[210:213], v[76:79]
	v_mfma_f32_16x16x32_bf16 v[72:75], v[160:163], v[210:213], v[72:75]
	v_mfma_f32_16x16x32_bf16 v[116:119], v[164:167], v[180:183], v[116:119]
	v_mfma_f32_16x16x32_bf16 v[112:115], v[172:175], v[180:183], v[112:115]
	v_mfma_f32_16x16x32_bf16 v[100:103], v[164:167], v[188:191], v[100:103]
	v_mfma_f32_16x16x32_bf16 v[96:99], v[172:175], v[188:191], v[96:99]
	v_mfma_f32_16x16x32_bf16 v[84:87], v[164:167], v[198:201], v[84:87]
	v_mfma_f32_16x16x32_bf16 v[80:83], v[172:175], v[198:201], v[80:83]
	v_mfma_f32_16x16x32_bf16 v[68:71], v[164:167], v[206:209], v[68:71]
	v_mfma_f32_16x16x32_bf16 v[64:67], v[172:175], v[206:209], v[64:67]
	v_mfma_f32_16x16x32_bf16 v[116:119], v[168:171], v[184:187], v[116:119]
	v_mfma_f32_16x16x32_bf16 v[112:115], v[176:179], v[184:187], v[112:115]
	v_mfma_f32_16x16x32_bf16 v[100:103], v[168:171], v[194:197], v[100:103]
	v_mfma_f32_16x16x32_bf16 v[96:99], v[176:179], v[194:197], v[96:99]
	v_mfma_f32_16x16x32_bf16 v[84:87], v[168:171], v[202:205], v[84:87]
	v_mfma_f32_16x16x32_bf16 v[80:83], v[176:179], v[202:205], v[80:83]
	v_mfma_f32_16x16x32_bf16 v[68:71], v[168:171], v[210:213], v[68:71]
	v_mfma_f32_16x16x32_bf16 v[64:67], v[176:179], v[210:213], v[64:67]
	s_barrier
	s_setprio 0
	s_add_i32 s26, s45, s28
	s_mov_b32 m0, s26
	ds_read_b128 v[180:183], v145 offset:49152
	ds_read_b128 v[184:187], v145 offset:50176
	ds_read_b128 v[188:191], v145 offset:51200
	ds_read_b128 v[194:197], v145 offset:52224
	ds_read_b128 v[198:201], v145 offset:53248
	ds_read_b128 v[202:205], v145 offset:54272
	ds_read_b128 v[206:209], v145 offset:55296
	ds_read_b128 v[210:213], v145 offset:56320
	global_load_lds_dwordx4 v132, s[98:99]
	s_add_i32 m0, s26, 0x2000
	s_add_u32 s24, s24, 0x10080
	s_addc_u32 s25, s25, 0
	s_add_i32 s26, s46, s28
	global_load_lds_dwordx4 v128, s[98:99]
	s_mov_b32 m0, s26
	s_nop 0
	global_load_lds_dwordx4 v132, s[24:25]
	s_add_i32 m0, s26, 0x2000
	s_nop 0
	global_load_lds_dwordx4 v128, s[24:25]
	s_waitcnt vmcnt(6)
	s_waitcnt lgkmcnt(0)
	s_setprio 1
	s_barrier
	v_mfma_f32_16x16x32_bf16 v[60:63], v[148:151], v[180:183], v[60:63]
	v_mfma_f32_16x16x32_bf16 v[56:59], v[156:159], v[180:183], v[56:59]
	v_mfma_f32_16x16x32_bf16 v[44:47], v[148:151], v[188:191], v[44:47]
	v_mfma_f32_16x16x32_bf16 v[40:43], v[156:159], v[188:191], v[40:43]
	v_mfma_f32_16x16x32_bf16 v[28:31], v[148:151], v[198:201], v[28:31]
	v_mfma_f32_16x16x32_bf16 v[24:27], v[156:159], v[198:201], v[24:27]
	v_mfma_f32_16x16x32_bf16 v[12:15], v[148:151], v[206:209], v[12:15]
	v_mfma_f32_16x16x32_bf16 v[8:11], v[156:159], v[206:209], v[8:11]
	v_mfma_f32_16x16x32_bf16 v[60:63], v[152:155], v[184:187], v[60:63]
	v_mfma_f32_16x16x32_bf16 v[56:59], v[160:163], v[184:187], v[56:59]
	v_mfma_f32_16x16x32_bf16 v[44:47], v[152:155], v[194:197], v[44:47]
	v_mfma_f32_16x16x32_bf16 v[40:43], v[160:163], v[194:197], v[40:43]
	v_mfma_f32_16x16x32_bf16 v[28:31], v[152:155], v[202:205], v[28:31]
	v_mfma_f32_16x16x32_bf16 v[24:27], v[160:163], v[202:205], v[24:27]
	v_mfma_f32_16x16x32_bf16 v[12:15], v[152:155], v[210:213], v[12:15]
	v_mfma_f32_16x16x32_bf16 v[8:11], v[160:163], v[210:213], v[8:11]
	v_mfma_f32_16x16x32_bf16 v[52:55], v[164:167], v[180:183], v[52:55]
	v_mfma_f32_16x16x32_bf16 v[48:51], v[172:175], v[180:183], v[48:51]
	v_mfma_f32_16x16x32_bf16 v[36:39], v[164:167], v[188:191], v[36:39]
	v_mfma_f32_16x16x32_bf16 v[32:35], v[172:175], v[188:191], v[32:35]
	v_mfma_f32_16x16x32_bf16 v[20:23], v[164:167], v[198:201], v[20:23]
	v_mfma_f32_16x16x32_bf16 v[16:19], v[172:175], v[198:201], v[16:19]
	v_mfma_f32_16x16x32_bf16 v[4:7], v[164:167], v[206:209], v[4:7]
	v_mfma_f32_16x16x32_bf16 v[0:3], v[172:175], v[206:209], v[0:3]
	v_mfma_f32_16x16x32_bf16 v[52:55], v[168:171], v[184:187], v[52:55]
	v_mfma_f32_16x16x32_bf16 v[48:51], v[176:179], v[184:187], v[48:51]
	v_mfma_f32_16x16x32_bf16 v[36:39], v[168:171], v[194:197], v[36:39]
	v_mfma_f32_16x16x32_bf16 v[32:35], v[176:179], v[194:197], v[32:35]
	v_mfma_f32_16x16x32_bf16 v[20:23], v[168:171], v[202:205], v[20:23]
	v_mfma_f32_16x16x32_bf16 v[16:19], v[176:179], v[202:205], v[16:19]
	v_mfma_f32_16x16x32_bf16 v[4:7], v[168:171], v[210:213], v[4:7]
	v_mfma_f32_16x16x32_bf16 v[0:3], v[176:179], v[210:213], v[0:3]
	s_barrier
	s_setprio 0
	s_add_u32 s22, s22, 0x100
	s_addc_u32 s23, s23, 0
	s_add_u32 s54, s54, 0x100
	s_addc_u32 s55, s55, 0
	s_cmp_ge_i32 s56, s35
	s_mov_b32 s24, s56
	s_cbranch_scc0 .LBB0_648

; #define PG8_STAGE(bufoff, gbase, voff) do { _Pragma("unroll") for (int _i = 0; _i < 2; ++_i) \
;         __builtin_amdgcn_global_load_lds((const unsigned*)((const char*)(gbase) + (voff)[_i]), (LAS unsigned*)(lds + (bufoff) + ldsw + _i * 8192), 16, 0, ((voff) == voffA ? AUXA : 0)); } while (0)
; #define PG8_LDA(dst, b, h) do { _Pragma("unroll") for (int m = 0; m < 4; ++m) _Pragma("unroll") for (int k = 0; k < 2; ++k) dst[m][k] = *(const LAS bf16x8*)(lds + PG8_SA(b, h) + aoff + m * 2048 + k * 1024); } while (0)
; #define PG8_LDB(dst, b, h) do { _Pragma("unroll") for (int n = 0; n < 2; ++n) _Pragma("unroll") for (int k = 0; k < 2; ++k) dst[n][k] = *(const LAS bf16x8*)(lds + PG8_SB(b, h) + boff + n * 2048 + k * 1024); } while (0)
; #define PG8_MMA(ai, bj, At, Bt) do { __builtin_amdgcn_s_setprio(1); _Pragma("unroll") for (int m = 0; m < 4; ++m) _Pragma("unroll") for (int n = 0; n < 2; ++n) _Pragma("unroll") for (int k = 0; k < 2; ++k) \
;         acc[ai][bj][m][n] = __builtin_amdgcn_mfma_f32_16x16x32_bf16(Bt[n][k], At[m][k], acc[ai][bj][m][n], 0, 0, 0); __builtin_amdgcn_s_setprio(0); } while (0)
; #define PG8_WAIT_V(n) asm volatile("s_waitcnt vmcnt(" #n ")" ::: "memory")
; #define PG8_WAIT_L(n) asm volatile("s_waitcnt lgkmcnt(" #n ")" ::: "memory")
; #define PG8_BAR __builtin_amdgcn_s_barrier()
; #define PG8_SCHED __builtin_amdgcn_sched_barrier(0)
;     ...
;         for (int t = 0; t < nt; t += 2) {
;             const bool last = (t == nt - 2);
;             const char* a1 = cA + (size_t)(t + 1) * kstep;
;             const char* a2 = last ? nA : cA + (size_t)(t + 2) * kstep; const char* b2 = last ? nB : cB + (size_t)(t + 2) * kstep;
;             const char* a3 = a2 + kstep; const char* b3 = b2 + kstep;
;             PG8_LDB(B0, 0, 0); PG8_LDB(B1, 0, 1); PG8_SCHED; PG8_LDA(At, 0, 0); PG8_STAGE(PG8_SA(1, 1), a1 + hsA, voffA);
;             if (Epi::NPRE != 0 && last) { E.pre(sv, cur, wr, fr); PG8_WAIT_V(16); } else { PG8_WAIT_V(8); }
;             PG8_WAIT_L(0); PG8_BAR; PG8_MMA(0, 0, At, B0); PG8_MMA(0, 1, At, B1); PG8_BAR; PG8_SCHED;
;             PG8_LDA(At, 0, 1); PG8_STAGE(PG8_SB(0, 0), b2, voffB); PG8_STAGE(PG8_SB(0, 1), b2 + hsB, voffB); PG8_STAGE(PG8_SA(0, 0), a2, voffA);
;             if (Epi::NPRE != 0 && last) { PG8_WAIT_V(16); } else { PG8_WAIT_V(8); }
;             PG8_WAIT_L(0); PG8_BAR; PG8_MMA(1, 0, At, B0); PG8_MMA(1, 1, At, B1); PG8_BAR; PG8_SCHED;
.LBB0_887:
	s_add_u32 s98, s24, 0xfffe0000
	s_mov_b32 m0, s40
	s_addc_u32 s99, s25, -1
	global_load_lds_dwordx4 v134, s[98:99]
	s_mov_b32 m0, s41
	s_nop 0
	global_load_lds_dwordx4 v130, s[98:99]
	ds_read_b128 v[150:153], v146
	ds_read_b128 v[154:157], v146 offset:1024
	ds_read_b128 v[158:161], v146 offset:2048
	ds_read_b128 v[162:165], v146 offset:3072
	ds_read_b128 v[166:169], v147
	ds_read_b128 v[170:173], v147 offset:1024
	ds_read_b128 v[174:177], v147 offset:2048
	ds_read_b128 v[178:181], v147 offset:3072
	s_add_i32 s53, s26, 2
	s_add_u32 s27, s24, 0xfffe0080
	s_addc_u32 s28, s25, -1
	s_cmp_eq_u32 s42, s26
	s_cselect_b32 s26, s50, s51
	s_cselect_b32 s29, s23, s28
	s_cselect_b32 s28, s48, s27
	s_cselect_b32 s27, s49, s52
	s_add_i32 m0, s3, 0xc000
	ds_read_b128 v[182:185], v148
	ds_read_b128 v[186:189], v148 offset:1024
	ds_read_b128 v[194:197], v148 offset:2048
	ds_read_b128 v[198:201], v148 offset:3072
	ds_read_b128 v[202:205], v148 offset:4096
	ds_read_b128 v[206:209], v148 offset:5120
	ds_read_b128 v[210:213], v148 offset:6144
	ds_read_b128 v[214:217], v148 offset:7168
	global_load_lds_dwordx4 v138, s[24:25]
	s_add_i32 m0, s3, 0xe000
	s_nop 0
	global_load_lds_dwordx4 v140, s[24:25]
	s_waitcnt vmcnt(8)
	s_waitcnt lgkmcnt(0)
	s_setprio 1
	s_barrier
	v_mfma_f32_16x16x32_bf16 v[124:127], v[150:153], v[182:185], v[124:127]
	v_mfma_f32_16x16x32_bf16 v[120:123], v[158:161], v[182:185], v[120:123]
	v_mfma_f32_16x16x32_bf16 v[108:111], v[150:153], v[194:197], v[108:111]
	v_mfma_f32_16x16x32_bf16 v[104:107], v[158:161], v[194:197], v[104:107]
	v_mfma_f32_16x16x32_bf16 v[92:95], v[150:153], v[202:205], v[92:95]
	v_mfma_f32_16x16x32_bf16 v[88:91], v[158:161], v[202:205], v[88:91]
	v_mfma_f32_16x16x32_bf16 v[76:79], v[150:153], v[210:213], v[76:79]
	v_mfma_f32_16x16x32_bf16 v[72:75], v[158:161], v[210:213], v[72:75]
	v_mfma_f32_16x16x32_bf16 v[124:127], v[154:157], v[186:189], v[124:127]
	v_mfma_f32_16x16x32_bf16 v[120:123], v[162:165], v[186:189], v[120:123]
	v_mfma_f32_16x16x32_bf16 v[108:111], v[154:157], v[198:201], v[108:111]
	v_mfma_f32_16x16x32_bf16 v[104:107], v[162:165], v[198:201], v[104:107]
	v_mfma_f32_16x16x32_bf16 v[92:95], v[154:157], v[206:209], v[92:95]
	v_mfma_f32_16x16x32_bf16 v[88:91], v[162:165], v[206:209], v[88:91]
	v_mfma_f32_16x16x32_bf16 v[76:79], v[154:157], v[214:217], v[76:79]
	v_mfma_f32_16x16x32_bf16 v[72:75], v[162:165], v[214:217], v[72:75]
	v_mfma_f32_16x16x32_bf16 v[116:119], v[166:169], v[182:185], v[116:119]
	v_mfma_f32_16x16x32_bf16 v[112:115], v[174:177], v[182:185], v[112:115]
	v_mfma_f32_16x16x32_bf16 v[100:103], v[166:169], v[194:197], v[100:103]
	v_mfma_f32_16x16x32_bf16 v[96:99], v[174:177], v[194:197], v[96:99]
	v_mfma_f32_16x16x32_bf16 v[84:87], v[166:169], v[202:205], v[84:87]
	v_mfma_f32_16x16x32_bf16 v[80:83], v[174:177], v[202:205], v[80:83]
	v_mfma_f32_16x16x32_bf16 v[68:71], v[166:169], v[210:213], v[68:71]
	v_mfma_f32_16x16x32_bf16 v[64:67], v[174:177], v[210:213], v[64:67]
	v_mfma_f32_16x16x32_bf16 v[116:119], v[170:173], v[186:189], v[116:119]
	v_mfma_f32_16x16x32_bf16 v[112:115], v[178:181], v[186:189], v[112:115]
	v_mfma_f32_16x16x32_bf16 v[100:103], v[170:173], v[198:201], v[100:103]
	v_mfma_f32_16x16x32_bf16 v[96:99], v[178:181], v[198:201], v[96:99]
	v_mfma_f32_16x16x32_bf16 v[84:87], v[170:173], v[206:209], v[84:87]
	v_mfma_f32_16x16x32_bf16 v[80:83], v[178:181], v[206:209], v[80:83]
	v_mfma_f32_16x16x32_bf16 v[68:71], v[170:173], v[214:217], v[68:71]
	v_mfma_f32_16x16x32_bf16 v[64:67], v[178:181], v[214:217], v[64:67]
	s_barrier
	s_setprio 0
	s_add_u32 s98, s26, s12
	s_addc_u32 s99, s27, s13
	s_add_i32 s54, s43, s34
	s_mov_b32 m0, s54
	ds_read_b128 v[182:185], v148 offset:16384
	ds_read_b128 v[186:189], v148 offset:17408
	ds_read_b128 v[194:197], v148 offset:18432
	ds_read_b128 v[198:201], v148 offset:19456
	ds_read_b128 v[202:205], v148 offset:20480
	ds_read_b128 v[206:209], v148 offset:21504
	ds_read_b128 v[210:213], v148 offset:22528
	ds_read_b128 v[214:217], v148 offset:23552
	global_load_lds_dwordx4 v132, s[26:27]
	s_add_i32 m0, s54, 0x2000
	s_add_u32 s54, s26, 0x20000
	s_addc_u32 s55, s27, 0
	s_add_i32 s56, s44, s34
	global_load_lds_dwordx4 v128, s[26:27]
	s_mov_b32 m0, s56
	s_nop 0
	global_load_lds_dwordx4 v132, s[54:55]
	s_add_i32 m0, s56, 0x2000
	s_nop 0
	global_load_lds_dwordx4 v128, s[54:55]
	s_waitcnt vmcnt(6)
	s_waitcnt lgkmcnt(0)
	s_setprio 1
	s_barrier
	v_mfma_f32_16x16x32_bf16 v[60:63], v[150:153], v[182:185], v[60:63]
	v_mfma_f32_16x16x32_bf16 v[56:59], v[158:161], v[182:185], v[56:59]
	v_mfma_f32_16x16x32_bf16 v[44:47], v[150:153], v[194:197], v[44:47]
	v_mfma_f32_16x16x32_bf16 v[40:43], v[158:161], v[194:197], v[40:43]
	v_mfma_f32_16x16x32_bf16 v[28:31], v[150:153], v[202:205], v[28:31]
	v_mfma_f32_16x16x32_bf16 v[24:27], v[158:161], v[202:205], v[24:27]
	v_mfma_f32_16x16x32_bf16 v[12:15], v[150:153], v[210:213], v[12:15]
	v_mfma_f32_16x16x32_bf16 v[8:11], v[158:161], v[210:213], v[8:11]
	v_mfma_f32_16x16x32_bf16 v[60:63], v[154:157], v[186:189], v[60:63]
	v_mfma_f32_16x16x32_bf16 v[56:59], v[162:165], v[186:189], v[56:59]
	v_mfma_f32_16x16x32_bf16 v[44:47], v[154:157], v[198:201], v[44:47]
	v_mfma_f32_16x16x32_bf16 v[40:43], v[162:165], v[198:201], v[40:43]
	v_mfma_f32_16x16x32_bf16 v[28:31], v[154:157], v[206:209], v[28:31]
	v_mfma_f32_16x16x32_bf16 v[24:27], v[162:165], v[206:209], v[24:27]
	v_mfma_f32_16x16x32_bf16 v[12:15], v[154:157], v[214:217], v[12:15]
	v_mfma_f32_16x16x32_bf16 v[8:11], v[162:165], v[214:217], v[8:11]
	v_mfma_f32_16x16x32_bf16 v[52:55], v[166:169], v[182:185], v[52:55]
	v_mfma_f32_16x16x32_bf16 v[48:51], v[174:177], v[182:185], v[48:51]
	v_mfma_f32_16x16x32_bf16 v[36:39], v[166:169], v[194:197], v[36:39]
	v_mfma_f32_16x16x32_bf16 v[32:35], v[174:177], v[194:197], v[32:35]
	v_mfma_f32_16x16x32_bf16 v[20:23], v[166:169], v[202:205], v[20:23]
	v_mfma_f32_16x16x32_bf16 v[16:19], v[174:177], v[202:205], v[16:19]
	v_mfma_f32_16x16x32_bf16 v[4:7], v[166:169], v[210:213], v[4:7]
	v_mfma_f32_16x16x32_bf16 v[0:3], v[174:177], v[210:213], v[0:3]
	v_mfma_f32_16x16x32_bf16 v[52:55], v[170:173], v[186:189], v[52:55]
	v_mfma_f32_16x16x32_bf16 v[48:51], v[178:181], v[186:189], v[48:51]
	v_mfma_f32_16x16x32_bf16 v[36:39], v[170:173], v[198:201], v[36:39]
	v_mfma_f32_16x16x32_bf16 v[32:35], v[178:181], v[198:201], v[32:35]
	v_mfma_f32_16x16x32_bf16 v[20:23], v[170:173], v[206:209], v[20:23]
	v_mfma_f32_16x16x32_bf16 v[16:19], v[178:181], v[206:209], v[16:19]
	v_mfma_f32_16x16x32_bf16 v[4:7], v[170:173], v[214:217], v[4:7]
	v_mfma_f32_16x16x32_bf16 v[0:3], v[178:181], v[214:217], v[0:3]
	s_barrier
; #define PG8_STAGE(bufoff, gbase, voff) do { _Pragma("unroll") for (int _i = 0; _i < 2; ++_i) \
;         __builtin_amdgcn_global_load_lds((const unsigned*)((const char*)(gbase) + (voff)[_i]), (LAS unsigned*)(lds + (bufoff) + ldsw + _i * 8192), 16, 0, ((voff) == voffA ? AUXA : 0)); } while (0)
; #define PG8_LDA(dst, b, h) do { _Pragma("unroll") for (int m = 0; m < 4; ++m) _Pragma("unroll") for (int k = 0; k < 2; ++k) dst[m][k] = *(const LAS bf16x8*)(lds + PG8_SA(b, h) + aoff + m * 2048 + k * 1024); } while (0)
; #define PG8_LDB(dst, b, h) do { _Pragma("unroll") for (int n = 0; n < 2; ++n) _Pragma("unroll") for (int k = 0; k < 2; ++k) dst[n][k] = *(const LAS bf16x8*)(lds + PG8_SB(b, h) + boff + n * 2048 + k * 1024); } while (0)
; #define PG8_MMA(ai, bj, At, Bt) do { __builtin_amdgcn_s_setprio(1); _Pragma("unroll") for (int m = 0; m < 4; ++m) _Pragma("unroll") for (int n = 0; n < 2; ++n) _Pragma("unroll") for (int k = 0; k < 2; ++k) \
;         acc[ai][bj][m][n] = __builtin_amdgcn_mfma_f32_16x16x32_bf16(Bt[n][k], At[m][k], acc[ai][bj][m][n], 0, 0, 0); __builtin_amdgcn_s_setprio(0); } while (0)
; #define PG8_WAIT_V(n) asm volatile("s_waitcnt vmcnt(" #n ")" ::: "memory")
; #define PG8_WAIT_L(n) asm volatile("s_waitcnt lgkmcnt(" #n ")" ::: "memory")
; #define PG8_BAR __builtin_amdgcn_s_barrier()
; #define PG8_SCHED __builtin_amdgcn_sched_barrier(0)
;     ...
;             PG8_LDB(B0, 1, 0); PG8_LDB(B1, 1, 1); PG8_SCHED; PG8_LDA(At, 1, 0); PG8_STAGE(PG8_SA(0, 1), a2 + hsA, voffA);
;             PG8_WAIT_V(8); PG8_WAIT_L(0); PG8_BAR; PG8_MMA(0, 0, At, B0); PG8_MMA(0, 1, At, B1); PG8_BAR; PG8_SCHED;
;             PG8_LDA(At, 1, 1); PG8_STAGE(PG8_SB(1, 0), b3, voffB); PG8_STAGE(PG8_SB(1, 1), b3 + hsB, voffB); PG8_STAGE(PG8_SA(1, 0), a3, voffA);
;             PG8_WAIT_V(8); PG8_WAIT_L(0); PG8_BAR; PG8_MMA(1, 0, At, B0); PG8_MMA(1, 1, At, B1); PG8_BAR; PG8_SCHED;
;         }
	s_mov_b32 m0, s3
	s_nop 0
	global_load_lds_dwordx4 v134, s[28:29]
	s_mov_b32 m0, s35
	s_nop 0
	global_load_lds_dwordx4 v130, s[28:29]
	s_setprio 0
	s_add_i32 s54, 0, 0x18000
	v_add_u32_e32 v149, s54, v143
	s_add_i32 s55, 0, 0x1c000
	ds_read_b128 v[150:153], v149
	ds_read_b128 v[154:157], v149 offset:1024
	ds_read_b128 v[158:161], v149 offset:2048
	ds_read_b128 v[162:165], v149 offset:3072
	v_add_u32_e32 v149, s55, v143
	ds_read_b128 v[166:169], v149
	ds_read_b128 v[170:173], v149 offset:1024
	ds_read_b128 v[174:177], v149 offset:2048
	ds_read_b128 v[178:181], v149 offset:3072
	s_add_u32 s28, s28, 0x20000
	s_addc_u32 s29, s29, 0
	s_mov_b32 m0, s36
	ds_read_b128 v[182:185], v148 offset:32768
	ds_read_b128 v[186:189], v148 offset:33792
	ds_read_b128 v[194:197], v148 offset:34816
	ds_read_b128 v[198:201], v148 offset:35840
	ds_read_b128 v[202:205], v148 offset:36864
	ds_read_b128 v[206:209], v148 offset:37888
	ds_read_b128 v[210:213], v148 offset:38912
	ds_read_b128 v[214:217], v148 offset:39936
	global_load_lds_dwordx4 v134, s[28:29]
	s_mov_b32 m0, s37
	s_nop 0
	global_load_lds_dwordx4 v130, s[28:29]
	s_waitcnt vmcnt(8)
	s_waitcnt lgkmcnt(0)
	s_setprio 1
	s_barrier
	v_mfma_f32_16x16x32_bf16 v[124:127], v[150:153], v[182:185], v[124:127]
	v_mfma_f32_16x16x32_bf16 v[120:123], v[158:161], v[182:185], v[120:123]
	v_mfma_f32_16x16x32_bf16 v[108:111], v[150:153], v[194:197], v[108:111]
	v_mfma_f32_16x16x32_bf16 v[104:107], v[158:161], v[194:197], v[104:107]
	v_mfma_f32_16x16x32_bf16 v[92:95], v[150:153], v[202:205], v[92:95]
	v_mfma_f32_16x16x32_bf16 v[88:91], v[158:161], v[202:205], v[88:91]
	v_mfma_f32_16x16x32_bf16 v[76:79], v[150:153], v[210:213], v[76:79]
	v_mfma_f32_16x16x32_bf16 v[72:75], v[158:161], v[210:213], v[72:75]
	v_mfma_f32_16x16x32_bf16 v[124:127], v[154:157], v[186:189], v[124:127]
	v_mfma_f32_16x16x32_bf16 v[120:123], v[162:165], v[186:189], v[120:123]
	v_mfma_f32_16x16x32_bf16 v[108:111], v[154:157], v[198:201], v[108:111]
	v_mfma_f32_16x16x32_bf16 v[104:107], v[162:165], v[198:201], v[104:107]
	v_mfma_f32_16x16x32_bf16 v[92:95], v[154:157], v[206:209], v[92:95]
	v_mfma_f32_16x16x32_bf16 v[88:91], v[162:165], v[206:209], v[88:91]
	v_mfma_f32_16x16x32_bf16 v[76:79], v[154:157], v[214:217], v[76:79]
	v_mfma_f32_16x16x32_bf16 v[72:75], v[162:165], v[214:217], v[72:75]
	v_mfma_f32_16x16x32_bf16 v[116:119], v[166:169], v[182:185], v[116:119]
	v_mfma_f32_16x16x32_bf16 v[112:115], v[174:177], v[182:185], v[112:115]
	v_mfma_f32_16x16x32_bf16 v[100:103], v[166:169], v[194:197], v[100:103]
	v_mfma_f32_16x16x32_bf16 v[96:99], v[174:177], v[194:197], v[96:99]
	v_mfma_f32_16x16x32_bf16 v[84:87], v[166:169], v[202:205], v[84:87]
	v_mfma_f32_16x16x32_bf16 v[80:83], v[174:177], v[202:205], v[80:83]
	v_mfma_f32_16x16x32_bf16 v[68:71], v[166:169], v[210:213], v[68:71]
	v_mfma_f32_16x16x32_bf16 v[64:67], v[174:177], v[210:213], v[64:67]
	v_mfma_f32_16x16x32_bf16 v[116:119], v[170:173], v[186:189], v[116:119]
	v_mfma_f32_16x16x32_bf16 v[112:115], v[178:181], v[186:189], v[112:115]
	v_mfma_f32_16x16x32_bf16 v[100:103], v[170:173], v[198:201], v[100:103]
	v_mfma_f32_16x16x32_bf16 v[96:99], v[178:181], v[198:201], v[96:99]
	v_mfma_f32_16x16x32_bf16 v[84:87], v[170:173], v[206:209], v[84:87]
	v_mfma_f32_16x16x32_bf16 v[80:83], v[178:181], v[206:209], v[80:83]
	v_mfma_f32_16x16x32_bf16 v[68:71], v[170:173], v[214:217], v[68:71]
	v_mfma_f32_16x16x32_bf16 v[64:67], v[178:181], v[214:217], v[64:67]
	s_barrier
	s_setprio 0
	s_add_i32 s28, s54, s34
	s_mov_b32 m0, s28
	ds_read_b128 v[182:185], v148 offset:49152
	ds_read_b128 v[186:189], v148 offset:50176
	ds_read_b128 v[194:197], v148 offset:51200
	ds_read_b128 v[198:201], v148 offset:52224
	ds_read_b128 v[202:205], v148 offset:53248
	ds_read_b128 v[206:209], v148 offset:54272
	ds_read_b128 v[210:213], v148 offset:55296
	ds_read_b128 v[214:217], v148 offset:56320
	global_load_lds_dwordx4 v132, s[98:99]
	s_add_i32 m0, s28, 0x2000
	s_add_u32 s26, s26, 0x20080
	s_addc_u32 s27, s27, 0
	s_add_i32 s28, s55, s34
	global_load_lds_dwordx4 v128, s[98:99]
	s_mov_b32 m0, s28
	s_nop 0
	global_load_lds_dwordx4 v132, s[26:27]
	s_add_i32 m0, s28, 0x2000
	s_nop 0
	global_load_lds_dwordx4 v128, s[26:27]
	s_waitcnt vmcnt(6)
	s_waitcnt lgkmcnt(0)
	s_setprio 1
	s_barrier
	v_mfma_f32_16x16x32_bf16 v[60:63], v[150:153], v[182:185], v[60:63]
	v_mfma_f32_16x16x32_bf16 v[56:59], v[158:161], v[182:185], v[56:59]
	v_mfma_f32_16x16x32_bf16 v[44:47], v[150:153], v[194:197], v[44:47]
	v_mfma_f32_16x16x32_bf16 v[40:43], v[158:161], v[194:197], v[40:43]
	v_mfma_f32_16x16x32_bf16 v[28:31], v[150:153], v[202:205], v[28:31]
	v_mfma_f32_16x16x32_bf16 v[24:27], v[158:161], v[202:205], v[24:27]
	v_mfma_f32_16x16x32_bf16 v[12:15], v[150:153], v[210:213], v[12:15]
	v_mfma_f32_16x16x32_bf16 v[8:11], v[158:161], v[210:213], v[8:11]
	v_mfma_f32_16x16x32_bf16 v[60:63], v[154:157], v[186:189], v[60:63]
	v_mfma_f32_16x16x32_bf16 v[56:59], v[162:165], v[186:189], v[56:59]
	v_mfma_f32_16x16x32_bf16 v[44:47], v[154:157], v[198:201], v[44:47]
	v_mfma_f32_16x16x32_bf16 v[40:43], v[162:165], v[198:201], v[40:43]
	v_mfma_f32_16x16x32_bf16 v[28:31], v[154:157], v[206:209], v[28:31]
	v_mfma_f32_16x16x32_bf16 v[24:27], v[162:165], v[206:209], v[24:27]
	v_mfma_f32_16x16x32_bf16 v[12:15], v[154:157], v[214:217], v[12:15]
	v_mfma_f32_16x16x32_bf16 v[8:11], v[162:165], v[214:217], v[8:11]
	v_mfma_f32_16x16x32_bf16 v[52:55], v[166:169], v[182:185], v[52:55]
	v_mfma_f32_16x16x32_bf16 v[48:51], v[174:177], v[182:185], v[48:51]
	v_mfma_f32_16x16x32_bf16 v[36:39], v[166:169], v[194:197], v[36:39]
	v_mfma_f32_16x16x32_bf16 v[32:35], v[174:177], v[194:197], v[32:35]
	v_mfma_f32_16x16x32_bf16 v[20:23], v[166:169], v[202:205], v[20:23]
	v_mfma_f32_16x16x32_bf16 v[16:19], v[174:177], v[202:205], v[16:19]
	v_mfma_f32_16x16x32_bf16 v[4:7], v[166:169], v[210:213], v[4:7]
	v_mfma_f32_16x16x32_bf16 v[0:3], v[174:177], v[210:213], v[0:3]
	v_mfma_f32_16x16x32_bf16 v[52:55], v[170:173], v[186:189], v[52:55]
	v_mfma_f32_16x16x32_bf16 v[48:51], v[178:181], v[186:189], v[48:51]
	v_mfma_f32_16x16x32_bf16 v[36:39], v[170:173], v[198:201], v[36:39]
	v_mfma_f32_16x16x32_bf16 v[32:35], v[178:181], v[198:201], v[32:35]
	v_mfma_f32_16x16x32_bf16 v[20:23], v[170:173], v[206:209], v[20:23]
	v_mfma_f32_16x16x32_bf16 v[16:19], v[178:181], v[206:209], v[16:19]
	v_mfma_f32_16x16x32_bf16 v[4:7], v[170:173], v[214:217], v[4:7]
	v_mfma_f32_16x16x32_bf16 v[0:3], v[178:181], v[214:217], v[0:3]
	s_barrier
	s_setprio 0
	s_add_u32 s24, s24, 0x100
	s_addc_u32 s25, s25, 0
	s_add_u32 s51, s51, 0x100
	s_addc_u32 s52, s52, 0
	s_cmp_ge_i32 s53, s39
	s_mov_b32 s26, s53
	s_cbranch_scc0 .LBB0_887

; #define PG8_STAGE(bufoff, gbase, voff) do { _Pragma("unroll") for (int _i = 0; _i < 2; ++_i) \
;         __builtin_amdgcn_global_load_lds((const unsigned*)((const char*)(gbase) + (voff)[_i]), (LAS unsigned*)(lds + (bufoff) + ldsw + _i * 8192), 16, 0, ((voff) == voffA ? AUXA : 0)); } while (0)
; #define PG8_LDA(dst, b, h) do { _Pragma("unroll") for (int m = 0; m < 4; ++m) _Pragma("unroll") for (int k = 0; k < 2; ++k) dst[m][k] = *(const LAS bf16x8*)(lds + PG8_SA(b, h) + aoff + m * 2048 + k * 1024); } while (0)
; #define PG8_LDB(dst, b, h) do { _Pragma("unroll") for (int n = 0; n < 2; ++n) _Pragma("unroll") for (int k = 0; k < 2; ++k) dst[n][k] = *(const LAS bf16x8*)(lds + PG8_SB(b, h) + boff + n * 2048 + k * 1024); } while (0)
; #define PG8_MMA(ai, bj, At, Bt) do { __builtin_amdgcn_s_setprio(1); _Pragma("unroll") for (int m = 0; m < 4; ++m) _Pragma("unroll") for (int n = 0; n < 2; ++n) _Pragma("unroll") for (int k = 0; k < 2; ++k) \
;         acc[ai][bj][m][n] = __builtin_amdgcn_mfma_f32_16x16x32_bf16(Bt[n][k], At[m][k], acc[ai][bj][m][n], 0, 0, 0); __builtin_amdgcn_s_setprio(0); } while (0)
; #define PG8_WAIT_V(n) asm volatile("s_waitcnt vmcnt(" #n ")" ::: "memory")
; #define PG8_WAIT_L(n) asm volatile("s_waitcnt lgkmcnt(" #n ")" ::: "memory")
; #define PG8_BAR __builtin_amdgcn_s_barrier()
; #define PG8_SCHED __builtin_amdgcn_sched_barrier(0)
;     ...
;         for (int t = 0; t < nt; t += 2) {
;             const bool last = (t == nt - 2);
;             const char* a1 = cA + (size_t)(t + 1) * kstep;
;             const char* a2 = last ? nA : cA + (size_t)(t + 2) * kstep; const char* b2 = last ? nB : cB + (size_t)(t + 2) * kstep;
;             const char* a3 = a2 + kstep; const char* b3 = b2 + kstep;
;             PG8_LDB(B0, 0, 0); PG8_LDB(B1, 0, 1); PG8_SCHED; PG8_LDA(At, 0, 0); PG8_STAGE(PG8_SA(1, 1), a1 + hsA, voffA);
;             if (Epi::NPRE != 0 && last) { E.pre(sv, cur, wr, fr); PG8_WAIT_V(16); } else { PG8_WAIT_V(8); }
;             PG8_WAIT_L(0); PG8_BAR; PG8_MMA(0, 0, At, B0); PG8_MMA(0, 1, At, B1); PG8_BAR; PG8_SCHED;
;             PG8_LDA(At, 0, 1); PG8_STAGE(PG8_SB(0, 0), b2, voffB); PG8_STAGE(PG8_SB(0, 1), b2 + hsB, voffB); PG8_STAGE(PG8_SA(0, 0), a2, voffA);
;             if (Epi::NPRE != 0 && last) { PG8_WAIT_V(16); } else { PG8_WAIT_V(8); }
;             PG8_WAIT_L(0); PG8_BAR; PG8_MMA(1, 0, At, B0); PG8_MMA(1, 1, At, B1); PG8_BAR; PG8_SCHED;
.LBB0_959:
	s_add_u32 s98, s28, 0xfffc0000
	s_mov_b32 m0, s40
	s_addc_u32 s99, s29, -1
	global_load_lds_dwordx4 v170, s[98:99]
	s_mov_b32 m0, s41
	s_nop 0
	global_load_lds_dwordx4 v166, s[98:99]
	ds_read_b128 v[88:91], v196
	ds_read_b128 v[92:95], v196 offset:1024
	ds_read_b128 v[104:107], v196 offset:2048
	ds_read_b128 v[108:111], v196 offset:3072
	ds_read_b128 v[144:147], v197
	ds_read_b128 v[148:151], v197 offset:1024
	ds_read_b128 v[152:155], v197 offset:2048
	ds_read_b128 v[156:159], v197 offset:3072
	s_add_i32 s51, s30, 2
	s_add_u32 s31, s28, 0xfffc0080
	s_addc_u32 s34, s29, -1
	s_cmp_eq_u32 s42, s30
	s_cselect_b32 s30, s48, s49
	s_cselect_b32 s35, s19, s34
	s_cselect_b32 s34, s21, s31
	s_cselect_b32 s31, s47, s50
	s_add_i32 m0, s5, 0xc000
	ds_read_b128 v[160:163], v198
	ds_read_b128 v[180:183], v198 offset:1024
	ds_read_b128 v[184:187], v198 offset:2048
	ds_read_b128 v[188:191], v198 offset:3072
	ds_read_b128 v[200:203], v198 offset:4096
	ds_read_b128 v[204:207], v198 offset:5120
	ds_read_b128 v[208:211], v198 offset:6144
	ds_read_b128 v[212:215], v198 offset:7168
	global_load_lds_dwordx4 v172, s[28:29]
	s_add_i32 m0, s5, 0xe000
	s_nop 0
	global_load_lds_dwordx4 v174, s[28:29]
	s_waitcnt vmcnt(8)
	s_waitcnt lgkmcnt(0)
	s_setprio 1
	s_barrier
	v_mfma_f32_16x16x32_bf16 v[136:139], v[88:91], v[160:163], v[136:139]
	v_mfma_f32_16x16x32_bf16 v[140:143], v[104:107], v[160:163], v[140:143]
	v_mfma_f32_16x16x32_bf16 v[124:127], v[88:91], v[184:187], v[124:127]
	v_mfma_f32_16x16x32_bf16 v[120:123], v[104:107], v[184:187], v[120:123]
	v_mfma_f32_16x16x32_bf16 v[100:103], v[88:91], v[200:203], v[100:103]
	v_mfma_f32_16x16x32_bf16 v[96:99], v[104:107], v[200:203], v[96:99]
	v_mfma_f32_16x16x32_bf16 v[76:79], v[88:91], v[208:211], v[76:79]
	v_mfma_f32_16x16x32_bf16 v[72:75], v[104:107], v[208:211], v[72:75]
	v_mfma_f32_16x16x32_bf16 v[136:139], v[92:95], v[180:183], v[136:139]
	v_mfma_f32_16x16x32_bf16 v[140:143], v[108:111], v[180:183], v[140:143]
	v_mfma_f32_16x16x32_bf16 v[124:127], v[92:95], v[188:191], v[124:127]
	v_mfma_f32_16x16x32_bf16 v[120:123], v[108:111], v[188:191], v[120:123]
	v_mfma_f32_16x16x32_bf16 v[100:103], v[92:95], v[204:207], v[100:103]
	v_mfma_f32_16x16x32_bf16 v[96:99], v[108:111], v[204:207], v[96:99]
	v_mfma_f32_16x16x32_bf16 v[76:79], v[92:95], v[212:215], v[76:79]
	v_mfma_f32_16x16x32_bf16 v[72:75], v[108:111], v[212:215], v[72:75]
	v_mfma_f32_16x16x32_bf16 v[132:135], v[144:147], v[160:163], v[132:135]
	v_mfma_f32_16x16x32_bf16 v[128:131], v[152:155], v[160:163], v[128:131]
	v_mfma_f32_16x16x32_bf16 v[116:119], v[144:147], v[184:187], v[116:119]
	v_mfma_f32_16x16x32_bf16 v[112:115], v[152:155], v[184:187], v[112:115]
	v_mfma_f32_16x16x32_bf16 v[84:87], v[144:147], v[200:203], v[84:87]
	v_mfma_f32_16x16x32_bf16 v[80:83], v[152:155], v[200:203], v[80:83]
	v_mfma_f32_16x16x32_bf16 v[68:71], v[144:147], v[208:211], v[68:71]
	v_mfma_f32_16x16x32_bf16 v[64:67], v[152:155], v[208:211], v[64:67]
	v_mfma_f32_16x16x32_bf16 v[132:135], v[148:151], v[180:183], v[132:135]
	v_mfma_f32_16x16x32_bf16 v[128:131], v[156:159], v[180:183], v[128:131]
	v_mfma_f32_16x16x32_bf16 v[116:119], v[148:151], v[188:191], v[116:119]
	v_mfma_f32_16x16x32_bf16 v[112:115], v[156:159], v[188:191], v[112:115]
	v_mfma_f32_16x16x32_bf16 v[84:87], v[148:151], v[204:207], v[84:87]
	v_mfma_f32_16x16x32_bf16 v[80:83], v[156:159], v[204:207], v[80:83]
	v_mfma_f32_16x16x32_bf16 v[68:71], v[148:151], v[212:215], v[68:71]
	v_mfma_f32_16x16x32_bf16 v[64:67], v[156:159], v[212:215], v[64:67]
	s_barrier
	s_setprio 0
	s_add_u32 s98, s30, s12
	s_addc_u32 s99, s31, s13
	s_add_i32 s52, s44, s3
	s_mov_b32 m0, s52
	ds_read_b128 v[160:163], v198 offset:16384
	ds_read_b128 v[180:183], v198 offset:17408
	ds_read_b128 v[184:187], v198 offset:18432
	ds_read_b128 v[188:191], v198 offset:19456
	ds_read_b128 v[200:203], v198 offset:20480
	ds_read_b128 v[204:207], v198 offset:21504
	ds_read_b128 v[208:211], v198 offset:22528
	ds_read_b128 v[212:215], v198 offset:23552
	global_load_lds_dwordx4 v168, s[30:31]
	s_add_i32 m0, s52, 0x2000
	s_add_u32 s52, s30, 0x40000
	s_addc_u32 s53, s31, 0
	s_add_i32 s54, s45, s3
	global_load_lds_dwordx4 v164, s[30:31]
	s_mov_b32 m0, s54
	s_nop 0
	global_load_lds_dwordx4 v168, s[52:53]
	s_add_i32 m0, s54, 0x2000
	s_nop 0
	global_load_lds_dwordx4 v164, s[52:53]
	s_waitcnt vmcnt(6)
	s_waitcnt lgkmcnt(0)
	s_setprio 1
	s_barrier
	v_mfma_f32_16x16x32_bf16 v[60:63], v[88:91], v[160:163], v[60:63]
	v_mfma_f32_16x16x32_bf16 v[56:59], v[104:107], v[160:163], v[56:59]
	v_mfma_f32_16x16x32_bf16 v[44:47], v[88:91], v[184:187], v[44:47]
	v_mfma_f32_16x16x32_bf16 v[40:43], v[104:107], v[184:187], v[40:43]
	v_mfma_f32_16x16x32_bf16 v[28:31], v[88:91], v[200:203], v[28:31]
	v_mfma_f32_16x16x32_bf16 v[24:27], v[104:107], v[200:203], v[24:27]
	v_mfma_f32_16x16x32_bf16 v[12:15], v[88:91], v[208:211], v[12:15]
	v_mfma_f32_16x16x32_bf16 v[8:11], v[104:107], v[208:211], v[8:11]
	v_mfma_f32_16x16x32_bf16 v[60:63], v[92:95], v[180:183], v[60:63]
	v_mfma_f32_16x16x32_bf16 v[56:59], v[108:111], v[180:183], v[56:59]
	v_mfma_f32_16x16x32_bf16 v[44:47], v[92:95], v[188:191], v[44:47]
	v_mfma_f32_16x16x32_bf16 v[40:43], v[108:111], v[188:191], v[40:43]
	v_mfma_f32_16x16x32_bf16 v[28:31], v[92:95], v[204:207], v[28:31]
	v_mfma_f32_16x16x32_bf16 v[24:27], v[108:111], v[204:207], v[24:27]
	v_mfma_f32_16x16x32_bf16 v[12:15], v[92:95], v[212:215], v[12:15]
	v_mfma_f32_16x16x32_bf16 v[8:11], v[108:111], v[212:215], v[8:11]
	v_mfma_f32_16x16x32_bf16 v[52:55], v[144:147], v[160:163], v[52:55]
	v_mfma_f32_16x16x32_bf16 v[48:51], v[152:155], v[160:163], v[48:51]
	v_mfma_f32_16x16x32_bf16 v[36:39], v[144:147], v[184:187], v[36:39]
	v_mfma_f32_16x16x32_bf16 v[32:35], v[152:155], v[184:187], v[32:35]
	v_mfma_f32_16x16x32_bf16 v[20:23], v[144:147], v[200:203], v[20:23]
	v_mfma_f32_16x16x32_bf16 v[16:19], v[152:155], v[200:203], v[16:19]
	v_mfma_f32_16x16x32_bf16 v[4:7], v[144:147], v[208:211], v[4:7]
	v_mfma_f32_16x16x32_bf16 v[0:3], v[152:155], v[208:211], v[0:3]
	v_mfma_f32_16x16x32_bf16 v[52:55], v[148:151], v[180:183], v[52:55]
	v_mfma_f32_16x16x32_bf16 v[48:51], v[156:159], v[180:183], v[48:51]
	v_mfma_f32_16x16x32_bf16 v[36:39], v[148:151], v[188:191], v[36:39]
	v_mfma_f32_16x16x32_bf16 v[32:35], v[156:159], v[188:191], v[32:35]
	v_mfma_f32_16x16x32_bf16 v[20:23], v[148:151], v[204:207], v[20:23]
	v_mfma_f32_16x16x32_bf16 v[16:19], v[156:159], v[204:207], v[16:19]
	v_mfma_f32_16x16x32_bf16 v[4:7], v[148:151], v[212:215], v[4:7]
	v_mfma_f32_16x16x32_bf16 v[0:3], v[156:159], v[212:215], v[0:3]
	s_barrier
; #define PG8_STAGE(bufoff, gbase, voff) do { _Pragma("unroll") for (int _i = 0; _i < 2; ++_i) \
;         __builtin_amdgcn_global_load_lds((const unsigned*)((const char*)(gbase) + (voff)[_i]), (LAS unsigned*)(lds + (bufoff) + ldsw + _i * 8192), 16, 0, ((voff) == voffA ? AUXA : 0)); } while (0)
; #define PG8_LDA(dst, b, h) do { _Pragma("unroll") for (int m = 0; m < 4; ++m) _Pragma("unroll") for (int k = 0; k < 2; ++k) dst[m][k] = *(const LAS bf16x8*)(lds + PG8_SA(b, h) + aoff + m * 2048 + k * 1024); } while (0)
; #define PG8_LDB(dst, b, h) do { _Pragma("unroll") for (int n = 0; n < 2; ++n) _Pragma("unroll") for (int k = 0; k < 2; ++k) dst[n][k] = *(const LAS bf16x8*)(lds + PG8_SB(b, h) + boff + n * 2048 + k * 1024); } while (0)
; #define PG8_MMA(ai, bj, At, Bt) do { __builtin_amdgcn_s_setprio(1); _Pragma("unroll") for (int m = 0; m < 4; ++m) _Pragma("unroll") for (int n = 0; n < 2; ++n) _Pragma("unroll") for (int k = 0; k < 2; ++k) \
;         acc[ai][bj][m][n] = __builtin_amdgcn_mfma_f32_16x16x32_bf16(Bt[n][k], At[m][k], acc[ai][bj][m][n], 0, 0, 0); __builtin_amdgcn_s_setprio(0); } while (0)
; #define PG8_WAIT_V(n) asm volatile("s_waitcnt vmcnt(" #n ")" ::: "memory")
; #define PG8_WAIT_L(n) asm volatile("s_waitcnt lgkmcnt(" #n ")" ::: "memory")
; #define PG8_BAR __builtin_amdgcn_s_barrier()
; #define PG8_SCHED __builtin_amdgcn_sched_barrier(0)
;     ...
;             PG8_LDB(B0, 1, 0); PG8_LDB(B1, 1, 1); PG8_SCHED; PG8_LDA(At, 1, 0); PG8_STAGE(PG8_SA(0, 1), a2 + hsA, voffA);
;             PG8_WAIT_V(8); PG8_WAIT_L(0); PG8_BAR; PG8_MMA(0, 0, At, B0); PG8_MMA(0, 1, At, B1); PG8_BAR; PG8_SCHED;
;             PG8_LDA(At, 1, 1); PG8_STAGE(PG8_SB(1, 0), b3, voffB); PG8_STAGE(PG8_SB(1, 1), b3 + hsB, voffB); PG8_STAGE(PG8_SA(1, 0), a3, voffA);
;             PG8_WAIT_V(8); PG8_WAIT_L(0); PG8_BAR; PG8_MMA(1, 0, At, B0); PG8_MMA(1, 1, At, B1); PG8_BAR; PG8_SCHED;
;         }
	s_mov_b32 m0, s5
	s_nop 0
	global_load_lds_dwordx4 v170, s[34:35]
	s_mov_b32 m0, s27
	s_nop 0
	global_load_lds_dwordx4 v166, s[34:35]
	s_setprio 0
	s_add_i32 s52, 0, 0x18000
	s_add_i32 s53, 0, 0x1c000
	v_add_u32_e32 v108, s52, v194
	v_add_u32_e32 v156, s53, v194
	ds_read_b128 v[88:91], v108
	ds_read_b128 v[92:95], v108 offset:1024
	ds_read_b128 v[104:107], v108 offset:2048
	ds_read_b128 v[108:111], v108 offset:3072
	ds_read_b128 v[144:147], v156
	ds_read_b128 v[148:151], v156 offset:1024
	ds_read_b128 v[152:155], v156 offset:2048
	ds_read_b128 v[156:159], v156 offset:3072
	s_add_u32 s34, s34, 0x40000
	s_addc_u32 s35, s35, 0
	s_mov_b32 m0, s36
	ds_read_b128 v[160:163], v198 offset:32768
	ds_read_b128 v[180:183], v198 offset:33792
	ds_read_b128 v[184:187], v198 offset:34816
	ds_read_b128 v[188:191], v198 offset:35840
	ds_read_b128 v[200:203], v198 offset:36864
	ds_read_b128 v[204:207], v198 offset:37888
	ds_read_b128 v[208:211], v198 offset:38912
	ds_read_b128 v[212:215], v198 offset:39936
	global_load_lds_dwordx4 v170, s[34:35]
	s_mov_b32 m0, s37
	s_nop 0
	global_load_lds_dwordx4 v166, s[34:35]
	s_waitcnt vmcnt(8)
	s_waitcnt lgkmcnt(0)
	s_setprio 1
	s_barrier
	v_mfma_f32_16x16x32_bf16 v[136:139], v[88:91], v[160:163], v[136:139]
	v_mfma_f32_16x16x32_bf16 v[140:143], v[104:107], v[160:163], v[140:143]
	v_mfma_f32_16x16x32_bf16 v[124:127], v[88:91], v[184:187], v[124:127]
	v_mfma_f32_16x16x32_bf16 v[120:123], v[104:107], v[184:187], v[120:123]
	v_mfma_f32_16x16x32_bf16 v[100:103], v[88:91], v[200:203], v[100:103]
	v_mfma_f32_16x16x32_bf16 v[96:99], v[104:107], v[200:203], v[96:99]
	v_mfma_f32_16x16x32_bf16 v[76:79], v[88:91], v[208:211], v[76:79]
	v_mfma_f32_16x16x32_bf16 v[72:75], v[104:107], v[208:211], v[72:75]
	v_mfma_f32_16x16x32_bf16 v[136:139], v[92:95], v[180:183], v[136:139]
	v_mfma_f32_16x16x32_bf16 v[140:143], v[108:111], v[180:183], v[140:143]
	v_mfma_f32_16x16x32_bf16 v[124:127], v[92:95], v[188:191], v[124:127]
	v_mfma_f32_16x16x32_bf16 v[120:123], v[108:111], v[188:191], v[120:123]
	v_mfma_f32_16x16x32_bf16 v[100:103], v[92:95], v[204:207], v[100:103]
	v_mfma_f32_16x16x32_bf16 v[96:99], v[108:111], v[204:207], v[96:99]
	v_mfma_f32_16x16x32_bf16 v[76:79], v[92:95], v[212:215], v[76:79]
	v_mfma_f32_16x16x32_bf16 v[72:75], v[108:111], v[212:215], v[72:75]
	v_mfma_f32_16x16x32_bf16 v[132:135], v[144:147], v[160:163], v[132:135]
	v_mfma_f32_16x16x32_bf16 v[128:131], v[152:155], v[160:163], v[128:131]
	v_mfma_f32_16x16x32_bf16 v[116:119], v[144:147], v[184:187], v[116:119]
	v_mfma_f32_16x16x32_bf16 v[112:115], v[152:155], v[184:187], v[112:115]
	v_mfma_f32_16x16x32_bf16 v[84:87], v[144:147], v[200:203], v[84:87]
	v_mfma_f32_16x16x32_bf16 v[80:83], v[152:155], v[200:203], v[80:83]
	v_mfma_f32_16x16x32_bf16 v[68:71], v[144:147], v[208:211], v[68:71]
	v_mfma_f32_16x16x32_bf16 v[64:67], v[152:155], v[208:211], v[64:67]
	v_mfma_f32_16x16x32_bf16 v[132:135], v[148:151], v[180:183], v[132:135]
	v_mfma_f32_16x16x32_bf16 v[128:131], v[156:159], v[180:183], v[128:131]
	v_mfma_f32_16x16x32_bf16 v[116:119], v[148:151], v[188:191], v[116:119]
	v_mfma_f32_16x16x32_bf16 v[112:115], v[156:159], v[188:191], v[112:115]
	v_mfma_f32_16x16x32_bf16 v[84:87], v[148:151], v[204:207], v[84:87]
	v_mfma_f32_16x16x32_bf16 v[80:83], v[156:159], v[204:207], v[80:83]
	v_mfma_f32_16x16x32_bf16 v[68:71], v[148:151], v[212:215], v[68:71]
	v_mfma_f32_16x16x32_bf16 v[64:67], v[156:159], v[212:215], v[64:67]
	s_barrier
	s_setprio 0
	s_add_i32 s34, s52, s3
	s_mov_b32 m0, s34
	ds_read_b128 v[160:163], v198 offset:49152
	ds_read_b128 v[180:183], v198 offset:50176
	ds_read_b128 v[184:187], v198 offset:51200
	ds_read_b128 v[188:191], v198 offset:52224
	ds_read_b128 v[200:203], v198 offset:53248
	ds_read_b128 v[204:207], v198 offset:54272
	ds_read_b128 v[208:211], v198 offset:55296
	ds_read_b128 v[212:215], v198 offset:56320
	global_load_lds_dwordx4 v168, s[98:99]
	s_add_i32 m0, s34, 0x2000
	s_add_u32 s30, s30, 0x40080
	s_addc_u32 s31, s31, 0
	s_add_i32 s34, s53, s3
	global_load_lds_dwordx4 v164, s[98:99]
	s_mov_b32 m0, s34
	s_nop 0
	global_load_lds_dwordx4 v168, s[30:31]
	s_add_i32 m0, s34, 0x2000
	s_nop 0
	global_load_lds_dwordx4 v164, s[30:31]
	s_waitcnt vmcnt(6)
	s_waitcnt lgkmcnt(0)
	s_setprio 1
	s_barrier
	v_mfma_f32_16x16x32_bf16 v[60:63], v[88:91], v[160:163], v[60:63]
	v_mfma_f32_16x16x32_bf16 v[56:59], v[104:107], v[160:163], v[56:59]
	v_mfma_f32_16x16x32_bf16 v[44:47], v[88:91], v[184:187], v[44:47]
	v_mfma_f32_16x16x32_bf16 v[40:43], v[104:107], v[184:187], v[40:43]
	v_mfma_f32_16x16x32_bf16 v[28:31], v[88:91], v[200:203], v[28:31]
	v_mfma_f32_16x16x32_bf16 v[24:27], v[104:107], v[200:203], v[24:27]
	v_mfma_f32_16x16x32_bf16 v[12:15], v[88:91], v[208:211], v[12:15]
	v_mfma_f32_16x16x32_bf16 v[8:11], v[104:107], v[208:211], v[8:11]
	v_mfma_f32_16x16x32_bf16 v[60:63], v[92:95], v[180:183], v[60:63]
	v_mfma_f32_16x16x32_bf16 v[56:59], v[108:111], v[180:183], v[56:59]
	v_mfma_f32_16x16x32_bf16 v[44:47], v[92:95], v[188:191], v[44:47]
	v_mfma_f32_16x16x32_bf16 v[40:43], v[108:111], v[188:191], v[40:43]
	v_mfma_f32_16x16x32_bf16 v[28:31], v[92:95], v[204:207], v[28:31]
	v_mfma_f32_16x16x32_bf16 v[24:27], v[108:111], v[204:207], v[24:27]
	v_mfma_f32_16x16x32_bf16 v[12:15], v[92:95], v[212:215], v[12:15]
	v_mfma_f32_16x16x32_bf16 v[8:11], v[108:111], v[212:215], v[8:11]
	v_mfma_f32_16x16x32_bf16 v[52:55], v[144:147], v[160:163], v[52:55]
	v_mfma_f32_16x16x32_bf16 v[48:51], v[152:155], v[160:163], v[48:51]
	v_mfma_f32_16x16x32_bf16 v[36:39], v[144:147], v[184:187], v[36:39]
	v_mfma_f32_16x16x32_bf16 v[32:35], v[152:155], v[184:187], v[32:35]
	v_mfma_f32_16x16x32_bf16 v[20:23], v[144:147], v[200:203], v[20:23]
	v_mfma_f32_16x16x32_bf16 v[16:19], v[152:155], v[200:203], v[16:19]
	v_mfma_f32_16x16x32_bf16 v[4:7], v[144:147], v[208:211], v[4:7]
	v_mfma_f32_16x16x32_bf16 v[0:3], v[152:155], v[208:211], v[0:3]
	v_mfma_f32_16x16x32_bf16 v[52:55], v[148:151], v[180:183], v[52:55]
	v_mfma_f32_16x16x32_bf16 v[48:51], v[156:159], v[180:183], v[48:51]
	v_mfma_f32_16x16x32_bf16 v[36:39], v[148:151], v[188:191], v[36:39]
	v_mfma_f32_16x16x32_bf16 v[32:35], v[156:159], v[188:191], v[32:35]
	v_mfma_f32_16x16x32_bf16 v[20:23], v[148:151], v[204:207], v[20:23]
	v_mfma_f32_16x16x32_bf16 v[16:19], v[156:159], v[204:207], v[16:19]
	v_mfma_f32_16x16x32_bf16 v[4:7], v[148:151], v[212:215], v[4:7]
	v_mfma_f32_16x16x32_bf16 v[0:3], v[156:159], v[212:215], v[0:3]
	s_barrier
	s_setprio 0
	s_add_u32 s28, s28, 0x100
	s_addc_u32 s29, s29, 0
	s_add_u32 s49, s49, 0x100
	s_addc_u32 s50, s50, 0
	s_cmp_ge_i32 s51, s39
	s_mov_b32 s30, s51
	s_cbranch_scc0 .LBB0_959

; #define PG8_STAGE(bufoff, gbase, voff) do { _Pragma("unroll") for (int _i = 0; _i < 2; ++_i) \
;         __builtin_amdgcn_global_load_lds((const unsigned*)((const char*)(gbase) + (voff)[_i]), (LAS unsigned*)(lds + (bufoff) + ldsw + _i * 8192), 16, 0, ((voff) == voffA ? AUXA : 0)); } while (0)
; #define PG8_LDA(dst, b, h) do { _Pragma("unroll") for (int m = 0; m < 4; ++m) _Pragma("unroll") for (int k = 0; k < 2; ++k) dst[m][k] = *(const LAS bf16x8*)(lds + PG8_SA(b, h) + aoff + m * 2048 + k * 1024); } while (0)
; #define PG8_LDB(dst, b, h) do { _Pragma("unroll") for (int n = 0; n < 2; ++n) _Pragma("unroll") for (int k = 0; k < 2; ++k) dst[n][k] = *(const LAS bf16x8*)(lds + PG8_SB(b, h) + boff + n * 2048 + k * 1024); } while (0)
; #define PG8_MMA(ai, bj, At, Bt) do { __builtin_amdgcn_s_setprio(1); _Pragma("unroll") for (int m = 0; m < 4; ++m) _Pragma("unroll") for (int n = 0; n < 2; ++n) _Pragma("unroll") for (int k = 0; k < 2; ++k) \
;         acc[ai][bj][m][n] = __builtin_amdgcn_mfma_f32_16x16x32_bf16(Bt[n][k], At[m][k], acc[ai][bj][m][n], 0, 0, 0); __builtin_amdgcn_s_setprio(0); } while (0)
; #define PG8_WAIT_V(n) asm volatile("s_waitcnt vmcnt(" #n ")" ::: "memory")
; #define PG8_WAIT_L(n) asm volatile("s_waitcnt lgkmcnt(" #n ")" ::: "memory")
; #define PG8_BAR __builtin_amdgcn_s_barrier()
; #define PG8_SCHED __builtin_amdgcn_sched_barrier(0)
;     ...
;         for (int t = 0; t < nt; t += 2) {
;             const bool last = (t == nt - 2);
;             const char* a1 = cA + (size_t)(t + 1) * kstep;
;             const char* a2 = last ? nA : cA + (size_t)(t + 2) * kstep; const char* b2 = last ? nB : cB + (size_t)(t + 2) * kstep;
;             const char* a3 = a2 + kstep; const char* b3 = b2 + kstep;
;             PG8_LDB(B0, 0, 0); PG8_LDB(B1, 0, 1); PG8_SCHED; PG8_LDA(At, 0, 0); PG8_STAGE(PG8_SA(1, 1), a1 + hsA, voffA);
;             if (Epi::NPRE != 0 && last) { E.pre(sv, cur, wr, fr); PG8_WAIT_V(16); } else { PG8_WAIT_V(8); }
;             PG8_WAIT_L(0); PG8_BAR; PG8_MMA(0, 0, At, B0); PG8_MMA(0, 1, At, B1); PG8_BAR; PG8_SCHED;
;             PG8_LDA(At, 0, 1); PG8_STAGE(PG8_SB(0, 0), b2, voffB); PG8_STAGE(PG8_SB(0, 1), b2 + hsB, voffB); PG8_STAGE(PG8_SA(0, 0), a2, voffA);
;             if (Epi::NPRE != 0 && last) { PG8_WAIT_V(16); } else { PG8_WAIT_V(8); }
;             PG8_WAIT_L(0); PG8_BAR; PG8_MMA(1, 0, At, B0); PG8_MMA(1, 1, At, B1); PG8_BAR; PG8_SCHED;
.LBB0_1040:
	s_add_u32 s98, s28, 0xfffc0000
	s_mov_b32 m0, s45
	s_addc_u32 s99, s29, -1
	global_load_lds_dwordx4 v134, s[98:99]
	s_mov_b32 m0, s46
	s_nop 0
	global_load_lds_dwordx4 v130, s[98:99]
	ds_read_b128 v[150:153], v147
	ds_read_b128 v[154:157], v147 offset:1024
	ds_read_b128 v[158:161], v147 offset:2048
	ds_read_b128 v[162:165], v147 offset:3072
	ds_read_b128 v[166:169], v148
	ds_read_b128 v[170:173], v148 offset:1024
	ds_read_b128 v[174:177], v148 offset:2048
	ds_read_b128 v[178:181], v148 offset:3072
	s_add_i32 s56, s30, 2
	s_add_u32 s31, s28, 0xfffc0080
	s_addc_u32 s34, s29, -1
	s_cmp_eq_u32 s47, s30
	s_cselect_b32 s30, s53, s54
	s_cselect_b32 s35, s21, s34
	s_cselect_b32 s34, s23, s31
	s_cselect_b32 s31, s52, s55
	s_add_i32 m0, s19, 0xc000
	ds_read_b128 v[182:185], v149
	ds_read_b128 v[186:189], v149 offset:1024
	ds_read_b128 v[190:193], v149 offset:2048
	ds_read_b128 v[194:197], v149 offset:3072
	ds_read_b128 v[198:201], v149 offset:4096
	ds_read_b128 v[202:205], v149 offset:5120
	ds_read_b128 v[206:209], v149 offset:6144
	ds_read_b128 v[210:213], v149 offset:7168
	global_load_lds_dwordx4 v136, s[28:29]
	s_add_i32 m0, s19, 0xe000
	s_nop 0
	global_load_lds_dwordx4 v138, s[28:29]
	s_waitcnt vmcnt(8)
	s_waitcnt lgkmcnt(0)
	s_setprio 1
	s_barrier
	v_mfma_f32_16x16x32_bf16 v[124:127], v[150:153], v[182:185], v[124:127]
	v_mfma_f32_16x16x32_bf16 v[120:123], v[158:161], v[182:185], v[120:123]
	v_mfma_f32_16x16x32_bf16 v[108:111], v[150:153], v[190:193], v[108:111]
	v_mfma_f32_16x16x32_bf16 v[104:107], v[158:161], v[190:193], v[104:107]
	v_mfma_f32_16x16x32_bf16 v[92:95], v[150:153], v[198:201], v[92:95]
	v_mfma_f32_16x16x32_bf16 v[88:91], v[158:161], v[198:201], v[88:91]
	v_mfma_f32_16x16x32_bf16 v[76:79], v[150:153], v[206:209], v[76:79]
	v_mfma_f32_16x16x32_bf16 v[72:75], v[158:161], v[206:209], v[72:75]
	v_mfma_f32_16x16x32_bf16 v[124:127], v[154:157], v[186:189], v[124:127]
	v_mfma_f32_16x16x32_bf16 v[120:123], v[162:165], v[186:189], v[120:123]
	v_mfma_f32_16x16x32_bf16 v[108:111], v[154:157], v[194:197], v[108:111]
	v_mfma_f32_16x16x32_bf16 v[104:107], v[162:165], v[194:197], v[104:107]
	v_mfma_f32_16x16x32_bf16 v[92:95], v[154:157], v[202:205], v[92:95]
	v_mfma_f32_16x16x32_bf16 v[88:91], v[162:165], v[202:205], v[88:91]
	v_mfma_f32_16x16x32_bf16 v[76:79], v[154:157], v[210:213], v[76:79]
	v_mfma_f32_16x16x32_bf16 v[72:75], v[162:165], v[210:213], v[72:75]
	v_mfma_f32_16x16x32_bf16 v[116:119], v[166:169], v[182:185], v[116:119]
	v_mfma_f32_16x16x32_bf16 v[112:115], v[174:177], v[182:185], v[112:115]
	v_mfma_f32_16x16x32_bf16 v[100:103], v[166:169], v[190:193], v[100:103]
	v_mfma_f32_16x16x32_bf16 v[96:99], v[174:177], v[190:193], v[96:99]
	v_mfma_f32_16x16x32_bf16 v[84:87], v[166:169], v[198:201], v[84:87]
	v_mfma_f32_16x16x32_bf16 v[80:83], v[174:177], v[198:201], v[80:83]
	v_mfma_f32_16x16x32_bf16 v[68:71], v[166:169], v[206:209], v[68:71]
	v_mfma_f32_16x16x32_bf16 v[64:67], v[174:177], v[206:209], v[64:67]
	v_mfma_f32_16x16x32_bf16 v[116:119], v[170:173], v[186:189], v[116:119]
	v_mfma_f32_16x16x32_bf16 v[112:115], v[178:181], v[186:189], v[112:115]
	v_mfma_f32_16x16x32_bf16 v[100:103], v[170:173], v[194:197], v[100:103]
	v_mfma_f32_16x16x32_bf16 v[96:99], v[178:181], v[194:197], v[96:99]
	v_mfma_f32_16x16x32_bf16 v[84:87], v[170:173], v[202:205], v[84:87]
	v_mfma_f32_16x16x32_bf16 v[80:83], v[178:181], v[202:205], v[80:83]
	v_mfma_f32_16x16x32_bf16 v[68:71], v[170:173], v[210:213], v[68:71]
	v_mfma_f32_16x16x32_bf16 v[64:67], v[178:181], v[210:213], v[64:67]
	s_barrier
	s_setprio 0
	s_add_u32 s98, s30, s14
	s_addc_u32 s99, s31, s15
	s_add_i32 s57, s49, s37
	s_mov_b32 m0, s57
	ds_read_b128 v[182:185], v149 offset:16384
	ds_read_b128 v[186:189], v149 offset:17408
	ds_read_b128 v[190:193], v149 offset:18432
	ds_read_b128 v[194:197], v149 offset:19456
	ds_read_b128 v[198:201], v149 offset:20480
	ds_read_b128 v[202:205], v149 offset:21504
	ds_read_b128 v[206:209], v149 offset:22528
	ds_read_b128 v[210:213], v149 offset:23552
	global_load_lds_dwordx4 v132, s[30:31]
	s_add_i32 m0, s57, 0x2000
	s_add_u32 s58, s30, 0x40000
	s_addc_u32 s59, s31, 0
	s_add_i32 s57, s50, s37
	global_load_lds_dwordx4 v128, s[30:31]
	s_mov_b32 m0, s57
	s_nop 0
	global_load_lds_dwordx4 v132, s[58:59]
	s_add_i32 m0, s57, 0x2000
	s_nop 0
	global_load_lds_dwordx4 v128, s[58:59]
	s_waitcnt vmcnt(6)
	s_waitcnt lgkmcnt(0)
	s_setprio 1
	s_barrier
	v_mfma_f32_16x16x32_bf16 v[60:63], v[150:153], v[182:185], v[60:63]
	v_mfma_f32_16x16x32_bf16 v[56:59], v[158:161], v[182:185], v[56:59]
	v_mfma_f32_16x16x32_bf16 v[44:47], v[150:153], v[190:193], v[44:47]
	v_mfma_f32_16x16x32_bf16 v[40:43], v[158:161], v[190:193], v[40:43]
	v_mfma_f32_16x16x32_bf16 v[28:31], v[150:153], v[198:201], v[28:31]
	v_mfma_f32_16x16x32_bf16 v[24:27], v[158:161], v[198:201], v[24:27]
	v_mfma_f32_16x16x32_bf16 v[12:15], v[150:153], v[206:209], v[12:15]
	v_mfma_f32_16x16x32_bf16 v[8:11], v[158:161], v[206:209], v[8:11]
	v_mfma_f32_16x16x32_bf16 v[60:63], v[154:157], v[186:189], v[60:63]
	v_mfma_f32_16x16x32_bf16 v[56:59], v[162:165], v[186:189], v[56:59]
	v_mfma_f32_16x16x32_bf16 v[44:47], v[154:157], v[194:197], v[44:47]
	v_mfma_f32_16x16x32_bf16 v[40:43], v[162:165], v[194:197], v[40:43]
	v_mfma_f32_16x16x32_bf16 v[28:31], v[154:157], v[202:205], v[28:31]
	v_mfma_f32_16x16x32_bf16 v[24:27], v[162:165], v[202:205], v[24:27]
	v_mfma_f32_16x16x32_bf16 v[12:15], v[154:157], v[210:213], v[12:15]
	v_mfma_f32_16x16x32_bf16 v[8:11], v[162:165], v[210:213], v[8:11]
	v_mfma_f32_16x16x32_bf16 v[52:55], v[166:169], v[182:185], v[52:55]
	v_mfma_f32_16x16x32_bf16 v[48:51], v[174:177], v[182:185], v[48:51]
	v_mfma_f32_16x16x32_bf16 v[36:39], v[166:169], v[190:193], v[36:39]
	v_mfma_f32_16x16x32_bf16 v[32:35], v[174:177], v[190:193], v[32:35]
	v_mfma_f32_16x16x32_bf16 v[20:23], v[166:169], v[198:201], v[20:23]
	v_mfma_f32_16x16x32_bf16 v[16:19], v[174:177], v[198:201], v[16:19]
	v_mfma_f32_16x16x32_bf16 v[4:7], v[166:169], v[206:209], v[4:7]
	v_mfma_f32_16x16x32_bf16 v[0:3], v[174:177], v[206:209], v[0:3]
	v_mfma_f32_16x16x32_bf16 v[52:55], v[170:173], v[186:189], v[52:55]
	v_mfma_f32_16x16x32_bf16 v[48:51], v[178:181], v[186:189], v[48:51]
	v_mfma_f32_16x16x32_bf16 v[36:39], v[170:173], v[194:197], v[36:39]
	v_mfma_f32_16x16x32_bf16 v[32:35], v[178:181], v[194:197], v[32:35]
	v_mfma_f32_16x16x32_bf16 v[20:23], v[170:173], v[202:205], v[20:23]
	v_mfma_f32_16x16x32_bf16 v[16:19], v[178:181], v[202:205], v[16:19]
	v_mfma_f32_16x16x32_bf16 v[4:7], v[170:173], v[210:213], v[4:7]
	v_mfma_f32_16x16x32_bf16 v[0:3], v[178:181], v[210:213], v[0:3]
	s_barrier
; #define PG8_STAGE(bufoff, gbase, voff) do { _Pragma("unroll") for (int _i = 0; _i < 2; ++_i) \
;         __builtin_amdgcn_global_load_lds((const unsigned*)((const char*)(gbase) + (voff)[_i]), (LAS unsigned*)(lds + (bufoff) + ldsw + _i * 8192), 16, 0, ((voff) == voffA ? AUXA : 0)); } while (0)
; #define PG8_LDA(dst, b, h) do { _Pragma("unroll") for (int m = 0; m < 4; ++m) _Pragma("unroll") for (int k = 0; k < 2; ++k) dst[m][k] = *(const LAS bf16x8*)(lds + PG8_SA(b, h) + aoff + m * 2048 + k * 1024); } while (0)
; #define PG8_LDB(dst, b, h) do { _Pragma("unroll") for (int n = 0; n < 2; ++n) _Pragma("unroll") for (int k = 0; k < 2; ++k) dst[n][k] = *(const LAS bf16x8*)(lds + PG8_SB(b, h) + boff + n * 2048 + k * 1024); } while (0)
; #define PG8_MMA(ai, bj, At, Bt) do { __builtin_amdgcn_s_setprio(1); _Pragma("unroll") for (int m = 0; m < 4; ++m) _Pragma("unroll") for (int n = 0; n < 2; ++n) _Pragma("unroll") for (int k = 0; k < 2; ++k) \
;         acc[ai][bj][m][n] = __builtin_amdgcn_mfma_f32_16x16x32_bf16(Bt[n][k], At[m][k], acc[ai][bj][m][n], 0, 0, 0); __builtin_amdgcn_s_setprio(0); } while (0)
; #define PG8_WAIT_V(n) asm volatile("s_waitcnt vmcnt(" #n ")" ::: "memory")
; #define PG8_WAIT_L(n) asm volatile("s_waitcnt lgkmcnt(" #n ")" ::: "memory")
; #define PG8_BAR __builtin_amdgcn_s_barrier()
; #define PG8_SCHED __builtin_amdgcn_sched_barrier(0)
;     ...
;             PG8_LDB(B0, 1, 0); PG8_LDB(B1, 1, 1); PG8_SCHED; PG8_LDA(At, 1, 0); PG8_STAGE(PG8_SA(0, 1), a2 + hsA, voffA);
;             PG8_WAIT_V(8); PG8_WAIT_L(0); PG8_BAR; PG8_MMA(0, 0, At, B0); PG8_MMA(0, 1, At, B1); PG8_BAR; PG8_SCHED;
;             PG8_LDA(At, 1, 1); PG8_STAGE(PG8_SB(1, 0), b3, voffB); PG8_STAGE(PG8_SB(1, 1), b3 + hsB, voffB); PG8_STAGE(PG8_SA(1, 0), a3, voffA);
;             PG8_WAIT_V(8); PG8_WAIT_L(0); PG8_BAR; PG8_MMA(1, 0, At, B0); PG8_MMA(1, 1, At, B1); PG8_BAR; PG8_SCHED;
;         }
	s_mov_b32 m0, s19
	s_nop 0
	global_load_lds_dwordx4 v134, s[34:35]
	s_mov_b32 m0, s40
	s_nop 0
	global_load_lds_dwordx4 v130, s[34:35]
	s_setprio 0
	s_add_i32 s57, 0, 0x18000
	s_add_i32 s58, 0, 0x1c000
	v_add_u32_e32 v162, s57, v145
	v_add_u32_e32 v178, s58, v145
	ds_read_b128 v[150:153], v162
	ds_read_b128 v[154:157], v162 offset:1024
	ds_read_b128 v[158:161], v162 offset:2048
	ds_read_b128 v[162:165], v162 offset:3072
	ds_read_b128 v[166:169], v178
	ds_read_b128 v[170:173], v178 offset:1024
	ds_read_b128 v[174:177], v178 offset:2048
	ds_read_b128 v[178:181], v178 offset:3072
	s_add_u32 s34, s34, 0x40000
	s_addc_u32 s35, s35, 0
	s_mov_b32 m0, s41
	ds_read_b128 v[182:185], v149 offset:32768
	ds_read_b128 v[186:189], v149 offset:33792
	ds_read_b128 v[190:193], v149 offset:34816
	ds_read_b128 v[194:197], v149 offset:35840
	ds_read_b128 v[198:201], v149 offset:36864
	ds_read_b128 v[202:205], v149 offset:37888
	ds_read_b128 v[206:209], v149 offset:38912
	ds_read_b128 v[210:213], v149 offset:39936
	global_load_lds_dwordx4 v134, s[34:35]
	s_mov_b32 m0, s42
	s_nop 0
	global_load_lds_dwordx4 v130, s[34:35]
	s_waitcnt vmcnt(8)
	s_waitcnt lgkmcnt(0)
	s_setprio 1
	s_barrier
	v_mfma_f32_16x16x32_bf16 v[124:127], v[150:153], v[182:185], v[124:127]
	v_mfma_f32_16x16x32_bf16 v[120:123], v[158:161], v[182:185], v[120:123]
	v_mfma_f32_16x16x32_bf16 v[108:111], v[150:153], v[190:193], v[108:111]
	v_mfma_f32_16x16x32_bf16 v[104:107], v[158:161], v[190:193], v[104:107]
	v_mfma_f32_16x16x32_bf16 v[92:95], v[150:153], v[198:201], v[92:95]
	v_mfma_f32_16x16x32_bf16 v[88:91], v[158:161], v[198:201], v[88:91]
	v_mfma_f32_16x16x32_bf16 v[76:79], v[150:153], v[206:209], v[76:79]
	v_mfma_f32_16x16x32_bf16 v[72:75], v[158:161], v[206:209], v[72:75]
	v_mfma_f32_16x16x32_bf16 v[124:127], v[154:157], v[186:189], v[124:127]
	v_mfma_f32_16x16x32_bf16 v[120:123], v[162:165], v[186:189], v[120:123]
	v_mfma_f32_16x16x32_bf16 v[108:111], v[154:157], v[194:197], v[108:111]
	v_mfma_f32_16x16x32_bf16 v[104:107], v[162:165], v[194:197], v[104:107]
	v_mfma_f32_16x16x32_bf16 v[92:95], v[154:157], v[202:205], v[92:95]
	v_mfma_f32_16x16x32_bf16 v[88:91], v[162:165], v[202:205], v[88:91]
	v_mfma_f32_16x16x32_bf16 v[76:79], v[154:157], v[210:213], v[76:79]
	v_mfma_f32_16x16x32_bf16 v[72:75], v[162:165], v[210:213], v[72:75]
	v_mfma_f32_16x16x32_bf16 v[116:119], v[166:169], v[182:185], v[116:119]
	v_mfma_f32_16x16x32_bf16 v[112:115], v[174:177], v[182:185], v[112:115]
	v_mfma_f32_16x16x32_bf16 v[100:103], v[166:169], v[190:193], v[100:103]
	v_mfma_f32_16x16x32_bf16 v[96:99], v[174:177], v[190:193], v[96:99]
	v_mfma_f32_16x16x32_bf16 v[84:87], v[166:169], v[198:201], v[84:87]
	v_mfma_f32_16x16x32_bf16 v[80:83], v[174:177], v[198:201], v[80:83]
	v_mfma_f32_16x16x32_bf16 v[68:71], v[166:169], v[206:209], v[68:71]
	v_mfma_f32_16x16x32_bf16 v[64:67], v[174:177], v[206:209], v[64:67]
	v_mfma_f32_16x16x32_bf16 v[116:119], v[170:173], v[186:189], v[116:119]
	v_mfma_f32_16x16x32_bf16 v[112:115], v[178:181], v[186:189], v[112:115]
	v_mfma_f32_16x16x32_bf16 v[100:103], v[170:173], v[194:197], v[100:103]
	v_mfma_f32_16x16x32_bf16 v[96:99], v[178:181], v[194:197], v[96:99]
	v_mfma_f32_16x16x32_bf16 v[84:87], v[170:173], v[202:205], v[84:87]
	v_mfma_f32_16x16x32_bf16 v[80:83], v[178:181], v[202:205], v[80:83]
	v_mfma_f32_16x16x32_bf16 v[68:71], v[170:173], v[210:213], v[68:71]
	v_mfma_f32_16x16x32_bf16 v[64:67], v[178:181], v[210:213], v[64:67]
	s_barrier
	s_setprio 0
	s_add_i32 s34, s57, s37
	s_mov_b32 m0, s34
	ds_read_b128 v[182:185], v149 offset:49152
	ds_read_b128 v[186:189], v149 offset:50176
	ds_read_b128 v[190:193], v149 offset:51200
	ds_read_b128 v[194:197], v149 offset:52224
	ds_read_b128 v[198:201], v149 offset:53248
	ds_read_b128 v[202:205], v149 offset:54272
	ds_read_b128 v[206:209], v149 offset:55296
	ds_read_b128 v[210:213], v149 offset:56320
	global_load_lds_dwordx4 v132, s[98:99]
	s_add_i32 m0, s34, 0x2000
	s_add_u32 s30, s30, 0x40080
	s_addc_u32 s31, s31, 0
	s_add_i32 s34, s58, s37
	global_load_lds_dwordx4 v128, s[98:99]
	s_mov_b32 m0, s34
	s_nop 0
	global_load_lds_dwordx4 v132, s[30:31]
	s_add_i32 m0, s34, 0x2000
	s_nop 0
	global_load_lds_dwordx4 v128, s[30:31]
	s_waitcnt vmcnt(6)
	s_waitcnt lgkmcnt(0)
	s_setprio 1
	s_barrier
	v_mfma_f32_16x16x32_bf16 v[60:63], v[150:153], v[182:185], v[60:63]
	v_mfma_f32_16x16x32_bf16 v[56:59], v[158:161], v[182:185], v[56:59]
	v_mfma_f32_16x16x32_bf16 v[44:47], v[150:153], v[190:193], v[44:47]
	v_mfma_f32_16x16x32_bf16 v[40:43], v[158:161], v[190:193], v[40:43]
	v_mfma_f32_16x16x32_bf16 v[28:31], v[150:153], v[198:201], v[28:31]
	v_mfma_f32_16x16x32_bf16 v[24:27], v[158:161], v[198:201], v[24:27]
	v_mfma_f32_16x16x32_bf16 v[12:15], v[150:153], v[206:209], v[12:15]
	v_mfma_f32_16x16x32_bf16 v[8:11], v[158:161], v[206:209], v[8:11]
	v_mfma_f32_16x16x32_bf16 v[60:63], v[154:157], v[186:189], v[60:63]
	v_mfma_f32_16x16x32_bf16 v[56:59], v[162:165], v[186:189], v[56:59]
	v_mfma_f32_16x16x32_bf16 v[44:47], v[154:157], v[194:197], v[44:47]
	v_mfma_f32_16x16x32_bf16 v[40:43], v[162:165], v[194:197], v[40:43]
	v_mfma_f32_16x16x32_bf16 v[28:31], v[154:157], v[202:205], v[28:31]
	v_mfma_f32_16x16x32_bf16 v[24:27], v[162:165], v[202:205], v[24:27]
	v_mfma_f32_16x16x32_bf16 v[12:15], v[154:157], v[210:213], v[12:15]
	v_mfma_f32_16x16x32_bf16 v[8:11], v[162:165], v[210:213], v[8:11]
	v_mfma_f32_16x16x32_bf16 v[52:55], v[166:169], v[182:185], v[52:55]
	v_mfma_f32_16x16x32_bf16 v[48:51], v[174:177], v[182:185], v[48:51]
	v_mfma_f32_16x16x32_bf16 v[36:39], v[166:169], v[190:193], v[36:39]
	v_mfma_f32_16x16x32_bf16 v[32:35], v[174:177], v[190:193], v[32:35]
	v_mfma_f32_16x16x32_bf16 v[20:23], v[166:169], v[198:201], v[20:23]
	v_mfma_f32_16x16x32_bf16 v[16:19], v[174:177], v[198:201], v[16:19]
	v_mfma_f32_16x16x32_bf16 v[4:7], v[166:169], v[206:209], v[4:7]
	v_mfma_f32_16x16x32_bf16 v[0:3], v[174:177], v[206:209], v[0:3]
	v_mfma_f32_16x16x32_bf16 v[52:55], v[170:173], v[186:189], v[52:55]
	v_mfma_f32_16x16x32_bf16 v[48:51], v[178:181], v[186:189], v[48:51]
	v_mfma_f32_16x16x32_bf16 v[36:39], v[170:173], v[194:197], v[36:39]
	v_mfma_f32_16x16x32_bf16 v[32:35], v[178:181], v[194:197], v[32:35]
	v_mfma_f32_16x16x32_bf16 v[20:23], v[170:173], v[202:205], v[20:23]
	v_mfma_f32_16x16x32_bf16 v[16:19], v[178:181], v[202:205], v[16:19]
	v_mfma_f32_16x16x32_bf16 v[4:7], v[170:173], v[210:213], v[4:7]
	v_mfma_f32_16x16x32_bf16 v[0:3], v[178:181], v[210:213], v[0:3]
	s_barrier
	s_setprio 0
	s_add_u32 s28, s28, 0x100
	s_addc_u32 s29, s29, 0
	s_add_u32 s54, s54, 0x100
	s_addc_u32 s55, s55, 0
	s_cmp_ge_i32 s56, s44
	s_mov_b32 s30, s56
	s_cbranch_scc0 .LBB0_1040

; #define PG8_STAGE(bufoff, gbase, voff) do { _Pragma("unroll") for (int _i = 0; _i < 2; ++_i) \
;         __builtin_amdgcn_global_load_lds((const unsigned*)((const char*)(gbase) + (voff)[_i]), (LAS unsigned*)(lds + (bufoff) + ldsw + _i * 8192), 16, 0, ((voff) == voffA ? AUXA : 0)); } while (0)
; #define PG8_LDA(dst, b, h) do { _Pragma("unroll") for (int m = 0; m < 4; ++m) _Pragma("unroll") for (int k = 0; k < 2; ++k) dst[m][k] = *(const LAS bf16x8*)(lds + PG8_SA(b, h) + aoff + m * 2048 + k * 1024); } while (0)
; #define PG8_LDB(dst, b, h) do { _Pragma("unroll") for (int n = 0; n < 2; ++n) _Pragma("unroll") for (int k = 0; k < 2; ++k) dst[n][k] = *(const LAS bf16x8*)(lds + PG8_SB(b, h) + boff + n * 2048 + k * 1024); } while (0)
; #define PG8_MMA(ai, bj, At, Bt) do { __builtin_amdgcn_s_setprio(1); _Pragma("unroll") for (int m = 0; m < 4; ++m) _Pragma("unroll") for (int n = 0; n < 2; ++n) _Pragma("unroll") for (int k = 0; k < 2; ++k) \
;         acc[ai][bj][m][n] = __builtin_amdgcn_mfma_f32_16x16x32_bf16(Bt[n][k], At[m][k], acc[ai][bj][m][n], 0, 0, 0); __builtin_amdgcn_s_setprio(0); } while (0)
; #define PG8_WAIT_V(n) asm volatile("s_waitcnt vmcnt(" #n ")" ::: "memory")
; #define PG8_WAIT_L(n) asm volatile("s_waitcnt lgkmcnt(" #n ")" ::: "memory")
; #define PG8_BAR __builtin_amdgcn_s_barrier()
; #define PG8_SCHED __builtin_amdgcn_sched_barrier(0)
;     ...
;             const bool last = (t == nt - 2);
;             const char* a1 = cA + (size_t)(t + 1) * kstep;
;             const char* a2 = last ? nA : cA + (size_t)(t + 2) * kstep; const char* b2 = last ? nB : cB + (size_t)(t + 2) * kstep;
;             const char* a3 = a2 + kstep; const char* b3 = b2 + kstep;
;             PG8_LDB(B0, 0, 0); PG8_LDB(B1, 0, 1); PG8_SCHED; PG8_LDA(At, 0, 0); PG8_STAGE(PG8_SA(1, 1), a1 + hsA, voffA);
;             if (Epi::NPRE != 0 && last) { E.pre(sv, cur, wr, fr); PG8_WAIT_V(16); } else { PG8_WAIT_V(8); }
;             PG8_WAIT_L(0); PG8_BAR; PG8_MMA(0, 0, At, B0); PG8_MMA(0, 1, At, B1); PG8_BAR; PG8_SCHED;
;             PG8_LDA(At, 0, 1); PG8_STAGE(PG8_SB(0, 0), b2, voffB); PG8_STAGE(PG8_SB(0, 1), b2 + hsB, voffB); PG8_STAGE(PG8_SA(0, 0), a2, voffA);
;             if (Epi::NPRE != 0 && last) { PG8_WAIT_V(16); } else { PG8_WAIT_V(8); }
;             PG8_WAIT_L(0); PG8_BAR; PG8_MMA(1, 0, At, B0); PG8_MMA(1, 1, At, B1); PG8_BAR; PG8_SCHED;
.LBB0_1112:
	s_add_u32 s98, s28, 0xfffc0000
	s_mov_b32 m0, s43
	s_addc_u32 s99, s29, -1
	global_load_lds_dwordx4 v134, s[98:99]
	s_mov_b32 m0, s44
	s_nop 0
	global_load_lds_dwordx4 v130, s[98:99]
	ds_read_b128 v[150:153], v147
	ds_read_b128 v[154:157], v147 offset:1024
	ds_read_b128 v[158:161], v147 offset:2048
	ds_read_b128 v[162:165], v147 offset:3072
	ds_read_b128 v[166:169], v148
	ds_read_b128 v[170:173], v148 offset:1024
	ds_read_b128 v[174:177], v148 offset:2048
	ds_read_b128 v[178:181], v148 offset:3072
	s_add_i32 s54, s30, 2
	s_add_u32 s31, s28, 0xfffc0080
	s_addc_u32 s34, s29, -1
	s_cmp_eq_u32 s45, s30
	s_cselect_b32 s30, s51, s52
	s_cselect_b32 s35, s21, s34
	s_cselect_b32 s34, s23, s31
	s_cselect_b32 s31, s50, s53
	s_add_i32 m0, s19, 0xc000
	ds_read_b128 v[182:185], v149
	ds_read_b128 v[186:189], v149 offset:1024
	ds_read_b128 v[190:193], v149 offset:2048
	ds_read_b128 v[194:197], v149 offset:3072
	ds_read_b128 v[198:201], v149 offset:4096
	ds_read_b128 v[202:205], v149 offset:5120
	ds_read_b128 v[206:209], v149 offset:6144
	ds_read_b128 v[210:213], v149 offset:7168
	global_load_lds_dwordx4 v136, s[28:29]
	s_add_i32 m0, s19, 0xe000
	s_nop 0
	global_load_lds_dwordx4 v138, s[28:29]
	s_waitcnt vmcnt(8)
	s_waitcnt lgkmcnt(0)
	s_setprio 1
	s_barrier
	v_mfma_f32_16x16x32_bf16 v[124:127], v[150:153], v[182:185], v[124:127]
	v_mfma_f32_16x16x32_bf16 v[120:123], v[158:161], v[182:185], v[120:123]
	v_mfma_f32_16x16x32_bf16 v[108:111], v[150:153], v[190:193], v[108:111]
	v_mfma_f32_16x16x32_bf16 v[104:107], v[158:161], v[190:193], v[104:107]
	v_mfma_f32_16x16x32_bf16 v[92:95], v[150:153], v[198:201], v[92:95]
	v_mfma_f32_16x16x32_bf16 v[88:91], v[158:161], v[198:201], v[88:91]
	v_mfma_f32_16x16x32_bf16 v[76:79], v[150:153], v[206:209], v[76:79]
	v_mfma_f32_16x16x32_bf16 v[72:75], v[158:161], v[206:209], v[72:75]
	v_mfma_f32_16x16x32_bf16 v[124:127], v[154:157], v[186:189], v[124:127]
	v_mfma_f32_16x16x32_bf16 v[120:123], v[162:165], v[186:189], v[120:123]
	v_mfma_f32_16x16x32_bf16 v[108:111], v[154:157], v[194:197], v[108:111]
	v_mfma_f32_16x16x32_bf16 v[104:107], v[162:165], v[194:197], v[104:107]
	v_mfma_f32_16x16x32_bf16 v[92:95], v[154:157], v[202:205], v[92:95]
	v_mfma_f32_16x16x32_bf16 v[88:91], v[162:165], v[202:205], v[88:91]
	v_mfma_f32_16x16x32_bf16 v[76:79], v[154:157], v[210:213], v[76:79]
	v_mfma_f32_16x16x32_bf16 v[72:75], v[162:165], v[210:213], v[72:75]
	v_mfma_f32_16x16x32_bf16 v[116:119], v[166:169], v[182:185], v[116:119]
	v_mfma_f32_16x16x32_bf16 v[112:115], v[174:177], v[182:185], v[112:115]
	v_mfma_f32_16x16x32_bf16 v[100:103], v[166:169], v[190:193], v[100:103]
	v_mfma_f32_16x16x32_bf16 v[96:99], v[174:177], v[190:193], v[96:99]
	v_mfma_f32_16x16x32_bf16 v[84:87], v[166:169], v[198:201], v[84:87]
	v_mfma_f32_16x16x32_bf16 v[80:83], v[174:177], v[198:201], v[80:83]
	v_mfma_f32_16x16x32_bf16 v[68:71], v[166:169], v[206:209], v[68:71]
	v_mfma_f32_16x16x32_bf16 v[64:67], v[174:177], v[206:209], v[64:67]
	v_mfma_f32_16x16x32_bf16 v[116:119], v[170:173], v[186:189], v[116:119]
	v_mfma_f32_16x16x32_bf16 v[112:115], v[178:181], v[186:189], v[112:115]
	v_mfma_f32_16x16x32_bf16 v[100:103], v[170:173], v[194:197], v[100:103]
	v_mfma_f32_16x16x32_bf16 v[96:99], v[178:181], v[194:197], v[96:99]
	v_mfma_f32_16x16x32_bf16 v[84:87], v[170:173], v[202:205], v[84:87]
	v_mfma_f32_16x16x32_bf16 v[80:83], v[178:181], v[202:205], v[80:83]
	v_mfma_f32_16x16x32_bf16 v[68:71], v[170:173], v[210:213], v[68:71]
	v_mfma_f32_16x16x32_bf16 v[64:67], v[178:181], v[210:213], v[64:67]
	s_barrier
	s_setprio 0
	s_add_u32 s98, s30, s14
	s_addc_u32 s99, s31, s15
	s_add_i32 s55, s47, s5
	s_mov_b32 m0, s55
	ds_read_b128 v[182:185], v149 offset:16384
	ds_read_b128 v[186:189], v149 offset:17408
	ds_read_b128 v[190:193], v149 offset:18432
	ds_read_b128 v[194:197], v149 offset:19456
	ds_read_b128 v[198:201], v149 offset:20480
	ds_read_b128 v[202:205], v149 offset:21504
	ds_read_b128 v[206:209], v149 offset:22528
	ds_read_b128 v[210:213], v149 offset:23552
	global_load_lds_dwordx4 v132, s[30:31]
	s_add_i32 m0, s55, 0x2000
	s_add_u32 s56, s30, 0x40000
	s_addc_u32 s57, s31, 0
	s_add_i32 s55, s48, s5
	global_load_lds_dwordx4 v128, s[30:31]
	s_mov_b32 m0, s55
	s_nop 0
	global_load_lds_dwordx4 v132, s[56:57]
	s_add_i32 m0, s55, 0x2000
	s_nop 0
	global_load_lds_dwordx4 v128, s[56:57]
	s_waitcnt vmcnt(6)
	s_waitcnt lgkmcnt(0)
	s_setprio 1
	s_barrier
	v_mfma_f32_16x16x32_bf16 v[60:63], v[150:153], v[182:185], v[60:63]
	v_mfma_f32_16x16x32_bf16 v[56:59], v[158:161], v[182:185], v[56:59]
	v_mfma_f32_16x16x32_bf16 v[44:47], v[150:153], v[190:193], v[44:47]
	v_mfma_f32_16x16x32_bf16 v[40:43], v[158:161], v[190:193], v[40:43]
	v_mfma_f32_16x16x32_bf16 v[28:31], v[150:153], v[198:201], v[28:31]
	v_mfma_f32_16x16x32_bf16 v[24:27], v[158:161], v[198:201], v[24:27]
	v_mfma_f32_16x16x32_bf16 v[12:15], v[150:153], v[206:209], v[12:15]
	v_mfma_f32_16x16x32_bf16 v[8:11], v[158:161], v[206:209], v[8:11]
	v_mfma_f32_16x16x32_bf16 v[60:63], v[154:157], v[186:189], v[60:63]
	v_mfma_f32_16x16x32_bf16 v[56:59], v[162:165], v[186:189], v[56:59]
	v_mfma_f32_16x16x32_bf16 v[44:47], v[154:157], v[194:197], v[44:47]
	v_mfma_f32_16x16x32_bf16 v[40:43], v[162:165], v[194:197], v[40:43]
	v_mfma_f32_16x16x32_bf16 v[28:31], v[154:157], v[202:205], v[28:31]
	v_mfma_f32_16x16x32_bf16 v[24:27], v[162:165], v[202:205], v[24:27]
	v_mfma_f32_16x16x32_bf16 v[12:15], v[154:157], v[210:213], v[12:15]
	v_mfma_f32_16x16x32_bf16 v[8:11], v[162:165], v[210:213], v[8:11]
	v_mfma_f32_16x16x32_bf16 v[52:55], v[166:169], v[182:185], v[52:55]
	v_mfma_f32_16x16x32_bf16 v[48:51], v[174:177], v[182:185], v[48:51]
	v_mfma_f32_16x16x32_bf16 v[36:39], v[166:169], v[190:193], v[36:39]
	v_mfma_f32_16x16x32_bf16 v[32:35], v[174:177], v[190:193], v[32:35]
	v_mfma_f32_16x16x32_bf16 v[20:23], v[166:169], v[198:201], v[20:23]
	v_mfma_f32_16x16x32_bf16 v[16:19], v[174:177], v[198:201], v[16:19]
	v_mfma_f32_16x16x32_bf16 v[4:7], v[166:169], v[206:209], v[4:7]
	v_mfma_f32_16x16x32_bf16 v[0:3], v[174:177], v[206:209], v[0:3]
	v_mfma_f32_16x16x32_bf16 v[52:55], v[170:173], v[186:189], v[52:55]
	v_mfma_f32_16x16x32_bf16 v[48:51], v[178:181], v[186:189], v[48:51]
	v_mfma_f32_16x16x32_bf16 v[36:39], v[170:173], v[194:197], v[36:39]
	v_mfma_f32_16x16x32_bf16 v[32:35], v[178:181], v[194:197], v[32:35]
	v_mfma_f32_16x16x32_bf16 v[20:23], v[170:173], v[202:205], v[20:23]
	v_mfma_f32_16x16x32_bf16 v[16:19], v[178:181], v[202:205], v[16:19]
	v_mfma_f32_16x16x32_bf16 v[4:7], v[170:173], v[210:213], v[4:7]
	v_mfma_f32_16x16x32_bf16 v[0:3], v[178:181], v[210:213], v[0:3]
	s_barrier
; #define PG8_STAGE(bufoff, gbase, voff) do { _Pragma("unroll") for (int _i = 0; _i < 2; ++_i) \
;         __builtin_amdgcn_global_load_lds((const unsigned*)((const char*)(gbase) + (voff)[_i]), (LAS unsigned*)(lds + (bufoff) + ldsw + _i * 8192), 16, 0, ((voff) == voffA ? AUXA : 0)); } while (0)
; #define PG8_LDA(dst, b, h) do { _Pragma("unroll") for (int m = 0; m < 4; ++m) _Pragma("unroll") for (int k = 0; k < 2; ++k) dst[m][k] = *(const LAS bf16x8*)(lds + PG8_SA(b, h) + aoff + m * 2048 + k * 1024); } while (0)
; #define PG8_LDB(dst, b, h) do { _Pragma("unroll") for (int n = 0; n < 2; ++n) _Pragma("unroll") for (int k = 0; k < 2; ++k) dst[n][k] = *(const LAS bf16x8*)(lds + PG8_SB(b, h) + boff + n * 2048 + k * 1024); } while (0)
; #define PG8_MMA(ai, bj, At, Bt) do { __builtin_amdgcn_s_setprio(1); _Pragma("unroll") for (int m = 0; m < 4; ++m) _Pragma("unroll") for (int n = 0; n < 2; ++n) _Pragma("unroll") for (int k = 0; k < 2; ++k) \
;         acc[ai][bj][m][n] = __builtin_amdgcn_mfma_f32_16x16x32_bf16(Bt[n][k], At[m][k], acc[ai][bj][m][n], 0, 0, 0); __builtin_amdgcn_s_setprio(0); } while (0)
; #define PG8_WAIT_V(n) asm volatile("s_waitcnt vmcnt(" #n ")" ::: "memory")
; #define PG8_WAIT_L(n) asm volatile("s_waitcnt lgkmcnt(" #n ")" ::: "memory")
; #define PG8_BAR __builtin_amdgcn_s_barrier()
; #define PG8_SCHED __builtin_amdgcn_sched_barrier(0)
;     ...
;             PG8_LDB(B0, 1, 0); PG8_LDB(B1, 1, 1); PG8_SCHED; PG8_LDA(At, 1, 0); PG8_STAGE(PG8_SA(0, 1), a2 + hsA, voffA);
;             PG8_WAIT_V(8); PG8_WAIT_L(0); PG8_BAR; PG8_MMA(0, 0, At, B0); PG8_MMA(0, 1, At, B1); PG8_BAR; PG8_SCHED;
;             PG8_LDA(At, 1, 1); PG8_STAGE(PG8_SB(1, 0), b3, voffB); PG8_STAGE(PG8_SB(1, 1), b3 + hsB, voffB); PG8_STAGE(PG8_SA(1, 0), a3, voffA);
;             PG8_WAIT_V(8); PG8_WAIT_L(0); PG8_BAR; PG8_MMA(1, 0, At, B0); PG8_MMA(1, 1, At, B1); PG8_BAR; PG8_SCHED;
;         }
	s_mov_b32 m0, s19
	s_nop 0
	global_load_lds_dwordx4 v134, s[34:35]
	s_mov_b32 m0, s38
	s_nop 0
	global_load_lds_dwordx4 v130, s[34:35]
	s_setprio 0
	s_add_i32 s55, 0, 0x18000
	s_add_i32 s56, 0, 0x1c000
	v_add_u32_e32 v162, s55, v145
	v_add_u32_e32 v178, s56, v145
	ds_read_b128 v[150:153], v162
	ds_read_b128 v[154:157], v162 offset:1024
	ds_read_b128 v[158:161], v162 offset:2048
	ds_read_b128 v[162:165], v162 offset:3072
	ds_read_b128 v[166:169], v178
	ds_read_b128 v[170:173], v178 offset:1024
	ds_read_b128 v[174:177], v178 offset:2048
	ds_read_b128 v[178:181], v178 offset:3072
	s_add_u32 s34, s34, 0x40000
	s_addc_u32 s35, s35, 0
	s_mov_b32 m0, s39
	ds_read_b128 v[182:185], v149 offset:32768
	ds_read_b128 v[186:189], v149 offset:33792
	ds_read_b128 v[190:193], v149 offset:34816
	ds_read_b128 v[194:197], v149 offset:35840
	ds_read_b128 v[198:201], v149 offset:36864
	ds_read_b128 v[202:205], v149 offset:37888
	ds_read_b128 v[206:209], v149 offset:38912
	ds_read_b128 v[210:213], v149 offset:39936
	global_load_lds_dwordx4 v134, s[34:35]
	s_mov_b32 m0, s40
	s_nop 0
	global_load_lds_dwordx4 v130, s[34:35]
	s_waitcnt vmcnt(8)
	s_waitcnt lgkmcnt(0)
	s_setprio 1
	s_barrier
	v_mfma_f32_16x16x32_bf16 v[124:127], v[150:153], v[182:185], v[124:127]
	v_mfma_f32_16x16x32_bf16 v[120:123], v[158:161], v[182:185], v[120:123]
	v_mfma_f32_16x16x32_bf16 v[108:111], v[150:153], v[190:193], v[108:111]
	v_mfma_f32_16x16x32_bf16 v[104:107], v[158:161], v[190:193], v[104:107]
	v_mfma_f32_16x16x32_bf16 v[92:95], v[150:153], v[198:201], v[92:95]
	v_mfma_f32_16x16x32_bf16 v[88:91], v[158:161], v[198:201], v[88:91]
	v_mfma_f32_16x16x32_bf16 v[76:79], v[150:153], v[206:209], v[76:79]
	v_mfma_f32_16x16x32_bf16 v[72:75], v[158:161], v[206:209], v[72:75]
	v_mfma_f32_16x16x32_bf16 v[124:127], v[154:157], v[186:189], v[124:127]
	v_mfma_f32_16x16x32_bf16 v[120:123], v[162:165], v[186:189], v[120:123]
	v_mfma_f32_16x16x32_bf16 v[108:111], v[154:157], v[194:197], v[108:111]
	v_mfma_f32_16x16x32_bf16 v[104:107], v[162:165], v[194:197], v[104:107]
	v_mfma_f32_16x16x32_bf16 v[92:95], v[154:157], v[202:205], v[92:95]
	v_mfma_f32_16x16x32_bf16 v[88:91], v[162:165], v[202:205], v[88:91]
	v_mfma_f32_16x16x32_bf16 v[76:79], v[154:157], v[210:213], v[76:79]
	v_mfma_f32_16x16x32_bf16 v[72:75], v[162:165], v[210:213], v[72:75]
	v_mfma_f32_16x16x32_bf16 v[116:119], v[166:169], v[182:185], v[116:119]
	v_mfma_f32_16x16x32_bf16 v[112:115], v[174:177], v[182:185], v[112:115]
	v_mfma_f32_16x16x32_bf16 v[100:103], v[166:169], v[190:193], v[100:103]
	v_mfma_f32_16x16x32_bf16 v[96:99], v[174:177], v[190:193], v[96:99]
	v_mfma_f32_16x16x32_bf16 v[84:87], v[166:169], v[198:201], v[84:87]
	v_mfma_f32_16x16x32_bf16 v[80:83], v[174:177], v[198:201], v[80:83]
	v_mfma_f32_16x16x32_bf16 v[68:71], v[166:169], v[206:209], v[68:71]
	v_mfma_f32_16x16x32_bf16 v[64:67], v[174:177], v[206:209], v[64:67]
	v_mfma_f32_16x16x32_bf16 v[116:119], v[170:173], v[186:189], v[116:119]
	v_mfma_f32_16x16x32_bf16 v[112:115], v[178:181], v[186:189], v[112:115]
	v_mfma_f32_16x16x32_bf16 v[100:103], v[170:173], v[194:197], v[100:103]
	v_mfma_f32_16x16x32_bf16 v[96:99], v[178:181], v[194:197], v[96:99]
	v_mfma_f32_16x16x32_bf16 v[84:87], v[170:173], v[202:205], v[84:87]
	v_mfma_f32_16x16x32_bf16 v[80:83], v[178:181], v[202:205], v[80:83]
	v_mfma_f32_16x16x32_bf16 v[68:71], v[170:173], v[210:213], v[68:71]
	v_mfma_f32_16x16x32_bf16 v[64:67], v[178:181], v[210:213], v[64:67]
	s_barrier
	s_setprio 0
	s_add_i32 s34, s55, s5
	s_mov_b32 m0, s34
	ds_read_b128 v[182:185], v149 offset:49152
	ds_read_b128 v[186:189], v149 offset:50176
	ds_read_b128 v[190:193], v149 offset:51200
	ds_read_b128 v[194:197], v149 offset:52224
	ds_read_b128 v[198:201], v149 offset:53248
	ds_read_b128 v[202:205], v149 offset:54272
	ds_read_b128 v[206:209], v149 offset:55296
	ds_read_b128 v[210:213], v149 offset:56320
	global_load_lds_dwordx4 v132, s[98:99]
	s_add_i32 m0, s34, 0x2000
	s_add_u32 s30, s30, 0x40080
	s_addc_u32 s31, s31, 0
	s_add_i32 s34, s56, s5
	global_load_lds_dwordx4 v128, s[98:99]
	s_mov_b32 m0, s34
	s_nop 0
	global_load_lds_dwordx4 v132, s[30:31]
	s_add_i32 m0, s34, 0x2000
	s_nop 0
	global_load_lds_dwordx4 v128, s[30:31]
	s_waitcnt vmcnt(6)
	s_waitcnt lgkmcnt(0)
	s_setprio 1
	s_barrier
	v_mfma_f32_16x16x32_bf16 v[60:63], v[150:153], v[182:185], v[60:63]
	v_mfma_f32_16x16x32_bf16 v[56:59], v[158:161], v[182:185], v[56:59]
	v_mfma_f32_16x16x32_bf16 v[44:47], v[150:153], v[190:193], v[44:47]
	v_mfma_f32_16x16x32_bf16 v[40:43], v[158:161], v[190:193], v[40:43]
	v_mfma_f32_16x16x32_bf16 v[28:31], v[150:153], v[198:201], v[28:31]
	v_mfma_f32_16x16x32_bf16 v[24:27], v[158:161], v[198:201], v[24:27]
	v_mfma_f32_16x16x32_bf16 v[12:15], v[150:153], v[206:209], v[12:15]
	v_mfma_f32_16x16x32_bf16 v[8:11], v[158:161], v[206:209], v[8:11]
	v_mfma_f32_16x16x32_bf16 v[60:63], v[154:157], v[186:189], v[60:63]
	v_mfma_f32_16x16x32_bf16 v[56:59], v[162:165], v[186:189], v[56:59]
	v_mfma_f32_16x16x32_bf16 v[44:47], v[154:157], v[194:197], v[44:47]
	v_mfma_f32_16x16x32_bf16 v[40:43], v[162:165], v[194:197], v[40:43]
	v_mfma_f32_16x16x32_bf16 v[28:31], v[154:157], v[202:205], v[28:31]
	v_mfma_f32_16x16x32_bf16 v[24:27], v[162:165], v[202:205], v[24:27]
	v_mfma_f32_16x16x32_bf16 v[12:15], v[154:157], v[210:213], v[12:15]
	v_mfma_f32_16x16x32_bf16 v[8:11], v[162:165], v[210:213], v[8:11]
	v_mfma_f32_16x16x32_bf16 v[52:55], v[166:169], v[182:185], v[52:55]
	v_mfma_f32_16x16x32_bf16 v[48:51], v[174:177], v[182:185], v[48:51]
	v_mfma_f32_16x16x32_bf16 v[36:39], v[166:169], v[190:193], v[36:39]
	v_mfma_f32_16x16x32_bf16 v[32:35], v[174:177], v[190:193], v[32:35]
	v_mfma_f32_16x16x32_bf16 v[20:23], v[166:169], v[198:201], v[20:23]
	v_mfma_f32_16x16x32_bf16 v[16:19], v[174:177], v[198:201], v[16:19]
	v_mfma_f32_16x16x32_bf16 v[4:7], v[166:169], v[206:209], v[4:7]
	v_mfma_f32_16x16x32_bf16 v[0:3], v[174:177], v[206:209], v[0:3]
	v_mfma_f32_16x16x32_bf16 v[52:55], v[170:173], v[186:189], v[52:55]
	v_mfma_f32_16x16x32_bf16 v[48:51], v[178:181], v[186:189], v[48:51]
	v_mfma_f32_16x16x32_bf16 v[36:39], v[170:173], v[194:197], v[36:39]
	v_mfma_f32_16x16x32_bf16 v[32:35], v[178:181], v[194:197], v[32:35]
	v_mfma_f32_16x16x32_bf16 v[20:23], v[170:173], v[202:205], v[20:23]
	v_mfma_f32_16x16x32_bf16 v[16:19], v[178:181], v[202:205], v[16:19]
	v_mfma_f32_16x16x32_bf16 v[4:7], v[170:173], v[210:213], v[4:7]
	v_mfma_f32_16x16x32_bf16 v[0:3], v[178:181], v[210:213], v[0:3]
	s_barrier
	s_setprio 0
	s_add_u32 s28, s28, 0x100
	s_addc_u32 s29, s29, 0
	s_add_u32 s52, s52, 0x100
	s_addc_u32 s53, s53, 0
	s_cmp_ge_i32 s54, s42
	s_mov_b32 s30, s54
	s_cbranch_scc0 .LBB0_1112

; #define PG8_STAGE(bufoff, gbase, voff) do { _Pragma("unroll") for (int _i = 0; _i < 2; ++_i) \
;         __builtin_amdgcn_global_load_lds((const unsigned*)((const char*)(gbase) + (voff)[_i]), (LAS unsigned*)(lds + (bufoff) + ldsw + _i * 8192), 16, 0, ((voff) == voffA ? AUXA : 0)); } while (0)
; #define PG8_LDA(dst, b, h) do { _Pragma("unroll") for (int m = 0; m < 4; ++m) _Pragma("unroll") for (int k = 0; k < 2; ++k) dst[m][k] = *(const LAS bf16x8*)(lds + PG8_SA(b, h) + aoff + m * 2048 + k * 1024); } while (0)
; #define PG8_LDB(dst, b, h) do { _Pragma("unroll") for (int n = 0; n < 2; ++n) _Pragma("unroll") for (int k = 0; k < 2; ++k) dst[n][k] = *(const LAS bf16x8*)(lds + PG8_SB(b, h) + boff + n * 2048 + k * 1024); } while (0)
; #define PG8_WAIT_V(n) asm volatile("s_waitcnt vmcnt(" #n ")" ::: "memory")
; #define PG8_SCHED __builtin_amdgcn_sched_barrier(0)
;     ...
;             const char* a1 = cA + (size_t)(t + 1) * kstep;
;             const char* a2 = last ? nA : cA + (size_t)(t + 2) * kstep; const char* b2 = last ? nB : cB + (size_t)(t + 2) * kstep;
;             const char* a3 = a2 + kstep; const char* b3 = b2 + kstep;
;             PG8_LDB(B0, 0, 0); PG8_LDB(B1, 0, 1); PG8_SCHED; PG8_LDA(At, 0, 0); PG8_STAGE(PG8_SA(1, 1), a1 + hsA, voffA);
;             if (Epi::NPRE != 0 && last) { E.pre(sv, cur, wr, fr); PG8_WAIT_V(16); } else { PG8_WAIT_V(8); }
.LBB0_1185:
	s_add_u32 s98, s28, 0xfff80000
	s_mov_b32 m0, s52
	s_addc_u32 s99, s29, -1
	global_load_lds_dwordx4 v198, s[98:99]
	s_mov_b32 m0, s53
	s_nop 0
	global_load_lds_dwordx4 v194, s[98:99]
	ds_read_b128 v[144:147], v223
	ds_read_b128 v[148:151], v223 offset:1024
	ds_read_b128 v[152:155], v223 offset:2048
	ds_read_b128 v[156:159], v223 offset:3072
	ds_read_b128 v[128:131], v224
	ds_read_b128 v[132:135], v224 offset:1024
	ds_read_b128 v[136:139], v224 offset:2048
	ds_read_b128 v[140:143], v224 offset:3072
	s_cmp_eq_u32 s54, s62
	s_cselect_b64 s[30:31], -1, 0
	s_cmp_lg_u32 s54, s62
	s_cselect_b64 s[36:37], -1, 0
	s_add_i32 m0, s42, 0xc000
	ds_read_b128 v[184:187], v225
	ds_read_b128 v[188:191], v225 offset:1024
	ds_read_b128 v[176:179], v225 offset:2048
	ds_read_b128 v[180:183], v225 offset:3072
	ds_read_b128 v[168:171], v225 offset:4096
	ds_read_b128 v[172:175], v225 offset:5120
	ds_read_b128 v[160:163], v225 offset:6144
	ds_read_b128 v[164:167], v225 offset:7168
	global_load_lds_dwordx4 v200, s[28:29]
	s_add_i32 m0, s42, 0xe000
	s_mov_b64 s[34:35], -1
	global_load_lds_dwordx4 v202, s[28:29]
	s_and_b64 vcc, exec, s[36:37]
	s_cbranch_vccz .LBB0_1187
	s_waitcnt vmcnt(8)
	s_mov_b64 s[34:35], 0

; #define PG8_STAGE(bufoff, gbase, voff) do { _Pragma("unroll") for (int _i = 0; _i < 2; ++_i) \
;         __builtin_amdgcn_global_load_lds((const unsigned*)((const char*)(gbase) + (voff)[_i]), (LAS unsigned*)(lds + (bufoff) + ldsw + _i * 8192), 16, 0, ((voff) == voffA ? AUXA : 0)); } while (0)
; #define PG8_LDA(dst, b, h) do { _Pragma("unroll") for (int m = 0; m < 4; ++m) _Pragma("unroll") for (int k = 0; k < 2; ++k) dst[m][k] = *(const LAS bf16x8*)(lds + PG8_SA(b, h) + aoff + m * 2048 + k * 1024); } while (0)
; #define PG8_MMA(ai, bj, At, Bt) do { __builtin_amdgcn_s_setprio(1); _Pragma("unroll") for (int m = 0; m < 4; ++m) _Pragma("unroll") for (int n = 0; n < 2; ++n) _Pragma("unroll") for (int k = 0; k < 2; ++k) \
;         acc[ai][bj][m][n] = __builtin_amdgcn_mfma_f32_16x16x32_bf16(Bt[n][k], At[m][k], acc[ai][bj][m][n], 0, 0, 0); __builtin_amdgcn_s_setprio(0); } while (0)
; #define PG8_WAIT_V(n) asm volatile("s_waitcnt vmcnt(" #n ")" ::: "memory")
; #define PG8_WAIT_L(n) asm volatile("s_waitcnt lgkmcnt(" #n ")" ::: "memory")
; #define PG8_BAR __builtin_amdgcn_s_barrier()
; #define PG8_SCHED __builtin_amdgcn_sched_barrier(0)
;     ...
;             if (Epi::NPRE != 0 && last) { E.pre(sv, cur, wr, fr); PG8_WAIT_V(16); } else { PG8_WAIT_V(8); }
;             PG8_WAIT_L(0); PG8_BAR; PG8_MMA(0, 0, At, B0); PG8_MMA(0, 1, At, B1); PG8_BAR; PG8_SCHED;
;             PG8_LDA(At, 0, 1); PG8_STAGE(PG8_SB(0, 0), b2, voffB); PG8_STAGE(PG8_SB(0, 1), b2 + hsB, voffB); PG8_STAGE(PG8_SA(0, 0), a2, voffA);
;             if (Epi::NPRE != 0 && last) { PG8_WAIT_V(16); } else { PG8_WAIT_V(8); }
.LBB0_1189:
	s_add_u32 s34, s28, 0xfff80080
	s_addc_u32 s35, s29, -1
	s_waitcnt lgkmcnt(0)
	s_and_b64 s[30:31], s[30:31], exec
	s_cselect_b32 s35, s21, s35
	s_cselect_b32 s34, s23, s34
	s_cselect_b32 s31, s58, s61
	s_cselect_b32 s30, s59, s60
	s_setprio 1
	s_barrier
	v_mfma_f32_16x16x32_bf16 v[124:127], v[144:147], v[184:187], v[124:127]
	v_mfma_f32_16x16x32_bf16 v[116:119], v[152:155], v[184:187], v[116:119]
	v_mfma_f32_16x16x32_bf16 v[108:111], v[144:147], v[176:179], v[108:111]
	v_mfma_f32_16x16x32_bf16 v[100:103], v[152:155], v[176:179], v[100:103]
	v_mfma_f32_16x16x32_bf16 v[92:95], v[144:147], v[168:171], v[92:95]
	v_mfma_f32_16x16x32_bf16 v[84:87], v[152:155], v[168:171], v[84:87]
	v_mfma_f32_16x16x32_bf16 v[76:79], v[144:147], v[160:163], v[76:79]
	v_mfma_f32_16x16x32_bf16 v[68:71], v[152:155], v[160:163], v[68:71]
	v_mfma_f32_16x16x32_bf16 v[124:127], v[148:151], v[188:191], v[124:127]
	v_mfma_f32_16x16x32_bf16 v[116:119], v[156:159], v[188:191], v[116:119]
	v_mfma_f32_16x16x32_bf16 v[108:111], v[148:151], v[180:183], v[108:111]
	v_mfma_f32_16x16x32_bf16 v[100:103], v[156:159], v[180:183], v[100:103]
	v_mfma_f32_16x16x32_bf16 v[92:95], v[148:151], v[172:175], v[92:95]
	v_mfma_f32_16x16x32_bf16 v[84:87], v[156:159], v[172:175], v[84:87]
	v_mfma_f32_16x16x32_bf16 v[76:79], v[148:151], v[164:167], v[76:79]
	v_mfma_f32_16x16x32_bf16 v[68:71], v[156:159], v[164:167], v[68:71]
	v_mfma_f32_16x16x32_bf16 v[120:123], v[128:131], v[184:187], v[120:123]
	v_mfma_f32_16x16x32_bf16 v[112:115], v[136:139], v[184:187], v[112:115]
	v_mfma_f32_16x16x32_bf16 v[104:107], v[128:131], v[176:179], v[104:107]
	v_mfma_f32_16x16x32_bf16 v[96:99], v[136:139], v[176:179], v[96:99]
	v_mfma_f32_16x16x32_bf16 v[88:91], v[128:131], v[168:171], v[88:91]
	v_mfma_f32_16x16x32_bf16 v[80:83], v[136:139], v[168:171], v[80:83]
	v_mfma_f32_16x16x32_bf16 v[72:75], v[128:131], v[160:163], v[72:75]
	v_mfma_f32_16x16x32_bf16 v[64:67], v[136:139], v[160:163], v[64:67]
	v_mfma_f32_16x16x32_bf16 v[120:123], v[132:135], v[188:191], v[120:123]
	v_mfma_f32_16x16x32_bf16 v[112:115], v[140:143], v[188:191], v[112:115]
	v_mfma_f32_16x16x32_bf16 v[104:107], v[132:135], v[180:183], v[104:107]
	v_mfma_f32_16x16x32_bf16 v[96:99], v[140:143], v[180:183], v[96:99]
	v_mfma_f32_16x16x32_bf16 v[88:91], v[132:135], v[172:175], v[88:91]
	v_mfma_f32_16x16x32_bf16 v[80:83], v[140:143], v[172:175], v[80:83]
	v_mfma_f32_16x16x32_bf16 v[72:75], v[132:135], v[164:167], v[72:75]
	v_mfma_f32_16x16x32_bf16 v[64:67], v[140:143], v[164:167], v[64:67]
	s_barrier
	s_setprio 0
	s_add_u32 s98, s30, s16
	s_addc_u32 s99, s31, s17
	s_mov_b32 m0, s43
	s_add_u32 s38, s30, 0x80000
	ds_read_b128 v[184:187], v225 offset:16384
	ds_read_b128 v[188:191], v225 offset:17408
	ds_read_b128 v[176:179], v225 offset:18432
	ds_read_b128 v[180:183], v225 offset:19456
	ds_read_b128 v[168:171], v225 offset:20480
	ds_read_b128 v[172:175], v225 offset:21504
	ds_read_b128 v[160:163], v225 offset:22528
	ds_read_b128 v[164:167], v225 offset:23552
	global_load_lds_dwordx4 v196, s[30:31]
	s_mov_b32 m0, s44
	s_addc_u32 s39, s31, 0
	global_load_lds_dwordx4 v192, s[30:31]
	s_mov_b32 m0, s45
	s_nop 0
	global_load_lds_dwordx4 v196, s[38:39]
	s_mov_b32 m0, s46
	s_nop 0
	global_load_lds_dwordx4 v192, s[38:39]
	s_mov_b64 s[38:39], -1
	s_and_b64 vcc, exec, s[36:37]
	s_cbranch_vccz .LBB0_1191
	s_waitcnt vmcnt(6)
	s_mov_b64 s[38:39], 0

; #define PG8_STAGE(bufoff, gbase, voff) do { _Pragma("unroll") for (int _i = 0; _i < 2; ++_i) \
;         __builtin_amdgcn_global_load_lds((const unsigned*)((const char*)(gbase) + (voff)[_i]), (LAS unsigned*)(lds + (bufoff) + ldsw + _i * 8192), 16, 0, ((voff) == voffA ? AUXA : 0)); } while (0)
; #define PG8_LDA(dst, b, h) do { _Pragma("unroll") for (int m = 0; m < 4; ++m) _Pragma("unroll") for (int k = 0; k < 2; ++k) dst[m][k] = *(const LAS bf16x8*)(lds + PG8_SA(b, h) + aoff + m * 2048 + k * 1024); } while (0)
; #define PG8_LDB(dst, b, h) do { _Pragma("unroll") for (int n = 0; n < 2; ++n) _Pragma("unroll") for (int k = 0; k < 2; ++k) dst[n][k] = *(const LAS bf16x8*)(lds + PG8_SB(b, h) + boff + n * 2048 + k * 1024); } while (0)
; #define PG8_MMA(ai, bj, At, Bt) do { __builtin_amdgcn_s_setprio(1); _Pragma("unroll") for (int m = 0; m < 4; ++m) _Pragma("unroll") for (int n = 0; n < 2; ++n) _Pragma("unroll") for (int k = 0; k < 2; ++k) \
;         acc[ai][bj][m][n] = __builtin_amdgcn_mfma_f32_16x16x32_bf16(Bt[n][k], At[m][k], acc[ai][bj][m][n], 0, 0, 0); __builtin_amdgcn_s_setprio(0); } while (0)
; #define PG8_WAIT_V(n) asm volatile("s_waitcnt vmcnt(" #n ")" ::: "memory")
; #define PG8_WAIT_L(n) asm volatile("s_waitcnt lgkmcnt(" #n ")" ::: "memory")
; #define PG8_BAR __builtin_amdgcn_s_barrier()
; #define PG8_SCHED __builtin_amdgcn_sched_barrier(0)
;     ...
;             const bool last = (t == nt - 2);
;             const char* a1 = cA + (size_t)(t + 1) * kstep;
;             const char* a2 = last ? nA : cA + (size_t)(t + 2) * kstep; const char* b2 = last ? nB : cB + (size_t)(t + 2) * kstep;
;             const char* a3 = a2 + kstep; const char* b3 = b2 + kstep;
;             PG8_LDB(B0, 0, 0); PG8_LDB(B1, 0, 1); PG8_SCHED; PG8_LDA(At, 0, 0); PG8_STAGE(PG8_SA(1, 1), a1 + hsA, voffA);
;             if (Epi::NPRE != 0 && last) { E.pre(sv, cur, wr, fr); PG8_WAIT_V(16); } else { PG8_WAIT_V(8); }
;             PG8_WAIT_L(0); PG8_BAR; PG8_MMA(0, 0, At, B0); PG8_MMA(0, 1, At, B1); PG8_BAR; PG8_SCHED;
;             PG8_LDA(At, 0, 1); PG8_STAGE(PG8_SB(0, 0), b2, voffB); PG8_STAGE(PG8_SB(0, 1), b2 + hsB, voffB); PG8_STAGE(PG8_SA(0, 0), a2, voffA);
;             if (Epi::NPRE != 0 && last) { PG8_WAIT_V(16); } else { PG8_WAIT_V(8); }
;             PG8_WAIT_L(0); PG8_BAR; PG8_MMA(1, 0, At, B0); PG8_MMA(1, 1, At, B1); PG8_BAR; PG8_SCHED;
.LBB0_1267:
	s_add_u32 s98, s34, 0xfff80000
	s_mov_b32 m0, s47
	s_addc_u32 s99, s35, -1
	global_load_lds_dwordx4 v152, s[98:99]
	s_mov_b32 m0, s48
	s_nop 0
	global_load_lds_dwordx4 v156, s[98:99]
	ds_read_b128 v[128:131], v189
	ds_read_b128 v[132:135], v189 offset:1024
	ds_read_b128 v[136:139], v189 offset:2048
	ds_read_b128 v[140:143], v189 offset:3072
	ds_read_b128 v[144:147], v190
	ds_read_b128 v[148:151], v190 offset:1024
	ds_read_b128 v[168:171], v190 offset:2048
	ds_read_b128 v[172:175], v190 offset:3072
	s_add_i32 s58, s36, 2
	s_add_u32 s37, s34, 0xfff80080
	s_addc_u32 s38, s35, -1
	s_cmp_eq_u32 s49, s36
	s_cselect_b32 s36, s55, s56
	s_cselect_b32 s39, s21, s38
	s_cselect_b32 s38, s23, s37
	s_cselect_b32 s37, s29, s57
	s_add_i32 m0, s31, 0xc000
	ds_read_b128 v[176:179], v191
	ds_read_b128 v[180:183], v191 offset:1024
	ds_read_b128 v[194:197], v191 offset:2048
	ds_read_b128 v[198:201], v191 offset:3072
	ds_read_b128 v[202:205], v191 offset:4096
	ds_read_b128 v[206:209], v191 offset:5120
	ds_read_b128 v[210:213], v191 offset:6144
	ds_read_b128 v[214:217], v191 offset:7168
	global_load_lds_dwordx4 v160, s[34:35]
	s_add_i32 m0, s31, 0xe000
	s_nop 0
	global_load_lds_dwordx4 v162, s[34:35]
	s_waitcnt vmcnt(8)
	s_waitcnt lgkmcnt(0)
	s_setprio 1
	s_barrier
	v_mfma_f32_16x16x32_bf16 v[124:127], v[128:131], v[176:179], v[124:127]
	v_mfma_f32_16x16x32_bf16 v[120:123], v[136:139], v[176:179], v[120:123]
	v_mfma_f32_16x16x32_bf16 v[108:111], v[128:131], v[194:197], v[108:111]
	v_mfma_f32_16x16x32_bf16 v[104:107], v[136:139], v[194:197], v[104:107]
	v_mfma_f32_16x16x32_bf16 v[92:95], v[128:131], v[202:205], v[92:95]
	v_mfma_f32_16x16x32_bf16 v[88:91], v[136:139], v[202:205], v[88:91]
	v_mfma_f32_16x16x32_bf16 v[76:79], v[128:131], v[210:213], v[76:79]
	v_mfma_f32_16x16x32_bf16 v[72:75], v[136:139], v[210:213], v[72:75]
	v_mfma_f32_16x16x32_bf16 v[124:127], v[132:135], v[180:183], v[124:127]
	v_mfma_f32_16x16x32_bf16 v[120:123], v[140:143], v[180:183], v[120:123]
	v_mfma_f32_16x16x32_bf16 v[108:111], v[132:135], v[198:201], v[108:111]
	v_mfma_f32_16x16x32_bf16 v[104:107], v[140:143], v[198:201], v[104:107]
	v_mfma_f32_16x16x32_bf16 v[92:95], v[132:135], v[206:209], v[92:95]
	v_mfma_f32_16x16x32_bf16 v[88:91], v[140:143], v[206:209], v[88:91]
	v_mfma_f32_16x16x32_bf16 v[76:79], v[132:135], v[214:217], v[76:79]
	v_mfma_f32_16x16x32_bf16 v[72:75], v[140:143], v[214:217], v[72:75]
	v_mfma_f32_16x16x32_bf16 v[116:119], v[144:147], v[176:179], v[116:119]
	v_mfma_f32_16x16x32_bf16 v[112:115], v[168:171], v[176:179], v[112:115]
	v_mfma_f32_16x16x32_bf16 v[100:103], v[144:147], v[194:197], v[100:103]
	v_mfma_f32_16x16x32_bf16 v[96:99], v[168:171], v[194:197], v[96:99]
	v_mfma_f32_16x16x32_bf16 v[84:87], v[144:147], v[202:205], v[84:87]
	v_mfma_f32_16x16x32_bf16 v[80:83], v[168:171], v[202:205], v[80:83]
	v_mfma_f32_16x16x32_bf16 v[68:71], v[144:147], v[210:213], v[68:71]
	v_mfma_f32_16x16x32_bf16 v[64:67], v[168:171], v[210:213], v[64:67]
	v_mfma_f32_16x16x32_bf16 v[116:119], v[148:151], v[180:183], v[116:119]
	v_mfma_f32_16x16x32_bf16 v[112:115], v[172:175], v[180:183], v[112:115]
	v_mfma_f32_16x16x32_bf16 v[100:103], v[148:151], v[198:201], v[100:103]
	v_mfma_f32_16x16x32_bf16 v[96:99], v[172:175], v[198:201], v[96:99]
	v_mfma_f32_16x16x32_bf16 v[84:87], v[148:151], v[206:209], v[84:87]
	v_mfma_f32_16x16x32_bf16 v[80:83], v[172:175], v[206:209], v[80:83]
	v_mfma_f32_16x16x32_bf16 v[68:71], v[148:151], v[214:217], v[68:71]
	v_mfma_f32_16x16x32_bf16 v[64:67], v[172:175], v[214:217], v[64:67]
	s_barrier
	s_setprio 0
	s_add_u32 s98, s36, s16
	s_addc_u32 s99, s37, s17
	s_add_i32 s59, s53, s41
	s_mov_b32 m0, s59
	ds_read_b128 v[176:179], v191 offset:16384
	ds_read_b128 v[180:183], v191 offset:17408
	ds_read_b128 v[194:197], v191 offset:18432
	ds_read_b128 v[198:201], v191 offset:19456
	ds_read_b128 v[202:205], v191 offset:20480
	ds_read_b128 v[206:209], v191 offset:21504
	ds_read_b128 v[210:213], v191 offset:22528
	ds_read_b128 v[214:217], v191 offset:23552
	global_load_lds_dwordx4 v154, s[36:37]
	s_add_i32 m0, s59, 0x2000
	s_add_u32 s60, s36, 0x80000
	s_addc_u32 s61, s37, 0
	s_add_i32 s59, s54, s41
	global_load_lds_dwordx4 v158, s[36:37]
	s_mov_b32 m0, s59
	s_nop 0
	global_load_lds_dwordx4 v154, s[60:61]
	s_add_i32 m0, s59, 0x2000
	s_nop 0
	global_load_lds_dwordx4 v158, s[60:61]
	s_waitcnt vmcnt(6)
	s_waitcnt lgkmcnt(0)
	s_setprio 1
	s_barrier
	v_mfma_f32_16x16x32_bf16 v[60:63], v[128:131], v[176:179], v[60:63]
	v_mfma_f32_16x16x32_bf16 v[56:59], v[136:139], v[176:179], v[56:59]
	v_mfma_f32_16x16x32_bf16 v[44:47], v[128:131], v[194:197], v[44:47]
	v_mfma_f32_16x16x32_bf16 v[40:43], v[136:139], v[194:197], v[40:43]
	v_mfma_f32_16x16x32_bf16 v[28:31], v[128:131], v[202:205], v[28:31]
	v_mfma_f32_16x16x32_bf16 v[24:27], v[136:139], v[202:205], v[24:27]
	v_mfma_f32_16x16x32_bf16 v[12:15], v[128:131], v[210:213], v[12:15]
	v_mfma_f32_16x16x32_bf16 v[8:11], v[136:139], v[210:213], v[8:11]
	v_mfma_f32_16x16x32_bf16 v[60:63], v[132:135], v[180:183], v[60:63]
	v_mfma_f32_16x16x32_bf16 v[56:59], v[140:143], v[180:183], v[56:59]
	v_mfma_f32_16x16x32_bf16 v[44:47], v[132:135], v[198:201], v[44:47]
	v_mfma_f32_16x16x32_bf16 v[40:43], v[140:143], v[198:201], v[40:43]
	v_mfma_f32_16x16x32_bf16 v[28:31], v[132:135], v[206:209], v[28:31]
	v_mfma_f32_16x16x32_bf16 v[24:27], v[140:143], v[206:209], v[24:27]
	v_mfma_f32_16x16x32_bf16 v[12:15], v[132:135], v[214:217], v[12:15]
	v_mfma_f32_16x16x32_bf16 v[8:11], v[140:143], v[214:217], v[8:11]
	v_mfma_f32_16x16x32_bf16 v[52:55], v[144:147], v[176:179], v[52:55]
	v_mfma_f32_16x16x32_bf16 v[48:51], v[168:171], v[176:179], v[48:51]
	v_mfma_f32_16x16x32_bf16 v[36:39], v[144:147], v[194:197], v[36:39]
	v_mfma_f32_16x16x32_bf16 v[32:35], v[168:171], v[194:197], v[32:35]
	v_mfma_f32_16x16x32_bf16 v[20:23], v[144:147], v[202:205], v[20:23]
	v_mfma_f32_16x16x32_bf16 v[16:19], v[168:171], v[202:205], v[16:19]
	v_mfma_f32_16x16x32_bf16 v[4:7], v[144:147], v[210:213], v[4:7]
	v_mfma_f32_16x16x32_bf16 v[0:3], v[168:171], v[210:213], v[0:3]
	v_mfma_f32_16x16x32_bf16 v[52:55], v[148:151], v[180:183], v[52:55]
	v_mfma_f32_16x16x32_bf16 v[48:51], v[172:175], v[180:183], v[48:51]
	v_mfma_f32_16x16x32_bf16 v[36:39], v[148:151], v[198:201], v[36:39]
	v_mfma_f32_16x16x32_bf16 v[32:35], v[172:175], v[198:201], v[32:35]
	v_mfma_f32_16x16x32_bf16 v[20:23], v[148:151], v[206:209], v[20:23]
	v_mfma_f32_16x16x32_bf16 v[16:19], v[172:175], v[206:209], v[16:19]
	v_mfma_f32_16x16x32_bf16 v[4:7], v[148:151], v[214:217], v[4:7]
	v_mfma_f32_16x16x32_bf16 v[0:3], v[172:175], v[214:217], v[0:3]
	s_barrier
; #define PG8_STAGE(bufoff, gbase, voff) do { _Pragma("unroll") for (int _i = 0; _i < 2; ++_i) \
;         __builtin_amdgcn_global_load_lds((const unsigned*)((const char*)(gbase) + (voff)[_i]), (LAS unsigned*)(lds + (bufoff) + ldsw + _i * 8192), 16, 0, ((voff) == voffA ? AUXA : 0)); } while (0)
; #define PG8_LDA(dst, b, h) do { _Pragma("unroll") for (int m = 0; m < 4; ++m) _Pragma("unroll") for (int k = 0; k < 2; ++k) dst[m][k] = *(const LAS bf16x8*)(lds + PG8_SA(b, h) + aoff + m * 2048 + k * 1024); } while (0)
; #define PG8_LDB(dst, b, h) do { _Pragma("unroll") for (int n = 0; n < 2; ++n) _Pragma("unroll") for (int k = 0; k < 2; ++k) dst[n][k] = *(const LAS bf16x8*)(lds + PG8_SB(b, h) + boff + n * 2048 + k * 1024); } while (0)
; #define PG8_MMA(ai, bj, At, Bt) do { __builtin_amdgcn_s_setprio(1); _Pragma("unroll") for (int m = 0; m < 4; ++m) _Pragma("unroll") for (int n = 0; n < 2; ++n) _Pragma("unroll") for (int k = 0; k < 2; ++k) \
;         acc[ai][bj][m][n] = __builtin_amdgcn_mfma_f32_16x16x32_bf16(Bt[n][k], At[m][k], acc[ai][bj][m][n], 0, 0, 0); __builtin_amdgcn_s_setprio(0); } while (0)
; #define PG8_WAIT_V(n) asm volatile("s_waitcnt vmcnt(" #n ")" ::: "memory")
; #define PG8_WAIT_L(n) asm volatile("s_waitcnt lgkmcnt(" #n ")" ::: "memory")
; #define PG8_BAR __builtin_amdgcn_s_barrier()
; #define PG8_SCHED __builtin_amdgcn_sched_barrier(0)
;     ...
;             PG8_LDB(B0, 1, 0); PG8_LDB(B1, 1, 1); PG8_SCHED; PG8_LDA(At, 1, 0); PG8_STAGE(PG8_SA(0, 1), a2 + hsA, voffA);
;             PG8_WAIT_V(8); PG8_WAIT_L(0); PG8_BAR; PG8_MMA(0, 0, At, B0); PG8_MMA(0, 1, At, B1); PG8_BAR; PG8_SCHED;
;             PG8_LDA(At, 1, 1); PG8_STAGE(PG8_SB(1, 0), b3, voffB); PG8_STAGE(PG8_SB(1, 1), b3 + hsB, voffB); PG8_STAGE(PG8_SA(1, 0), a3, voffA);
;             PG8_WAIT_V(8); PG8_WAIT_L(0); PG8_BAR; PG8_MMA(1, 0, At, B0); PG8_MMA(1, 1, At, B1); PG8_BAR; PG8_SCHED;
;         }
	s_mov_b32 m0, s31
	s_nop 0
	global_load_lds_dwordx4 v152, s[38:39]
	s_mov_b32 m0, s42
	s_nop 0
	global_load_lds_dwordx4 v156, s[38:39]
	s_setprio 0
	s_add_i32 s59, 0, 0x18000
	s_add_i32 s60, 0, 0x1c000
	v_add_u32_e32 v140, s59, v187
	v_add_u32_e32 v172, s60, v187
	ds_read_b128 v[128:131], v140
	ds_read_b128 v[132:135], v140 offset:1024
	ds_read_b128 v[136:139], v140 offset:2048
	ds_read_b128 v[140:143], v140 offset:3072
	ds_read_b128 v[144:147], v172
	ds_read_b128 v[148:151], v172 offset:1024
	ds_read_b128 v[168:171], v172 offset:2048
	ds_read_b128 v[172:175], v172 offset:3072
	s_add_u32 s38, s38, 0x80000
	s_addc_u32 s39, s39, 0
	s_mov_b32 m0, s43
	ds_read_b128 v[176:179], v191 offset:32768
	ds_read_b128 v[180:183], v191 offset:33792
	ds_read_b128 v[194:197], v191 offset:34816
	ds_read_b128 v[198:201], v191 offset:35840
	ds_read_b128 v[202:205], v191 offset:36864
	ds_read_b128 v[206:209], v191 offset:37888
	ds_read_b128 v[210:213], v191 offset:38912
	ds_read_b128 v[214:217], v191 offset:39936
	global_load_lds_dwordx4 v152, s[38:39]
	s_mov_b32 m0, s44
	s_nop 0
	global_load_lds_dwordx4 v156, s[38:39]
	s_waitcnt vmcnt(8)
	s_waitcnt lgkmcnt(0)
	s_setprio 1
	s_barrier
	v_mfma_f32_16x16x32_bf16 v[124:127], v[128:131], v[176:179], v[124:127]
	v_mfma_f32_16x16x32_bf16 v[120:123], v[136:139], v[176:179], v[120:123]
	v_mfma_f32_16x16x32_bf16 v[108:111], v[128:131], v[194:197], v[108:111]
	v_mfma_f32_16x16x32_bf16 v[104:107], v[136:139], v[194:197], v[104:107]
	v_mfma_f32_16x16x32_bf16 v[92:95], v[128:131], v[202:205], v[92:95]
	v_mfma_f32_16x16x32_bf16 v[88:91], v[136:139], v[202:205], v[88:91]
	v_mfma_f32_16x16x32_bf16 v[76:79], v[128:131], v[210:213], v[76:79]
	v_mfma_f32_16x16x32_bf16 v[72:75], v[136:139], v[210:213], v[72:75]
	v_mfma_f32_16x16x32_bf16 v[124:127], v[132:135], v[180:183], v[124:127]
	v_mfma_f32_16x16x32_bf16 v[120:123], v[140:143], v[180:183], v[120:123]
	v_mfma_f32_16x16x32_bf16 v[108:111], v[132:135], v[198:201], v[108:111]
	v_mfma_f32_16x16x32_bf16 v[104:107], v[140:143], v[198:201], v[104:107]
	v_mfma_f32_16x16x32_bf16 v[92:95], v[132:135], v[206:209], v[92:95]
	v_mfma_f32_16x16x32_bf16 v[88:91], v[140:143], v[206:209], v[88:91]
	v_mfma_f32_16x16x32_bf16 v[76:79], v[132:135], v[214:217], v[76:79]
	v_mfma_f32_16x16x32_bf16 v[72:75], v[140:143], v[214:217], v[72:75]
	v_mfma_f32_16x16x32_bf16 v[116:119], v[144:147], v[176:179], v[116:119]
	v_mfma_f32_16x16x32_bf16 v[112:115], v[168:171], v[176:179], v[112:115]
	v_mfma_f32_16x16x32_bf16 v[100:103], v[144:147], v[194:197], v[100:103]
	v_mfma_f32_16x16x32_bf16 v[96:99], v[168:171], v[194:197], v[96:99]
	v_mfma_f32_16x16x32_bf16 v[84:87], v[144:147], v[202:205], v[84:87]
	v_mfma_f32_16x16x32_bf16 v[80:83], v[168:171], v[202:205], v[80:83]
	v_mfma_f32_16x16x32_bf16 v[68:71], v[144:147], v[210:213], v[68:71]
	v_mfma_f32_16x16x32_bf16 v[64:67], v[168:171], v[210:213], v[64:67]
	v_mfma_f32_16x16x32_bf16 v[116:119], v[148:151], v[180:183], v[116:119]
	v_mfma_f32_16x16x32_bf16 v[112:115], v[172:175], v[180:183], v[112:115]
	v_mfma_f32_16x16x32_bf16 v[100:103], v[148:151], v[198:201], v[100:103]
	v_mfma_f32_16x16x32_bf16 v[96:99], v[172:175], v[198:201], v[96:99]
	v_mfma_f32_16x16x32_bf16 v[84:87], v[148:151], v[206:209], v[84:87]
	v_mfma_f32_16x16x32_bf16 v[80:83], v[172:175], v[206:209], v[80:83]
	v_mfma_f32_16x16x32_bf16 v[68:71], v[148:151], v[214:217], v[68:71]
	v_mfma_f32_16x16x32_bf16 v[64:67], v[172:175], v[214:217], v[64:67]
	s_barrier
	s_setprio 0
	s_add_i32 s38, s59, s41
	s_mov_b32 m0, s38
	ds_read_b128 v[176:179], v191 offset:49152
	ds_read_b128 v[180:183], v191 offset:50176
	ds_read_b128 v[194:197], v191 offset:51200
	ds_read_b128 v[198:201], v191 offset:52224
	ds_read_b128 v[202:205], v191 offset:53248
	ds_read_b128 v[206:209], v191 offset:54272
	ds_read_b128 v[210:213], v191 offset:55296
	ds_read_b128 v[214:217], v191 offset:56320
	global_load_lds_dwordx4 v154, s[98:99]
	s_add_i32 m0, s38, 0x2000
	s_add_u32 s36, s36, 0x80080
	s_addc_u32 s37, s37, 0
	s_add_i32 s38, s60, s41
	global_load_lds_dwordx4 v158, s[98:99]
	s_mov_b32 m0, s38
	s_nop 0
	global_load_lds_dwordx4 v154, s[36:37]
	s_add_i32 m0, s38, 0x2000
	s_nop 0
	global_load_lds_dwordx4 v158, s[36:37]
	s_waitcnt vmcnt(6)
	s_waitcnt lgkmcnt(0)
	s_setprio 1
	s_barrier
	v_mfma_f32_16x16x32_bf16 v[60:63], v[128:131], v[176:179], v[60:63]
	v_mfma_f32_16x16x32_bf16 v[56:59], v[136:139], v[176:179], v[56:59]
	v_mfma_f32_16x16x32_bf16 v[44:47], v[128:131], v[194:197], v[44:47]
	v_mfma_f32_16x16x32_bf16 v[40:43], v[136:139], v[194:197], v[40:43]
	v_mfma_f32_16x16x32_bf16 v[28:31], v[128:131], v[202:205], v[28:31]
	v_mfma_f32_16x16x32_bf16 v[24:27], v[136:139], v[202:205], v[24:27]
	v_mfma_f32_16x16x32_bf16 v[12:15], v[128:131], v[210:213], v[12:15]
	v_mfma_f32_16x16x32_bf16 v[8:11], v[136:139], v[210:213], v[8:11]
	v_mfma_f32_16x16x32_bf16 v[60:63], v[132:135], v[180:183], v[60:63]
	v_mfma_f32_16x16x32_bf16 v[56:59], v[140:143], v[180:183], v[56:59]
	v_mfma_f32_16x16x32_bf16 v[44:47], v[132:135], v[198:201], v[44:47]
	v_mfma_f32_16x16x32_bf16 v[40:43], v[140:143], v[198:201], v[40:43]
	v_mfma_f32_16x16x32_bf16 v[28:31], v[132:135], v[206:209], v[28:31]
	v_mfma_f32_16x16x32_bf16 v[24:27], v[140:143], v[206:209], v[24:27]
	v_mfma_f32_16x16x32_bf16 v[12:15], v[132:135], v[214:217], v[12:15]
	v_mfma_f32_16x16x32_bf16 v[8:11], v[140:143], v[214:217], v[8:11]
	v_mfma_f32_16x16x32_bf16 v[52:55], v[144:147], v[176:179], v[52:55]
	v_mfma_f32_16x16x32_bf16 v[48:51], v[168:171], v[176:179], v[48:51]
	v_mfma_f32_16x16x32_bf16 v[36:39], v[144:147], v[194:197], v[36:39]
	v_mfma_f32_16x16x32_bf16 v[32:35], v[168:171], v[194:197], v[32:35]
	v_mfma_f32_16x16x32_bf16 v[20:23], v[144:147], v[202:205], v[20:23]
	v_mfma_f32_16x16x32_bf16 v[16:19], v[168:171], v[202:205], v[16:19]
	v_mfma_f32_16x16x32_bf16 v[4:7], v[144:147], v[210:213], v[4:7]
	v_mfma_f32_16x16x32_bf16 v[0:3], v[168:171], v[210:213], v[0:3]
	v_mfma_f32_16x16x32_bf16 v[52:55], v[148:151], v[180:183], v[52:55]
	v_mfma_f32_16x16x32_bf16 v[48:51], v[172:175], v[180:183], v[48:51]
	v_mfma_f32_16x16x32_bf16 v[36:39], v[148:151], v[198:201], v[36:39]
	v_mfma_f32_16x16x32_bf16 v[32:35], v[172:175], v[198:201], v[32:35]
	v_mfma_f32_16x16x32_bf16 v[20:23], v[148:151], v[206:209], v[20:23]
	v_mfma_f32_16x16x32_bf16 v[16:19], v[172:175], v[206:209], v[16:19]
	v_mfma_f32_16x16x32_bf16 v[4:7], v[148:151], v[214:217], v[4:7]
	v_mfma_f32_16x16x32_bf16 v[0:3], v[172:175], v[214:217], v[0:3]
	s_barrier
	s_setprio 0
	s_add_u32 s34, s34, 0x100
	s_addc_u32 s35, s35, 0
	s_add_u32 s56, s56, 0x100
	s_addc_u32 s57, s57, 0
	s_cmp_ge_i32 s58, s46
	s_mov_b32 s36, s58
	s_cbranch_scc0 .LBB0_1267

; #define PG8_STAGE(bufoff, gbase, voff) do { _Pragma("unroll") for (int _i = 0; _i < 2; ++_i) \
;         __builtin_amdgcn_global_load_lds((const unsigned*)((const char*)(gbase) + (voff)[_i]), (LAS unsigned*)(lds + (bufoff) + ldsw + _i * 8192), 16, 0, ((voff) == voffA ? AUXA : 0)); } while (0)
; #define PG8_LDA(dst, b, h) do { _Pragma("unroll") for (int m = 0; m < 4; ++m) _Pragma("unroll") for (int k = 0; k < 2; ++k) dst[m][k] = *(const LAS bf16x8*)(lds + PG8_SA(b, h) + aoff + m * 2048 + k * 1024); } while (0)
; #define PG8_LDB(dst, b, h) do { _Pragma("unroll") for (int n = 0; n < 2; ++n) _Pragma("unroll") for (int k = 0; k < 2; ++k) dst[n][k] = *(const LAS bf16x8*)(lds + PG8_SB(b, h) + boff + n * 2048 + k * 1024); } while (0)
; #define PG8_WAIT_V(n) asm volatile("s_waitcnt vmcnt(" #n ")" ::: "memory")
; #define PG8_SCHED __builtin_amdgcn_sched_barrier(0)
;     ...
;             const char* a1 = cA + (size_t)(t + 1) * kstep;
;             const char* a2 = last ? nA : cA + (size_t)(t + 2) * kstep; const char* b2 = last ? nB : cB + (size_t)(t + 2) * kstep;
;             const char* a3 = a2 + kstep; const char* b3 = b2 + kstep;
;             PG8_LDB(B0, 0, 0); PG8_LDB(B1, 0, 1); PG8_SCHED; PG8_LDA(At, 0, 0); PG8_STAGE(PG8_SA(1, 1), a1 + hsA, voffA);
;             if (Epi::NPRE != 0 && last) { E.pre(sv, cur, wr, fr); PG8_WAIT_V(16); } else { PG8_WAIT_V(8); }
.LBB0_1356:
	s_add_u32 s98, s26, 0xfff80000
	s_mov_b32 m0, s50
	s_addc_u32 s99, s27, -1
	global_load_lds_dwordx4 v198, s[98:99]
	s_mov_b32 m0, s51
	s_nop 0
	global_load_lds_dwordx4 v194, s[98:99]
	ds_read_b128 v[144:147], v223
	ds_read_b128 v[148:151], v223 offset:1024
	ds_read_b128 v[152:155], v223 offset:2048
	ds_read_b128 v[156:159], v223 offset:3072
	ds_read_b128 v[128:131], v224
	ds_read_b128 v[132:135], v224 offset:1024
	ds_read_b128 v[136:139], v224 offset:2048
	ds_read_b128 v[140:143], v224 offset:3072
	s_cmp_eq_u32 s52, s61
	s_cselect_b64 s[28:29], -1, 0
	s_cmp_lg_u32 s52, s61
	s_cselect_b64 s[34:35], -1, 0
	s_add_i32 m0, s40, 0xc000
	ds_read_b128 v[184:187], v225
	ds_read_b128 v[188:191], v225 offset:1024
	ds_read_b128 v[176:179], v225 offset:2048
	ds_read_b128 v[180:183], v225 offset:3072
	ds_read_b128 v[168:171], v225 offset:4096
	ds_read_b128 v[172:175], v225 offset:5120
	ds_read_b128 v[160:163], v225 offset:6144
	ds_read_b128 v[164:167], v225 offset:7168
	global_load_lds_dwordx4 v200, s[26:27]
	s_add_i32 m0, s40, 0xe000
	s_mov_b64 s[30:31], -1
	global_load_lds_dwordx4 v202, s[26:27]
	s_and_b64 vcc, exec, s[34:35]
	s_cbranch_vccz .LBB0_1358
	s_waitcnt vmcnt(8)
	s_mov_b64 s[30:31], 0

; #define PG8_STAGE(bufoff, gbase, voff) do { _Pragma("unroll") for (int _i = 0; _i < 2; ++_i) \
;         __builtin_amdgcn_global_load_lds((const unsigned*)((const char*)(gbase) + (voff)[_i]), (LAS unsigned*)(lds + (bufoff) + ldsw + _i * 8192), 16, 0, ((voff) == voffA ? AUXA : 0)); } while (0)
; #define PG8_LDA(dst, b, h) do { _Pragma("unroll") for (int m = 0; m < 4; ++m) _Pragma("unroll") for (int k = 0; k < 2; ++k) dst[m][k] = *(const LAS bf16x8*)(lds + PG8_SA(b, h) + aoff + m * 2048 + k * 1024); } while (0)
; #define PG8_MMA(ai, bj, At, Bt) do { __builtin_amdgcn_s_setprio(1); _Pragma("unroll") for (int m = 0; m < 4; ++m) _Pragma("unroll") for (int n = 0; n < 2; ++n) _Pragma("unroll") for (int k = 0; k < 2; ++k) \
;         acc[ai][bj][m][n] = __builtin_amdgcn_mfma_f32_16x16x32_bf16(Bt[n][k], At[m][k], acc[ai][bj][m][n], 0, 0, 0); __builtin_amdgcn_s_setprio(0); } while (0)
; #define PG8_WAIT_V(n) asm volatile("s_waitcnt vmcnt(" #n ")" ::: "memory")
; #define PG8_WAIT_L(n) asm volatile("s_waitcnt lgkmcnt(" #n ")" ::: "memory")
; #define PG8_BAR __builtin_amdgcn_s_barrier()
; #define PG8_SCHED __builtin_amdgcn_sched_barrier(0)
;     ...
;             if (Epi::NPRE != 0 && last) { E.pre(sv, cur, wr, fr); PG8_WAIT_V(16); } else { PG8_WAIT_V(8); }
;             PG8_WAIT_L(0); PG8_BAR; PG8_MMA(0, 0, At, B0); PG8_MMA(0, 1, At, B1); PG8_BAR; PG8_SCHED;
;             PG8_LDA(At, 0, 1); PG8_STAGE(PG8_SB(0, 0), b2, voffB); PG8_STAGE(PG8_SB(0, 1), b2 + hsB, voffB); PG8_STAGE(PG8_SA(0, 0), a2, voffA);
;             if (Epi::NPRE != 0 && last) { PG8_WAIT_V(16); } else { PG8_WAIT_V(8); }
.LBB0_1360:
	s_add_u32 s30, s26, 0xfff80080
	s_addc_u32 s31, s27, -1
	s_waitcnt lgkmcnt(0)
	s_and_b64 s[28:29], s[28:29], exec
	s_cselect_b32 s31, s19, s31
	s_cselect_b32 s30, s21, s30
	s_cselect_b32 s29, s57, s60
	s_cselect_b32 s28, s58, s59
	s_setprio 1
	s_barrier
	v_mfma_f32_16x16x32_bf16 v[124:127], v[144:147], v[184:187], v[124:127]
	v_mfma_f32_16x16x32_bf16 v[116:119], v[152:155], v[184:187], v[116:119]
	v_mfma_f32_16x16x32_bf16 v[108:111], v[144:147], v[176:179], v[108:111]
	v_mfma_f32_16x16x32_bf16 v[100:103], v[152:155], v[176:179], v[100:103]
	v_mfma_f32_16x16x32_bf16 v[92:95], v[144:147], v[168:171], v[92:95]
	v_mfma_f32_16x16x32_bf16 v[84:87], v[152:155], v[168:171], v[84:87]
	v_mfma_f32_16x16x32_bf16 v[76:79], v[144:147], v[160:163], v[76:79]
	v_mfma_f32_16x16x32_bf16 v[68:71], v[152:155], v[160:163], v[68:71]
	v_mfma_f32_16x16x32_bf16 v[124:127], v[148:151], v[188:191], v[124:127]
	v_mfma_f32_16x16x32_bf16 v[116:119], v[156:159], v[188:191], v[116:119]
	v_mfma_f32_16x16x32_bf16 v[108:111], v[148:151], v[180:183], v[108:111]
	v_mfma_f32_16x16x32_bf16 v[100:103], v[156:159], v[180:183], v[100:103]
	v_mfma_f32_16x16x32_bf16 v[92:95], v[148:151], v[172:175], v[92:95]
	v_mfma_f32_16x16x32_bf16 v[84:87], v[156:159], v[172:175], v[84:87]
	v_mfma_f32_16x16x32_bf16 v[76:79], v[148:151], v[164:167], v[76:79]
	v_mfma_f32_16x16x32_bf16 v[68:71], v[156:159], v[164:167], v[68:71]
	v_mfma_f32_16x16x32_bf16 v[120:123], v[128:131], v[184:187], v[120:123]
	v_mfma_f32_16x16x32_bf16 v[112:115], v[136:139], v[184:187], v[112:115]
	v_mfma_f32_16x16x32_bf16 v[104:107], v[128:131], v[176:179], v[104:107]
	v_mfma_f32_16x16x32_bf16 v[96:99], v[136:139], v[176:179], v[96:99]
	v_mfma_f32_16x16x32_bf16 v[88:91], v[128:131], v[168:171], v[88:91]
	v_mfma_f32_16x16x32_bf16 v[80:83], v[136:139], v[168:171], v[80:83]
	v_mfma_f32_16x16x32_bf16 v[72:75], v[128:131], v[160:163], v[72:75]
	v_mfma_f32_16x16x32_bf16 v[64:67], v[136:139], v[160:163], v[64:67]
	v_mfma_f32_16x16x32_bf16 v[120:123], v[132:135], v[188:191], v[120:123]
	v_mfma_f32_16x16x32_bf16 v[112:115], v[140:143], v[188:191], v[112:115]
	v_mfma_f32_16x16x32_bf16 v[104:107], v[132:135], v[180:183], v[104:107]
	v_mfma_f32_16x16x32_bf16 v[96:99], v[140:143], v[180:183], v[96:99]
	v_mfma_f32_16x16x32_bf16 v[88:91], v[132:135], v[172:175], v[88:91]
	v_mfma_f32_16x16x32_bf16 v[80:83], v[140:143], v[172:175], v[80:83]
	v_mfma_f32_16x16x32_bf16 v[72:75], v[132:135], v[164:167], v[72:75]
	v_mfma_f32_16x16x32_bf16 v[64:67], v[140:143], v[164:167], v[64:67]
	s_barrier
	s_setprio 0
	s_add_u32 s98, s28, s14
	s_addc_u32 s99, s29, s15
	s_mov_b32 m0, s41
	s_add_u32 s36, s28, 0x80000
	ds_read_b128 v[184:187], v225 offset:16384
	ds_read_b128 v[188:191], v225 offset:17408
	ds_read_b128 v[176:179], v225 offset:18432
	ds_read_b128 v[180:183], v225 offset:19456
	ds_read_b128 v[168:171], v225 offset:20480
	ds_read_b128 v[172:175], v225 offset:21504
	ds_read_b128 v[160:163], v225 offset:22528
	ds_read_b128 v[164:167], v225 offset:23552
	global_load_lds_dwordx4 v196, s[28:29]
	s_mov_b32 m0, s42
	s_addc_u32 s37, s29, 0
	global_load_lds_dwordx4 v192, s[28:29]
	s_mov_b32 m0, s43
	s_nop 0
	global_load_lds_dwordx4 v196, s[36:37]
	s_mov_b32 m0, s44
	s_nop 0
	global_load_lds_dwordx4 v192, s[36:37]
	s_mov_b64 s[36:37], -1
	s_and_b64 vcc, exec, s[34:35]
	s_cbranch_vccz .LBB0_1362
	s_waitcnt vmcnt(6)
	s_mov_b64 s[36:37], 0

; #define PG8_STAGE(bufoff, gbase, voff) do { _Pragma("unroll") for (int _i = 0; _i < 2; ++_i) \
;         __builtin_amdgcn_global_load_lds((const unsigned*)((const char*)(gbase) + (voff)[_i]), (LAS unsigned*)(lds + (bufoff) + ldsw + _i * 8192), 16, 0, ((voff) == voffA ? AUXA : 0)); } while (0)
; #define PG8_LDA(dst, b, h) do { _Pragma("unroll") for (int m = 0; m < 4; ++m) _Pragma("unroll") for (int k = 0; k < 2; ++k) dst[m][k] = *(const LAS bf16x8*)(lds + PG8_SA(b, h) + aoff + m * 2048 + k * 1024); } while (0)
; #define PG8_LDB(dst, b, h) do { _Pragma("unroll") for (int n = 0; n < 2; ++n) _Pragma("unroll") for (int k = 0; k < 2; ++k) dst[n][k] = *(const LAS bf16x8*)(lds + PG8_SB(b, h) + boff + n * 2048 + k * 1024); } while (0)
; #define PG8_MMA(ai, bj, At, Bt) do { __builtin_amdgcn_s_setprio(1); _Pragma("unroll") for (int m = 0; m < 4; ++m) _Pragma("unroll") for (int n = 0; n < 2; ++n) _Pragma("unroll") for (int k = 0; k < 2; ++k) \
;         acc[ai][bj][m][n] = __builtin_amdgcn_mfma_f32_16x16x32_bf16(Bt[n][k], At[m][k], acc[ai][bj][m][n], 0, 0, 0); __builtin_amdgcn_s_setprio(0); } while (0)
; #define PG8_WAIT_V(n) asm volatile("s_waitcnt vmcnt(" #n ")" ::: "memory")
; #define PG8_WAIT_L(n) asm volatile("s_waitcnt lgkmcnt(" #n ")" ::: "memory")
; #define PG8_BAR __builtin_amdgcn_s_barrier()
; #define PG8_SCHED __builtin_amdgcn_sched_barrier(0)
;     ...
;             const bool last = (t == nt - 2);
;             const char* a1 = cA + (size_t)(t + 1) * kstep;
;             const char* a2 = last ? nA : cA + (size_t)(t + 2) * kstep; const char* b2 = last ? nB : cB + (size_t)(t + 2) * kstep;
;             const char* a3 = a2 + kstep; const char* b3 = b2 + kstep;
;             PG8_LDB(B0, 0, 0); PG8_LDB(B1, 0, 1); PG8_SCHED; PG8_LDA(At, 0, 0); PG8_STAGE(PG8_SA(1, 1), a1 + hsA, voffA);
;             if (Epi::NPRE != 0 && last) { E.pre(sv, cur, wr, fr); PG8_WAIT_V(16); } else { PG8_WAIT_V(8); }
;             PG8_WAIT_L(0); PG8_BAR; PG8_MMA(0, 0, At, B0); PG8_MMA(0, 1, At, B1); PG8_BAR; PG8_SCHED;
;             PG8_LDA(At, 0, 1); PG8_STAGE(PG8_SB(0, 0), b2, voffB); PG8_STAGE(PG8_SB(0, 1), b2 + hsB, voffB); PG8_STAGE(PG8_SA(0, 0), a2, voffA);
;             if (Epi::NPRE != 0 && last) { PG8_WAIT_V(16); } else { PG8_WAIT_V(8); }
;             PG8_WAIT_L(0); PG8_BAR; PG8_MMA(1, 0, At, B0); PG8_MMA(1, 1, At, B1); PG8_BAR; PG8_SCHED;
.LBB0_1440:
	s_add_u32 s98, s16, 0xffea0000
	s_mov_b32 m0, s34
	s_addc_u32 s99, s17, -1
	global_load_lds_dwordx4 v134, s[98:99]
	s_mov_b32 m0, s35
	s_nop 0
	global_load_lds_dwordx4 v130, s[98:99]
	ds_read_b128 v[144:147], v159
	ds_read_b128 v[148:151], v159 offset:1024
	ds_read_b128 v[152:155], v159 offset:2048
	ds_read_b128 v[162:165], v159 offset:3072
	ds_read_b128 v[166:169], v160
	ds_read_b128 v[170:173], v160 offset:1024
	ds_read_b128 v[174:177], v160 offset:2048
	ds_read_b128 v[178:181], v160 offset:3072
	s_add_i32 s46, s18, 2
	s_add_u32 s19, s16, 0xffea0080
	s_addc_u32 s20, s17, -1
	s_cmp_eq_u32 s36, s18
	s_cselect_b32 s18, s14, s44
	s_cselect_b32 s21, s5, s20
	s_cselect_b32 s20, s4, s19
	s_cselect_b32 s19, s15, s45
	s_add_i32 m0, s26, 0xc000
	ds_read_b128 v[182:185], v161
	ds_read_b128 v[186:189], v161 offset:1024
	ds_read_b128 v[190:193], v161 offset:2048
	ds_read_b128 v[194:197], v161 offset:3072
	ds_read_b128 v[198:201], v161 offset:4096
	ds_read_b128 v[202:205], v161 offset:5120
	ds_read_b128 v[206:209], v161 offset:6144
	ds_read_b128 v[210:213], v161 offset:7168
	global_load_lds_dwordx4 v136, s[16:17]
	s_add_i32 m0, s26, 0xe000
	s_nop 0
	global_load_lds_dwordx4 v138, s[16:17]
	s_waitcnt vmcnt(8)
	s_waitcnt lgkmcnt(0)
	s_setprio 1
	s_barrier
	v_mfma_f32_16x16x32_bf16 v[124:127], v[144:147], v[182:185], v[124:127]
	v_mfma_f32_16x16x32_bf16 v[120:123], v[152:155], v[182:185], v[120:123]
	v_mfma_f32_16x16x32_bf16 v[116:119], v[144:147], v[190:193], v[116:119]
	v_mfma_f32_16x16x32_bf16 v[112:115], v[152:155], v[190:193], v[112:115]
	v_mfma_f32_16x16x32_bf16 v[104:107], v[144:147], v[198:201], v[104:107]
	v_mfma_f32_16x16x32_bf16 v[96:99], v[152:155], v[198:201], v[96:99]
	v_mfma_f32_16x16x32_bf16 v[88:91], v[144:147], v[206:209], v[88:91]
	v_mfma_f32_16x16x32_bf16 v[80:83], v[152:155], v[206:209], v[80:83]
	v_mfma_f32_16x16x32_bf16 v[124:127], v[148:151], v[186:189], v[124:127]
	v_mfma_f32_16x16x32_bf16 v[120:123], v[162:165], v[186:189], v[120:123]
	v_mfma_f32_16x16x32_bf16 v[116:119], v[148:151], v[194:197], v[116:119]
	v_mfma_f32_16x16x32_bf16 v[112:115], v[162:165], v[194:197], v[112:115]
	v_mfma_f32_16x16x32_bf16 v[104:107], v[148:151], v[202:205], v[104:107]
	v_mfma_f32_16x16x32_bf16 v[96:99], v[162:165], v[202:205], v[96:99]
	v_mfma_f32_16x16x32_bf16 v[88:91], v[148:151], v[210:213], v[88:91]
	v_mfma_f32_16x16x32_bf16 v[80:83], v[162:165], v[210:213], v[80:83]
	v_mfma_f32_16x16x32_bf16 v[108:111], v[166:169], v[182:185], v[108:111]
	v_mfma_f32_16x16x32_bf16 v[100:103], v[174:177], v[182:185], v[100:103]
	v_mfma_f32_16x16x32_bf16 v[92:95], v[166:169], v[190:193], v[92:95]
	v_mfma_f32_16x16x32_bf16 v[84:87], v[174:177], v[190:193], v[84:87]
	v_mfma_f32_16x16x32_bf16 v[76:79], v[166:169], v[198:201], v[76:79]
	v_mfma_f32_16x16x32_bf16 v[72:75], v[174:177], v[198:201], v[72:75]
	v_mfma_f32_16x16x32_bf16 v[68:71], v[166:169], v[206:209], v[68:71]
	v_mfma_f32_16x16x32_bf16 v[64:67], v[174:177], v[206:209], v[64:67]
	v_mfma_f32_16x16x32_bf16 v[108:111], v[170:173], v[186:189], v[108:111]
	v_mfma_f32_16x16x32_bf16 v[100:103], v[178:181], v[186:189], v[100:103]
	v_mfma_f32_16x16x32_bf16 v[92:95], v[170:173], v[194:197], v[92:95]
	v_mfma_f32_16x16x32_bf16 v[84:87], v[178:181], v[194:197], v[84:87]
	v_mfma_f32_16x16x32_bf16 v[76:79], v[170:173], v[202:205], v[76:79]
	v_mfma_f32_16x16x32_bf16 v[72:75], v[178:181], v[202:205], v[72:75]
	v_mfma_f32_16x16x32_bf16 v[68:71], v[170:173], v[210:213], v[68:71]
	v_mfma_f32_16x16x32_bf16 v[64:67], v[178:181], v[210:213], v[64:67]
	s_barrier
	s_setprio 0
	s_add_u32 s98, s18, s8
	s_addc_u32 s99, s19, s9
	s_add_i32 s47, s38, s23
	s_mov_b32 m0, s47
	ds_read_b128 v[182:185], v161 offset:16384
	ds_read_b128 v[186:189], v161 offset:17408
	ds_read_b128 v[190:193], v161 offset:18432
	ds_read_b128 v[194:197], v161 offset:19456
	ds_read_b128 v[198:201], v161 offset:20480
	ds_read_b128 v[202:205], v161 offset:21504
	ds_read_b128 v[206:209], v161 offset:22528
	ds_read_b128 v[210:213], v161 offset:23552
	global_load_lds_dwordx4 v132, s[18:19]
	s_add_i32 m0, s47, 0x2000
	s_add_u32 s48, s18, 0x160000
	s_addc_u32 s49, s19, 0
	s_add_i32 s47, s39, s23
	global_load_lds_dwordx4 v128, s[18:19]
	s_mov_b32 m0, s47
	s_nop 0
	global_load_lds_dwordx4 v132, s[48:49]
	s_add_i32 m0, s47, 0x2000
	s_nop 0
	global_load_lds_dwordx4 v128, s[48:49]
	s_waitcnt vmcnt(6)
	s_waitcnt lgkmcnt(0)
	s_setprio 1
	s_barrier
	v_mfma_f32_16x16x32_bf16 v[60:63], v[144:147], v[182:185], v[60:63]
	v_mfma_f32_16x16x32_bf16 v[56:59], v[152:155], v[182:185], v[56:59]
	v_mfma_f32_16x16x32_bf16 v[52:55], v[144:147], v[190:193], v[52:55]
	v_mfma_f32_16x16x32_bf16 v[48:51], v[152:155], v[190:193], v[48:51]
	v_mfma_f32_16x16x32_bf16 v[40:43], v[144:147], v[198:201], v[40:43]
	v_mfma_f32_16x16x32_bf16 v[32:35], v[152:155], v[198:201], v[32:35]
	v_mfma_f32_16x16x32_bf16 v[24:27], v[144:147], v[206:209], v[24:27]
	v_mfma_f32_16x16x32_bf16 v[16:19], v[152:155], v[206:209], v[16:19]
	v_mfma_f32_16x16x32_bf16 v[60:63], v[148:151], v[186:189], v[60:63]
	v_mfma_f32_16x16x32_bf16 v[56:59], v[162:165], v[186:189], v[56:59]
	v_mfma_f32_16x16x32_bf16 v[52:55], v[148:151], v[194:197], v[52:55]
	v_mfma_f32_16x16x32_bf16 v[48:51], v[162:165], v[194:197], v[48:51]
	v_mfma_f32_16x16x32_bf16 v[40:43], v[148:151], v[202:205], v[40:43]
	v_mfma_f32_16x16x32_bf16 v[32:35], v[162:165], v[202:205], v[32:35]
	v_mfma_f32_16x16x32_bf16 v[24:27], v[148:151], v[210:213], v[24:27]
	v_mfma_f32_16x16x32_bf16 v[16:19], v[162:165], v[210:213], v[16:19]
	v_mfma_f32_16x16x32_bf16 v[44:47], v[166:169], v[182:185], v[44:47]
	v_mfma_f32_16x16x32_bf16 v[36:39], v[174:177], v[182:185], v[36:39]
	v_mfma_f32_16x16x32_bf16 v[28:31], v[166:169], v[190:193], v[28:31]
	v_mfma_f32_16x16x32_bf16 v[20:23], v[174:177], v[190:193], v[20:23]
	v_mfma_f32_16x16x32_bf16 v[12:15], v[166:169], v[198:201], v[12:15]
	v_mfma_f32_16x16x32_bf16 v[8:11], v[174:177], v[198:201], v[8:11]
	v_mfma_f32_16x16x32_bf16 v[4:7], v[166:169], v[206:209], v[4:7]
	v_mfma_f32_16x16x32_bf16 v[0:3], v[174:177], v[206:209], v[0:3]
	v_mfma_f32_16x16x32_bf16 v[44:47], v[170:173], v[186:189], v[44:47]
	v_mfma_f32_16x16x32_bf16 v[36:39], v[178:181], v[186:189], v[36:39]
	v_mfma_f32_16x16x32_bf16 v[28:31], v[170:173], v[194:197], v[28:31]
	v_mfma_f32_16x16x32_bf16 v[20:23], v[178:181], v[194:197], v[20:23]
	v_mfma_f32_16x16x32_bf16 v[12:15], v[170:173], v[202:205], v[12:15]
	v_mfma_f32_16x16x32_bf16 v[8:11], v[178:181], v[202:205], v[8:11]
	v_mfma_f32_16x16x32_bf16 v[4:7], v[170:173], v[210:213], v[4:7]
	v_mfma_f32_16x16x32_bf16 v[0:3], v[178:181], v[210:213], v[0:3]
	s_barrier
; #define PG8_STAGE(bufoff, gbase, voff) do { _Pragma("unroll") for (int _i = 0; _i < 2; ++_i) \
;         __builtin_amdgcn_global_load_lds((const unsigned*)((const char*)(gbase) + (voff)[_i]), (LAS unsigned*)(lds + (bufoff) + ldsw + _i * 8192), 16, 0, ((voff) == voffA ? AUXA : 0)); } while (0)
; #define PG8_LDA(dst, b, h) do { _Pragma("unroll") for (int m = 0; m < 4; ++m) _Pragma("unroll") for (int k = 0; k < 2; ++k) dst[m][k] = *(const LAS bf16x8*)(lds + PG8_SA(b, h) + aoff + m * 2048 + k * 1024); } while (0)
; #define PG8_LDB(dst, b, h) do { _Pragma("unroll") for (int n = 0; n < 2; ++n) _Pragma("unroll") for (int k = 0; k < 2; ++k) dst[n][k] = *(const LAS bf16x8*)(lds + PG8_SB(b, h) + boff + n * 2048 + k * 1024); } while (0)
; #define PG8_MMA(ai, bj, At, Bt) do { __builtin_amdgcn_s_setprio(1); _Pragma("unroll") for (int m = 0; m < 4; ++m) _Pragma("unroll") for (int n = 0; n < 2; ++n) _Pragma("unroll") for (int k = 0; k < 2; ++k) \
;         acc[ai][bj][m][n] = __builtin_amdgcn_mfma_f32_16x16x32_bf16(Bt[n][k], At[m][k], acc[ai][bj][m][n], 0, 0, 0); __builtin_amdgcn_s_setprio(0); } while (0)
; #define PG8_WAIT_V(n) asm volatile("s_waitcnt vmcnt(" #n ")" ::: "memory")
; #define PG8_WAIT_L(n) asm volatile("s_waitcnt lgkmcnt(" #n ")" ::: "memory")
; #define PG8_BAR __builtin_amdgcn_s_barrier()
; #define PG8_SCHED __builtin_amdgcn_sched_barrier(0)
;     ...
;             PG8_LDB(B0, 1, 0); PG8_LDB(B1, 1, 1); PG8_SCHED; PG8_LDA(At, 1, 0); PG8_STAGE(PG8_SA(0, 1), a2 + hsA, voffA);
;             PG8_WAIT_V(8); PG8_WAIT_L(0); PG8_BAR; PG8_MMA(0, 0, At, B0); PG8_MMA(0, 1, At, B1); PG8_BAR; PG8_SCHED;
;             PG8_LDA(At, 1, 1); PG8_STAGE(PG8_SB(1, 0), b3, voffB); PG8_STAGE(PG8_SB(1, 1), b3 + hsB, voffB); PG8_STAGE(PG8_SA(1, 0), a3, voffA);
	s_mov_b32 m0, s26
	s_nop 0
	global_load_lds_dwordx4 v134, s[20:21]
	s_mov_b32 m0, s27
	s_nop 0
	global_load_lds_dwordx4 v130, s[20:21]
	s_setprio 0
	s_add_i32 s47, 0, 0x18000
	s_add_i32 s48, 0, 0x1c000
	v_add_u32_e32 v162, s47, v157
	v_add_u32_e32 v178, s48, v157
	ds_read_b128 v[144:147], v162
	ds_read_b128 v[148:151], v162 offset:1024
	ds_read_b128 v[152:155], v162 offset:2048
	ds_read_b128 v[162:165], v162 offset:3072
	ds_read_b128 v[166:169], v178
	ds_read_b128 v[170:173], v178 offset:1024
	ds_read_b128 v[174:177], v178 offset:2048
	ds_read_b128 v[178:181], v178 offset:3072
	s_add_u32 s20, s20, 0x160000
	s_addc_u32 s21, s21, 0
	s_mov_b32 m0, s28
	ds_read_b128 v[182:185], v161 offset:32768
	ds_read_b128 v[186:189], v161 offset:33792
	ds_read_b128 v[190:193], v161 offset:34816
	ds_read_b128 v[194:197], v161 offset:35840
	ds_read_b128 v[198:201], v161 offset:36864
	ds_read_b128 v[202:205], v161 offset:37888
	ds_read_b128 v[206:209], v161 offset:38912
	ds_read_b128 v[210:213], v161 offset:39936
	global_load_lds_dwordx4 v134, s[20:21]
	s_mov_b32 m0, s29
	s_nop 0
	global_load_lds_dwordx4 v130, s[20:21]
	s_waitcnt vmcnt(8)
	s_waitcnt lgkmcnt(0)
	s_setprio 1
	s_barrier
	v_mfma_f32_16x16x32_bf16 v[124:127], v[144:147], v[182:185], v[124:127]
	v_mfma_f32_16x16x32_bf16 v[120:123], v[152:155], v[182:185], v[120:123]
	v_mfma_f32_16x16x32_bf16 v[116:119], v[144:147], v[190:193], v[116:119]
	v_mfma_f32_16x16x32_bf16 v[112:115], v[152:155], v[190:193], v[112:115]
	v_mfma_f32_16x16x32_bf16 v[104:107], v[144:147], v[198:201], v[104:107]
	v_mfma_f32_16x16x32_bf16 v[96:99], v[152:155], v[198:201], v[96:99]
	v_mfma_f32_16x16x32_bf16 v[88:91], v[144:147], v[206:209], v[88:91]
	v_mfma_f32_16x16x32_bf16 v[80:83], v[152:155], v[206:209], v[80:83]
	v_mfma_f32_16x16x32_bf16 v[124:127], v[148:151], v[186:189], v[124:127]
	v_mfma_f32_16x16x32_bf16 v[120:123], v[162:165], v[186:189], v[120:123]
	v_mfma_f32_16x16x32_bf16 v[116:119], v[148:151], v[194:197], v[116:119]
	v_mfma_f32_16x16x32_bf16 v[112:115], v[162:165], v[194:197], v[112:115]
	v_mfma_f32_16x16x32_bf16 v[104:107], v[148:151], v[202:205], v[104:107]
	v_mfma_f32_16x16x32_bf16 v[96:99], v[162:165], v[202:205], v[96:99]
	v_mfma_f32_16x16x32_bf16 v[88:91], v[148:151], v[210:213], v[88:91]
	v_mfma_f32_16x16x32_bf16 v[80:83], v[162:165], v[210:213], v[80:83]
	v_mfma_f32_16x16x32_bf16 v[108:111], v[166:169], v[182:185], v[108:111]
	v_mfma_f32_16x16x32_bf16 v[100:103], v[174:177], v[182:185], v[100:103]
	v_mfma_f32_16x16x32_bf16 v[92:95], v[166:169], v[190:193], v[92:95]
	v_mfma_f32_16x16x32_bf16 v[84:87], v[174:177], v[190:193], v[84:87]
	v_mfma_f32_16x16x32_bf16 v[76:79], v[166:169], v[198:201], v[76:79]
	v_mfma_f32_16x16x32_bf16 v[72:75], v[174:177], v[198:201], v[72:75]
	v_mfma_f32_16x16x32_bf16 v[68:71], v[166:169], v[206:209], v[68:71]
	v_mfma_f32_16x16x32_bf16 v[64:67], v[174:177], v[206:209], v[64:67]
	v_mfma_f32_16x16x32_bf16 v[108:111], v[170:173], v[186:189], v[108:111]
	v_mfma_f32_16x16x32_bf16 v[100:103], v[178:181], v[186:189], v[100:103]
	v_mfma_f32_16x16x32_bf16 v[92:95], v[170:173], v[194:197], v[92:95]
	v_mfma_f32_16x16x32_bf16 v[84:87], v[178:181], v[194:197], v[84:87]
	v_mfma_f32_16x16x32_bf16 v[76:79], v[170:173], v[202:205], v[76:79]
	v_mfma_f32_16x16x32_bf16 v[72:75], v[178:181], v[202:205], v[72:75]
	v_mfma_f32_16x16x32_bf16 v[68:71], v[170:173], v[210:213], v[68:71]
	v_mfma_f32_16x16x32_bf16 v[64:67], v[178:181], v[210:213], v[64:67]
	s_barrier
	s_setprio 0
	s_add_i32 s20, s47, s23
	s_mov_b32 m0, s20
	ds_read_b128 v[182:185], v161 offset:49152
	ds_read_b128 v[186:189], v161 offset:50176
	ds_read_b128 v[190:193], v161 offset:51200
	ds_read_b128 v[194:197], v161 offset:52224
	ds_read_b128 v[198:201], v161 offset:53248
	ds_read_b128 v[202:205], v161 offset:54272
	ds_read_b128 v[206:209], v161 offset:55296
	ds_read_b128 v[210:213], v161 offset:56320
	global_load_lds_dwordx4 v132, s[98:99]
	s_add_i32 m0, s20, 0x2000
	s_add_u32 s18, s18, 0x160080
	s_addc_u32 s19, s19, 0
	s_add_i32 s20, s48, s23
	global_load_lds_dwordx4 v128, s[98:99]
	s_mov_b32 m0, s20
	s_nop 0
	global_load_lds_dwordx4 v132, s[18:19]
	s_add_i32 m0, s20, 0x2000
	s_nop 0
	global_load_lds_dwordx4 v128, s[18:19]
	s_waitcnt vmcnt(6)
	s_waitcnt lgkmcnt(0)
	s_setprio 1
	s_barrier
; #define PG8_STAGE(bufoff, gbase, voff) do { _Pragma("unroll") for (int _i = 0; _i < 2; ++_i) \
;         __builtin_amdgcn_global_load_lds((const unsigned*)((const char*)(gbase) + (voff)[_i]), (LAS unsigned*)(lds + (bufoff) + ldsw + _i * 8192), 16, 0, ((voff) == voffA ? AUXA : 0)); } while (0)
; #define PG8_LDA(dst, b, h) do { _Pragma("unroll") for (int m = 0; m < 4; ++m) _Pragma("unroll") for (int k = 0; k < 2; ++k) dst[m][k] = *(const LAS bf16x8*)(lds + PG8_SA(b, h) + aoff + m * 2048 + k * 1024); } while (0)
; #define PG8_MMA(ai, bj, At, Bt) do { __builtin_amdgcn_s_setprio(1); _Pragma("unroll") for (int m = 0; m < 4; ++m) _Pragma("unroll") for (int n = 0; n < 2; ++n) _Pragma("unroll") for (int k = 0; k < 2; ++k) \
;         acc[ai][bj][m][n] = __builtin_amdgcn_mfma_f32_16x16x32_bf16(Bt[n][k], At[m][k], acc[ai][bj][m][n], 0, 0, 0); __builtin_amdgcn_s_setprio(0); } while (0)
; #define PG8_WAIT_V(n) asm volatile("s_waitcnt vmcnt(" #n ")" ::: "memory")
; #define PG8_WAIT_L(n) asm volatile("s_waitcnt lgkmcnt(" #n ")" ::: "memory")
; #define PG8_BAR __builtin_amdgcn_s_barrier()
; #define PG8_SCHED __builtin_amdgcn_sched_barrier(0)
;     ...
;             PG8_WAIT_V(8); PG8_WAIT_L(0); PG8_BAR; PG8_MMA(0, 0, At, B0); PG8_MMA(0, 1, At, B1); PG8_BAR; PG8_SCHED;
;             PG8_LDA(At, 1, 1); PG8_STAGE(PG8_SB(1, 0), b3, voffB); PG8_STAGE(PG8_SB(1, 1), b3 + hsB, voffB); PG8_STAGE(PG8_SA(1, 0), a3, voffA);
;             PG8_WAIT_V(8); PG8_WAIT_L(0); PG8_BAR; PG8_MMA(1, 0, At, B0); PG8_MMA(1, 1, At, B1); PG8_BAR; PG8_SCHED;
;         }
;     __device__ __forceinline__ void operator()(const Acc& acc, const Unit& u, int wr, int wc, int fr, int fq, const float (&sv8)[8]) const {
;     ...
;                     const f32x4 y0 = xr[m][bj][0] + acc[ai][bj][m][0] * scale, y1 = xr[m][bj][1] + acc[ai][bj][m][1] * scale;
	v_mfma_f32_16x16x32_bf16 v[60:63], v[144:147], v[182:185], v[60:63]
	v_mfma_f32_16x16x32_bf16 v[56:59], v[152:155], v[182:185], v[56:59]
	v_mfma_f32_16x16x32_bf16 v[52:55], v[144:147], v[190:193], v[52:55]
	v_mfma_f32_16x16x32_bf16 v[48:51], v[152:155], v[190:193], v[48:51]
	v_mfma_f32_16x16x32_bf16 v[40:43], v[144:147], v[198:201], v[40:43]
	v_mfma_f32_16x16x32_bf16 v[32:35], v[152:155], v[198:201], v[32:35]
	v_mfma_f32_16x16x32_bf16 v[24:27], v[144:147], v[206:209], v[24:27]
	v_mfma_f32_16x16x32_bf16 v[16:19], v[152:155], v[206:209], v[16:19]
	v_mfma_f32_16x16x32_bf16 v[60:63], v[148:151], v[186:189], v[60:63]
	v_mfma_f32_16x16x32_bf16 v[56:59], v[162:165], v[186:189], v[56:59]
	v_mfma_f32_16x16x32_bf16 v[52:55], v[148:151], v[194:197], v[52:55]
	v_mfma_f32_16x16x32_bf16 v[48:51], v[162:165], v[194:197], v[48:51]
	v_mfma_f32_16x16x32_bf16 v[40:43], v[148:151], v[202:205], v[40:43]
	v_mfma_f32_16x16x32_bf16 v[32:35], v[162:165], v[202:205], v[32:35]
	v_mfma_f32_16x16x32_bf16 v[24:27], v[148:151], v[210:213], v[24:27]
	v_mfma_f32_16x16x32_bf16 v[16:19], v[162:165], v[210:213], v[16:19]
	v_mfma_f32_16x16x32_bf16 v[44:47], v[166:169], v[182:185], v[44:47]
	v_mfma_f32_16x16x32_bf16 v[36:39], v[174:177], v[182:185], v[36:39]
	v_mfma_f32_16x16x32_bf16 v[28:31], v[166:169], v[190:193], v[28:31]
	v_mfma_f32_16x16x32_bf16 v[20:23], v[174:177], v[190:193], v[20:23]
	v_mfma_f32_16x16x32_bf16 v[12:15], v[166:169], v[198:201], v[12:15]
	v_mfma_f32_16x16x32_bf16 v[8:11], v[174:177], v[198:201], v[8:11]
	v_mfma_f32_16x16x32_bf16 v[4:7], v[166:169], v[206:209], v[4:7]
	v_mfma_f32_16x16x32_bf16 v[0:3], v[174:177], v[206:209], v[0:3]
	v_mfma_f32_16x16x32_bf16 v[44:47], v[170:173], v[186:189], v[44:47]
	v_mfma_f32_16x16x32_bf16 v[36:39], v[178:181], v[186:189], v[36:39]
	v_mfma_f32_16x16x32_bf16 v[28:31], v[170:173], v[194:197], v[28:31]
	v_mfma_f32_16x16x32_bf16 v[20:23], v[178:181], v[194:197], v[20:23]
	v_mfma_f32_16x16x32_bf16 v[12:15], v[170:173], v[202:205], v[12:15]
	v_mfma_f32_16x16x32_bf16 v[8:11], v[178:181], v[202:205], v[8:11]
	v_mfma_f32_16x16x32_bf16 v[4:7], v[170:173], v[210:213], v[4:7]
	v_mfma_f32_16x16x32_bf16 v[0:3], v[178:181], v[210:213], v[0:3]
	s_barrier
	s_setprio 0
	s_add_u32 s16, s16, 0x100
	s_addc_u32 s17, s17, 0
	s_add_u32 s44, s44, 0x100
	s_addc_u32 s45, s45, 0
	s_cmp_ge_i32 s46, s31
	s_mov_b32 s18, s46
	s_cbranch_scc0 .LBB0_1440
	v_pk_mul_f32 v[126:127], v[126:127], 0.5 op_sel_hi:[1,0]
	v_pk_mul_f32 v[146:147], v[124:125], 0.5 op_sel_hi:[1,0]
	v_pk_mul_f32 v[144:145], v[122:123], 0.5 op_sel_hi:[1,0]
	v_pk_mul_f32 v[124:125], v[120:121], 0.5 op_sel_hi:[1,0]
	v_pk_mul_f32 v[154:155], v[110:111], 0.5 op_sel_hi:[1,0]
	v_pk_mul_f32 v[152:153], v[108:109], 0.5 op_sel_hi:[1,0]
	v_pk_mul_f32 v[150:151], v[102:103], 0.5 op_sel_hi:[1,0]
	v_pk_mul_f32 v[148:149], v[100:101], 0.5 op_sel_hi:[1,0]
	v_pk_mul_f32 v[118:119], v[118:119], 0.5 op_sel_hi:[1,0]
	v_pk_mul_f32 v[116:117], v[116:117], 0.5 op_sel_hi:[1,0]
	v_pk_mul_f32 v[110:111], v[114:115], 0.5 op_sel_hi:[1,0]
	v_pk_mul_f32 v[108:109], v[112:113], 0.5 op_sel_hi:[1,0]
	v_pk_mul_f32 v[122:123], v[94:95], 0.5 op_sel_hi:[1,0]
	v_pk_mul_f32 v[120:121], v[92:93], 0.5 op_sel_hi:[1,0]
	v_pk_mul_f32 v[114:115], v[86:87], 0.5 op_sel_hi:[1,0]
	v_pk_mul_f32 v[112:113], v[84:85], 0.5 op_sel_hi:[1,0]
	v_pk_mul_f32 v[102:103], v[106:107], 0.5 op_sel_hi:[1,0]
	v_pk_mul_f32 v[100:101], v[104:105], 0.5 op_sel_hi:[1,0]
	v_pk_mul_f32 v[94:95], v[98:99], 0.5 op_sel_hi:[1,0]
	v_pk_mul_f32 v[92:93], v[96:97], 0.5 op_sel_hi:[1,0]
	v_pk_mul_f32 v[106:107], v[78:79], 0.5 op_sel_hi:[1,0]
	v_pk_mul_f32 v[104:105], v[76:77], 0.5 op_sel_hi:[1,0]
	v_pk_mul_f32 v[98:99], v[74:75], 0.5 op_sel_hi:[1,0]
	v_pk_mul_f32 v[96:97], v[72:73], 0.5 op_sel_hi:[1,0]
	v_pk_mul_f32 v[86:87], v[90:91], 0.5 op_sel_hi:[1,0]
	v_pk_mul_f32 v[84:85], v[88:89], 0.5 op_sel_hi:[1,0]
	v_pk_mul_f32 v[78:79], v[82:83], 0.5 op_sel_hi:[1,0]
	v_pk_mul_f32 v[76:77], v[80:81], 0.5 op_sel_hi:[1,0]
	v_pk_mul_f32 v[90:91], v[70:71], 0.5 op_sel_hi:[1,0]
	v_pk_mul_f32 v[88:89], v[68:69], 0.5 op_sel_hi:[1,0]
	v_pk_mul_f32 v[82:83], v[66:67], 0.5 op_sel_hi:[1,0]
	v_pk_mul_f32 v[80:81], v[64:65], 0.5 op_sel_hi:[1,0]
	v_pk_mul_f32 v[66:67], v[62:63], 0.5 op_sel_hi:[1,0]
	v_pk_mul_f32 v[64:65], v[60:61], 0.5 op_sel_hi:[1,0]
	v_pk_mul_f32 v[62:63], v[58:59], 0.5 op_sel_hi:[1,0]
	v_pk_mul_f32 v[60:61], v[56:57], 0.5 op_sel_hi:[1,0]
	v_pk_mul_f32 v[74:75], v[46:47], 0.5 op_sel_hi:[1,0]
	v_pk_mul_f32 v[72:73], v[44:45], 0.5 op_sel_hi:[1,0]
	v_pk_mul_f32 v[70:71], v[38:39], 0.5 op_sel_hi:[1,0]
	v_pk_mul_f32 v[68:69], v[36:37], 0.5 op_sel_hi:[1,0]
	v_pk_mul_f32 v[54:55], v[54:55], 0.5 op_sel_hi:[1,0]
	v_pk_mul_f32 v[52:53], v[52:53], 0.5 op_sel_hi:[1,0]
	v_pk_mul_f32 v[46:47], v[50:51], 0.5 op_sel_hi:[1,0]
	v_pk_mul_f32 v[44:45], v[48:49], 0.5 op_sel_hi:[1,0]
	v_pk_mul_f32 v[58:59], v[30:31], 0.5 op_sel_hi:[1,0]
	v_pk_mul_f32 v[56:57], v[28:29], 0.5 op_sel_hi:[1,0]
	v_pk_mul_f32 v[50:51], v[22:23], 0.5 op_sel_hi:[1,0]
	v_pk_mul_f32 v[48:49], v[20:21], 0.5 op_sel_hi:[1,0]
	v_pk_mul_f32 v[30:31], v[42:43], 0.5 op_sel_hi:[1,0]
	v_pk_mul_f32 v[28:29], v[40:41], 0.5 op_sel_hi:[1,0]
	v_pk_mul_f32 v[22:23], v[34:35], 0.5 op_sel_hi:[1,0]
	v_pk_mul_f32 v[20:21], v[32:33], 0.5 op_sel_hi:[1,0]
	v_pk_mul_f32 v[38:39], v[14:15], 0.5 op_sel_hi:[1,0]
	v_pk_mul_f32 v[36:37], v[12:13], 0.5 op_sel_hi:[1,0]
	v_pk_mul_f32 v[34:35], v[10:11], 0.5 op_sel_hi:[1,0]
	v_pk_mul_f32 v[32:33], v[8:9], 0.5 op_sel_hi:[1,0]
	v_pk_mul_f32 v[14:15], v[26:27], 0.5 op_sel_hi:[1,0]
	v_pk_mul_f32 v[12:13], v[24:25], 0.5 op_sel_hi:[1,0]
	v_pk_mul_f32 v[10:11], v[18:19], 0.5 op_sel_hi:[1,0]
	v_pk_mul_f32 v[8:9], v[16:17], 0.5 op_sel_hi:[1,0]
	v_pk_mul_f32 v[6:7], v[6:7], 0.5 op_sel_hi:[1,0]
	v_pk_mul_f32 v[4:5], v[4:5], 0.5 op_sel_hi:[1,0]
	v_pk_mul_f32 v[2:3], v[2:3], 0.5 op_sel_hi:[1,0]
	v_pk_mul_f32 v[0:1], v[0:1], 0.5 op_sel_hi:[1,0]
